# GEMM MFMA segments: per-cluster s_setprio flips and the duplicate lgkmcnt(0) ahead of each 16-MFMA cluster removed (idle-probe showed the MFMA segment is the pole)
# speedup vs baseline: 1.0094x; 1.0057x over previous
;     __device__ __forceinline__ unsigned* BAR() const { return (unsigned*)(ws + OFF_BAR); }
; #define STAGE(bufoff, gbase, voff) do { _Pragma("unroll") for (int _i = 0; _i < 2; ++_i) \
;         __builtin_amdgcn_global_load_lds((const unsigned*)((const char*)(gbase) + voff[_i]), (LAS unsigned*)(lds + (bufoff) + ldsw + _i * 8192), 16, 0, 0); } while (0)
; #define LDA(dst, b, h) do { _Pragma("unroll") for (int m = 0; m < 4; ++m) _Pragma("unroll") for (int k = 0; k < 2; ++k) dst[m][k] = *(const LAS bf16x8*)(lds + SA(b, h) + aoff + m * 2048 + k * 1024); } while (0)
; #define LDB(dst, b, h) do { _Pragma("unroll") for (int n = 0; n < 2; ++n) _Pragma("unroll") for (int k = 0; k < 2; ++k) dst[n][k] = *(const LAS bf16x8*)(lds + SB(b, h) + boff + n * 2048 + k * 1024); } while (0)
; #define MMA(ai, bj, At, Bx) do { __builtin_amdgcn_s_setprio(1); _Pragma("unroll") for (int m = 0; m < 4; ++m) _Pragma("unroll") for (int n = 0; n < 2; ++n) _Pragma("unroll") for (int k = 0; k < 2; ++k) \
;       acc[ai][bj][m][n] = __builtin_amdgcn_mfma_f32_16x16x32_bf16(At[m][k], Bx[n][k], acc[ai][bj][m][n], 0, 0, 0); \
;     __builtin_amdgcn_s_setprio(0); } while (0)
; #define WAIT_L(n) asm volatile("s_waitcnt lgkmcnt(" #n ")" ::: "memory")
; #define BAR __builtin_amdgcn_s_barrier()
; #define SCHED __builtin_amdgcn_sched_barrier(0)
;     ...
;     for (int t = 0; t < nt - 2; t += 2) {
;         if (KSEG && t > 0 && (t % (KSEG ? KSEG : 1)) == 0) hook(t / (KSEG ? KSEG : 1), acc);
;         const char* a1 = pA(t + 1); const char* a2 = pA(t + 2); const char* a3 = pA(t + 3);
;         const char* b2 = pB(t + 2); const char* b3 = pB(t + 3);
;         LDB(B0, 0, 0); SCHED; LDA(At, 0, 0); STAGE(SA(1, 1), a1 + hstepA, voffA);
;         WAIT_L(8); BAR; WAIT_L(0); MMA(0, 0, At, B0); BAR; SCHED;
;         LDB(B1, 0, 1); STAGE(SB(0, 0), b2, voffB);
;         BAR; WAIT_L(0); MMA(0, 1, At, B1); BAR;
;         LDA(At, 0, 1); STAGE(SA(0, 0), a2, voffA);
.LBB0_227:
	s_add_i32 s9, 0, 0x10000
	v_add_u32_e32 v138, s9, v143
	ds_read_b128 v[144:147], v138
	ds_read_b128 v[148:151], v138 offset:1024
	ds_read_b128 v[152:155], v138 offset:2048
	ds_read_b128 v[156:159], v138 offset:3072
	v_lshl_add_u64 v[138:139], s[4:5], 0, v[136:137]
	s_add_i32 s8, s12, 0xc000
	v_lshl_add_u64 v[214:215], v[138:139], 0, s[36:37]
	s_mov_b32 m0, s8
	v_lshl_add_u64 v[230:231], s[4:5], 0, v[140:141]
	s_add_i32 s7, s12, 0xe000
	ds_read_b128 v[160:163], v142
	ds_read_b128 v[164:167], v142 offset:1024
	ds_read_b128 v[190:193], v142 offset:2048
	ds_read_b128 v[194:197], v142 offset:3072
	ds_read_b128 v[198:201], v142 offset:4096
	ds_read_b128 v[202:205], v142 offset:5120
	ds_read_b128 v[206:209], v142 offset:6144
	ds_read_b128 v[210:213], v142 offset:7168
	global_load_lds_dwordx4 v[214:215], off
	v_lshl_add_u64 v[214:215], v[230:231], 0, s[36:37]
	s_mov_b32 m0, s7
	s_nop 0
	global_load_lds_dwordx4 v[214:215], off
	s_waitcnt lgkmcnt(8)
	s_barrier
	s_waitcnt lgkmcnt(0)
	v_mfma_f32_16x16x32_bf16 v[126:129], v[160:163], v[144:147], v[126:129]
	v_mfma_f32_16x16x32_bf16 v[122:125], v[160:163], v[152:155], v[122:125]
	v_mfma_f32_16x16x32_bf16 v[118:121], v[190:193], v[144:147], v[118:121]
	v_mfma_f32_16x16x32_bf16 v[114:117], v[190:193], v[152:155], v[114:117]
	v_mfma_f32_16x16x32_bf16 v[110:113], v[198:201], v[144:147], v[110:113]
	v_mfma_f32_16x16x32_bf16 v[106:109], v[198:201], v[152:155], v[106:109]
	v_mfma_f32_16x16x32_bf16 v[102:105], v[206:209], v[144:147], v[102:105]
	v_mfma_f32_16x16x32_bf16 v[98:101], v[206:209], v[152:155], v[98:101]
	v_mfma_f32_16x16x32_bf16 v[126:129], v[164:167], v[148:151], v[126:129]
	v_mfma_f32_16x16x32_bf16 v[122:125], v[164:167], v[156:159], v[122:125]
	v_mfma_f32_16x16x32_bf16 v[118:121], v[194:197], v[148:151], v[118:121]
	v_mfma_f32_16x16x32_bf16 v[114:117], v[194:197], v[156:159], v[114:117]
	v_mfma_f32_16x16x32_bf16 v[110:113], v[202:205], v[148:151], v[110:113]
	v_mfma_f32_16x16x32_bf16 v[106:109], v[202:205], v[156:159], v[106:109]
	v_mfma_f32_16x16x32_bf16 v[102:105], v[210:213], v[148:151], v[102:105]
	v_mfma_f32_16x16x32_bf16 v[98:101], v[210:213], v[156:159], v[98:101]
	s_barrier
	s_add_i32 s16, 0, 0x14000
	v_lshl_add_u64 v[232:233], s[4:5], 0, v[132:133]
	s_add_i32 s9, s9, s11
	v_add_u32_e32 v226, s16, v143
	v_lshl_add_u64 v[234:235], v[232:233], 0, s[38:39]
	s_mov_b32 m0, s9
	ds_read_b128 v[214:217], v226
	ds_read_b128 v[218:221], v226 offset:1024
	ds_read_b128 v[222:225], v226 offset:2048
	ds_read_b128 v[226:229], v226 offset:3072
	global_load_lds_dwordx4 v[234:235], off
	v_lshl_add_u64 v[234:235], s[4:5], 0, v[134:135]
	v_lshl_add_u64 v[236:237], v[234:235], 0, s[38:39]
	s_add_i32 m0, s9, 0x2000
	s_nop 0
	global_load_lds_dwordx4 v[236:237], off
	s_barrier
	s_waitcnt lgkmcnt(0)
	v_mfma_f32_16x16x32_bf16 v[94:97], v[160:163], v[214:217], v[94:97]
	v_mfma_f32_16x16x32_bf16 v[90:93], v[160:163], v[222:225], v[90:93]
	v_mfma_f32_16x16x32_bf16 v[86:89], v[190:193], v[214:217], v[86:89]
	v_mfma_f32_16x16x32_bf16 v[82:85], v[190:193], v[222:225], v[82:85]
	v_mfma_f32_16x16x32_bf16 v[78:81], v[198:201], v[214:217], v[78:81]
	v_mfma_f32_16x16x32_bf16 v[74:77], v[198:201], v[222:225], v[74:77]
	v_mfma_f32_16x16x32_bf16 v[70:73], v[206:209], v[214:217], v[70:73]
	v_mfma_f32_16x16x32_bf16 v[66:69], v[206:209], v[222:225], v[66:69]
	v_mfma_f32_16x16x32_bf16 v[94:97], v[164:167], v[218:221], v[94:97]
	v_mfma_f32_16x16x32_bf16 v[90:93], v[164:167], v[226:229], v[90:93]
	v_mfma_f32_16x16x32_bf16 v[86:89], v[194:197], v[218:221], v[86:89]
	v_mfma_f32_16x16x32_bf16 v[82:85], v[194:197], v[226:229], v[82:85]
	v_mfma_f32_16x16x32_bf16 v[78:81], v[202:205], v[218:221], v[78:81]
	v_mfma_f32_16x16x32_bf16 v[74:77], v[202:205], v[226:229], v[74:77]
	v_mfma_f32_16x16x32_bf16 v[70:73], v[210:213], v[218:221], v[70:73]
	v_mfma_f32_16x16x32_bf16 v[66:69], v[210:213], v[226:229], v[66:69]
	s_mov_b32 m0, s12
	v_lshl_add_u64 v[236:237], v[138:139], 0, s[40:41]
	s_barrier
	ds_read_b128 v[160:163], v142 offset:16384
	ds_read_b128 v[164:167], v142 offset:17408
	ds_read_b128 v[190:193], v142 offset:18432
	ds_read_b128 v[194:197], v142 offset:19456
	ds_read_b128 v[198:201], v142 offset:20480
	ds_read_b128 v[202:205], v142 offset:21504
	ds_read_b128 v[206:209], v142 offset:22528
	ds_read_b128 v[210:213], v142 offset:23552
	global_load_lds_dwordx4 v[236:237], off
	v_lshl_add_u64 v[236:237], v[230:231], 0, s[40:41]
	s_mov_b32 m0, s13
	s_nop 0
	global_load_lds_dwordx4 v[236:237], off
	s_barrier
	s_waitcnt lgkmcnt(0)
	v_mfma_f32_16x16x32_bf16 v[62:65], v[160:163], v[144:147], v[62:65]
	v_mfma_f32_16x16x32_bf16 v[58:61], v[160:163], v[152:155], v[58:61]
	v_mfma_f32_16x16x32_bf16 v[54:57], v[190:193], v[144:147], v[54:57]
	v_mfma_f32_16x16x32_bf16 v[50:53], v[190:193], v[152:155], v[50:53]
	v_mfma_f32_16x16x32_bf16 v[46:49], v[198:201], v[144:147], v[46:49]
	v_mfma_f32_16x16x32_bf16 v[42:45], v[198:201], v[152:155], v[42:45]
	v_mfma_f32_16x16x32_bf16 v[38:41], v[206:209], v[144:147], v[38:41]
	v_mfma_f32_16x16x32_bf16 v[34:37], v[206:209], v[152:155], v[34:37]
	v_mfma_f32_16x16x32_bf16 v[62:65], v[164:167], v[148:151], v[62:65]
	v_mfma_f32_16x16x32_bf16 v[58:61], v[164:167], v[156:159], v[58:61]
	v_mfma_f32_16x16x32_bf16 v[54:57], v[194:197], v[148:151], v[54:57]
	v_mfma_f32_16x16x32_bf16 v[50:53], v[194:197], v[156:159], v[50:53]
	v_mfma_f32_16x16x32_bf16 v[46:49], v[202:205], v[148:151], v[46:49]
	v_mfma_f32_16x16x32_bf16 v[42:45], v[202:205], v[156:159], v[42:45]
	v_mfma_f32_16x16x32_bf16 v[38:41], v[210:213], v[148:151], v[38:41]
	v_mfma_f32_16x16x32_bf16 v[34:37], v[210:213], v[156:159], v[34:37]
	s_barrier
;     __device__ __forceinline__ unsigned* BAR() const { return (unsigned*)(ws + OFF_BAR); }
; #define STAGE(bufoff, gbase, voff) do { _Pragma("unroll") for (int _i = 0; _i < 2; ++_i) \
;         __builtin_amdgcn_global_load_lds((const unsigned*)((const char*)(gbase) + voff[_i]), (LAS unsigned*)(lds + (bufoff) + ldsw + _i * 8192), 16, 0, 0); } while (0)
; #define LDA(dst, b, h) do { _Pragma("unroll") for (int m = 0; m < 4; ++m) _Pragma("unroll") for (int k = 0; k < 2; ++k) dst[m][k] = *(const LAS bf16x8*)(lds + SA(b, h) + aoff + m * 2048 + k * 1024); } while (0)
; #define LDB(dst, b, h) do { _Pragma("unroll") for (int n = 0; n < 2; ++n) _Pragma("unroll") for (int k = 0; k < 2; ++k) dst[n][k] = *(const LAS bf16x8*)(lds + SB(b, h) + boff + n * 2048 + k * 1024); } while (0)
; #define MMA(ai, bj, At, Bx) do { __builtin_amdgcn_s_setprio(1); _Pragma("unroll") for (int m = 0; m < 4; ++m) _Pragma("unroll") for (int n = 0; n < 2; ++n) _Pragma("unroll") for (int k = 0; k < 2; ++k) \
;       acc[ai][bj][m][n] = __builtin_amdgcn_mfma_f32_16x16x32_bf16(At[m][k], Bx[n][k], acc[ai][bj][m][n], 0, 0, 0); \
;     __builtin_amdgcn_s_setprio(0); } while (0)
; #define WAIT_V(n) asm volatile("s_waitcnt vmcnt(" #n ")" ::: "memory")
; #define WAIT_L(n) asm volatile("s_waitcnt lgkmcnt(" #n ")" ::: "memory")
; #define BAR __builtin_amdgcn_s_barrier()
; #define SCHED __builtin_amdgcn_sched_barrier(0)
;     ...
;         LDA(At, 0, 1); STAGE(SA(0, 0), a2, voffA);
;         BAR; WAIT_L(0); MMA(1, 0, At, B0); BAR; SCHED;
;         STAGE(SB(0, 1), b2 + hstepB, voffB);
;         WAIT_V(6); BAR; MMA(1, 1, At, B1); BAR;
;         LDB(B0, 1, 0); SCHED; LDA(At, 1, 0); STAGE(SA(0, 1), a2 + hstepA, voffA);
;         WAIT_L(8); BAR; WAIT_L(0); MMA(0, 0, At, B0); BAR; SCHED;
;         LDB(B1, 1, 1); STAGE(SB(1, 0), b3, voffB);
;         BAR; WAIT_L(0); MMA(0, 1, At, B1); BAR;
;         LDA(At, 1, 1); STAGE(SA(1, 0), a3, voffA);
	s_add_i32 s9, s16, s11
	v_lshl_add_u64 v[144:145], v[232:233], 0, s[44:45]
	s_mov_b32 m0, s9
	s_nop 0
	global_load_lds_dwordx4 v[144:145], off
	v_lshl_add_u64 v[144:145], v[234:235], 0, s[44:45]
	s_add_i32 m0, s9, 0x2000
	s_nop 0
	global_load_lds_dwordx4 v[144:145], off
	s_waitcnt vmcnt(6)
	s_barrier
	v_mfma_f32_16x16x32_bf16 v[30:33], v[160:163], v[214:217], v[30:33]
	v_mfma_f32_16x16x32_bf16 v[26:29], v[160:163], v[222:225], v[26:29]
	v_mfma_f32_16x16x32_bf16 v[22:25], v[190:193], v[214:217], v[22:25]
	v_mfma_f32_16x16x32_bf16 v[18:21], v[190:193], v[222:225], v[18:21]
	v_mfma_f32_16x16x32_bf16 v[14:17], v[198:201], v[214:217], v[14:17]
	v_mfma_f32_16x16x32_bf16 v[10:13], v[198:201], v[222:225], v[10:13]
	v_mfma_f32_16x16x32_bf16 v[6:9], v[206:209], v[214:217], v[6:9]
	v_mfma_f32_16x16x32_bf16 v[2:5], v[206:209], v[222:225], v[2:5]
	v_mfma_f32_16x16x32_bf16 v[30:33], v[164:167], v[218:221], v[30:33]
	v_mfma_f32_16x16x32_bf16 v[26:29], v[164:167], v[226:229], v[26:29]
	v_mfma_f32_16x16x32_bf16 v[22:25], v[194:197], v[218:221], v[22:25]
	v_mfma_f32_16x16x32_bf16 v[18:21], v[194:197], v[226:229], v[18:21]
	v_mfma_f32_16x16x32_bf16 v[14:17], v[202:205], v[218:221], v[14:17]
	v_mfma_f32_16x16x32_bf16 v[10:13], v[202:205], v[226:229], v[10:13]
	v_mfma_f32_16x16x32_bf16 v[6:9], v[210:213], v[218:221], v[6:9]
	v_mfma_f32_16x16x32_bf16 v[2:5], v[210:213], v[226:229], v[2:5]
	s_add_i32 s9, 0, 0x18000
	v_add_u32_e32 v156, s9, v143
	s_barrier
	ds_read_b128 v[144:147], v156
	ds_read_b128 v[148:151], v156 offset:1024
	ds_read_b128 v[152:155], v156 offset:2048
	ds_read_b128 v[156:159], v156 offset:3072
	s_mov_b32 m0, s14
	v_lshl_add_u64 v[214:215], v[138:139], 0, s[46:47]
	ds_read_b128 v[160:163], v142 offset:32768
	ds_read_b128 v[164:167], v142 offset:33792
	ds_read_b128 v[190:193], v142 offset:34816
	ds_read_b128 v[194:197], v142 offset:35840
	ds_read_b128 v[198:201], v142 offset:36864
	ds_read_b128 v[202:205], v142 offset:37888
	ds_read_b128 v[206:209], v142 offset:38912
	ds_read_b128 v[210:213], v142 offset:39936
	global_load_lds_dwordx4 v[214:215], off
	v_lshl_add_u64 v[214:215], v[230:231], 0, s[46:47]
	s_mov_b32 m0, s15
	s_nop 0
	global_load_lds_dwordx4 v[214:215], off
	s_waitcnt lgkmcnt(8)
	s_barrier
	s_waitcnt lgkmcnt(0)
	v_mfma_f32_16x16x32_bf16 v[126:129], v[160:163], v[144:147], v[126:129]
	v_mfma_f32_16x16x32_bf16 v[122:125], v[160:163], v[152:155], v[122:125]
	v_mfma_f32_16x16x32_bf16 v[118:121], v[190:193], v[144:147], v[118:121]
	v_mfma_f32_16x16x32_bf16 v[114:117], v[190:193], v[152:155], v[114:117]
	v_mfma_f32_16x16x32_bf16 v[110:113], v[198:201], v[144:147], v[110:113]
	v_mfma_f32_16x16x32_bf16 v[106:109], v[198:201], v[152:155], v[106:109]
	v_mfma_f32_16x16x32_bf16 v[102:105], v[206:209], v[144:147], v[102:105]
	v_mfma_f32_16x16x32_bf16 v[98:101], v[206:209], v[152:155], v[98:101]
	v_mfma_f32_16x16x32_bf16 v[126:129], v[164:167], v[148:151], v[126:129]
	v_mfma_f32_16x16x32_bf16 v[122:125], v[164:167], v[156:159], v[122:125]
	v_mfma_f32_16x16x32_bf16 v[118:121], v[194:197], v[148:151], v[118:121]
	v_mfma_f32_16x16x32_bf16 v[114:117], v[194:197], v[156:159], v[114:117]
	v_mfma_f32_16x16x32_bf16 v[110:113], v[202:205], v[148:151], v[110:113]
	v_mfma_f32_16x16x32_bf16 v[106:109], v[202:205], v[156:159], v[106:109]
	v_mfma_f32_16x16x32_bf16 v[102:105], v[210:213], v[148:151], v[102:105]
	v_mfma_f32_16x16x32_bf16 v[98:101], v[210:213], v[156:159], v[98:101]
	s_barrier
	s_add_i32 s16, 0, 0x1c000
	s_add_i32 s9, s9, s11
	v_add_u32_e32 v226, s16, v143
	v_lshl_add_u64 v[236:237], v[232:233], 0, s[48:49]
	s_mov_b32 m0, s9
	ds_read_b128 v[214:217], v226
	ds_read_b128 v[218:221], v226 offset:1024
	ds_read_b128 v[222:225], v226 offset:2048
	ds_read_b128 v[226:229], v226 offset:3072
	global_load_lds_dwordx4 v[236:237], off
	v_lshl_add_u64 v[236:237], v[234:235], 0, s[48:49]
	s_add_i32 m0, s9, 0x2000
	s_nop 0
	global_load_lds_dwordx4 v[236:237], off
	s_barrier
	s_waitcnt lgkmcnt(0)
	v_mfma_f32_16x16x32_bf16 v[94:97], v[160:163], v[214:217], v[94:97]
	v_mfma_f32_16x16x32_bf16 v[90:93], v[160:163], v[222:225], v[90:93]
	v_mfma_f32_16x16x32_bf16 v[86:89], v[190:193], v[214:217], v[86:89]
	v_mfma_f32_16x16x32_bf16 v[82:85], v[190:193], v[222:225], v[82:85]
	v_mfma_f32_16x16x32_bf16 v[78:81], v[198:201], v[214:217], v[78:81]
	v_mfma_f32_16x16x32_bf16 v[74:77], v[198:201], v[222:225], v[74:77]
	v_mfma_f32_16x16x32_bf16 v[70:73], v[206:209], v[214:217], v[70:73]
	v_mfma_f32_16x16x32_bf16 v[66:69], v[206:209], v[222:225], v[66:69]
	v_mfma_f32_16x16x32_bf16 v[94:97], v[164:167], v[218:221], v[94:97]
	v_mfma_f32_16x16x32_bf16 v[90:93], v[164:167], v[226:229], v[90:93]
	v_mfma_f32_16x16x32_bf16 v[86:89], v[194:197], v[218:221], v[86:89]
	v_mfma_f32_16x16x32_bf16 v[82:85], v[194:197], v[226:229], v[82:85]
	v_mfma_f32_16x16x32_bf16 v[78:81], v[202:205], v[218:221], v[78:81]
	v_mfma_f32_16x16x32_bf16 v[74:77], v[202:205], v[226:229], v[74:77]
	v_mfma_f32_16x16x32_bf16 v[70:73], v[210:213], v[218:221], v[70:73]
	v_mfma_f32_16x16x32_bf16 v[66:69], v[210:213], v[226:229], v[66:69]
	s_mov_b32 m0, s24
	v_lshl_add_u64 v[138:139], v[138:139], 0, s[42:43]
	s_barrier
	ds_read_b128 v[160:163], v142 offset:49152
	ds_read_b128 v[164:167], v142 offset:50176
	ds_read_b128 v[190:193], v142 offset:51200
	ds_read_b128 v[194:197], v142 offset:52224
	ds_read_b128 v[198:201], v142 offset:53248
	ds_read_b128 v[202:205], v142 offset:54272
	ds_read_b128 v[206:209], v142 offset:55296
	ds_read_b128 v[210:213], v142 offset:56320
	global_load_lds_dwordx4 v[138:139], off
	v_lshl_add_u64 v[138:139], v[230:231], 0, s[42:43]
	s_mov_b32 m0, s30
	s_nop 0
	global_load_lds_dwordx4 v[138:139], off
	s_barrier
;     __device__ __forceinline__ unsigned* BAR() const { return (unsigned*)(ws + OFF_BAR); }
; #define STAGE(bufoff, gbase, voff) do { _Pragma("unroll") for (int _i = 0; _i < 2; ++_i) \
;         __builtin_amdgcn_global_load_lds((const unsigned*)((const char*)(gbase) + voff[_i]), (LAS unsigned*)(lds + (bufoff) + ldsw + _i * 8192), 16, 0, 0); } while (0)
; #define LDA(dst, b, h) do { _Pragma("unroll") for (int m = 0; m < 4; ++m) _Pragma("unroll") for (int k = 0; k < 2; ++k) dst[m][k] = *(const LAS bf16x8*)(lds + SA(b, h) + aoff + m * 2048 + k * 1024); } while (0)
; #define LDB(dst, b, h) do { _Pragma("unroll") for (int n = 0; n < 2; ++n) _Pragma("unroll") for (int k = 0; k < 2; ++k) dst[n][k] = *(const LAS bf16x8*)(lds + SB(b, h) + boff + n * 2048 + k * 1024); } while (0)
; #define MMA(ai, bj, At, Bx) do { __builtin_amdgcn_s_setprio(1); _Pragma("unroll") for (int m = 0; m < 4; ++m) _Pragma("unroll") for (int n = 0; n < 2; ++n) _Pragma("unroll") for (int k = 0; k < 2; ++k) \
;       acc[ai][bj][m][n] = __builtin_amdgcn_mfma_f32_16x16x32_bf16(At[m][k], Bx[n][k], acc[ai][bj][m][n], 0, 0, 0); \
;     __builtin_amdgcn_s_setprio(0); } while (0)
; #define WAIT_V(n) asm volatile("s_waitcnt vmcnt(" #n ")" ::: "memory")
; #define WAIT_L(n) asm volatile("s_waitcnt lgkmcnt(" #n ")" ::: "memory")
; #define BAR __builtin_amdgcn_s_barrier()
; #define SCHED __builtin_amdgcn_sched_barrier(0)
;     ...
;         LDA(At, 1, 1); STAGE(SA(1, 0), a3, voffA);
;         BAR; WAIT_L(0); MMA(1, 0, At, B0); BAR; SCHED;
;         STAGE(SB(1, 1), b3 + hstepB, voffB);
;         WAIT_V(6); BAR; MMA(1, 1, At, B1); BAR;
;     }
;     { LDB(B0, 0, 0); LDA(At, 0, 0); STAGE(SA(1, 1), pA(nt - 1) + hstepA, voffA);
;       BAR; WAIT_L(0); MMA(0, 0, At, B0); BAR;
;       LDB(B1, 0, 1); BAR; WAIT_L(0); MMA(0, 1, At, B1); BAR;
;       LDA(At, 0, 1); WAIT_V(4); BAR; WAIT_L(0); MMA(1, 0, At, B0); MMA(1, 1, At, B1); BAR; }
	s_waitcnt lgkmcnt(0)
	v_mfma_f32_16x16x32_bf16 v[62:65], v[160:163], v[144:147], v[62:65]
	v_mfma_f32_16x16x32_bf16 v[58:61], v[160:163], v[152:155], v[58:61]
	v_mfma_f32_16x16x32_bf16 v[54:57], v[190:193], v[144:147], v[54:57]
	v_mfma_f32_16x16x32_bf16 v[50:53], v[190:193], v[152:155], v[50:53]
	v_mfma_f32_16x16x32_bf16 v[46:49], v[198:201], v[144:147], v[46:49]
	v_mfma_f32_16x16x32_bf16 v[42:45], v[198:201], v[152:155], v[42:45]
	v_mfma_f32_16x16x32_bf16 v[38:41], v[206:209], v[144:147], v[38:41]
	v_mfma_f32_16x16x32_bf16 v[34:37], v[206:209], v[152:155], v[34:37]
	v_mfma_f32_16x16x32_bf16 v[62:65], v[164:167], v[148:151], v[62:65]
	v_mfma_f32_16x16x32_bf16 v[58:61], v[164:167], v[156:159], v[58:61]
	v_mfma_f32_16x16x32_bf16 v[54:57], v[194:197], v[148:151], v[54:57]
	v_mfma_f32_16x16x32_bf16 v[50:53], v[194:197], v[156:159], v[50:53]
	v_mfma_f32_16x16x32_bf16 v[46:49], v[202:205], v[148:151], v[46:49]
	v_mfma_f32_16x16x32_bf16 v[42:45], v[202:205], v[156:159], v[42:45]
	v_mfma_f32_16x16x32_bf16 v[38:41], v[210:213], v[148:151], v[38:41]
	v_mfma_f32_16x16x32_bf16 v[34:37], v[210:213], v[156:159], v[34:37]
	s_barrier
	s_add_i32 s9, s16, s11
	v_lshl_add_u64 v[138:139], v[232:233], 0, s[50:51]
	s_mov_b32 m0, s9
	s_nop 0
	global_load_lds_dwordx4 v[138:139], off
	v_lshl_add_u64 v[138:139], v[234:235], 0, s[50:51]
	s_add_i32 m0, s9, 0x2000
	s_nop 0
	global_load_lds_dwordx4 v[138:139], off
	s_waitcnt vmcnt(6)
	s_barrier
	v_mfma_f32_16x16x32_bf16 v[30:33], v[160:163], v[214:217], v[30:33]
	v_mfma_f32_16x16x32_bf16 v[26:29], v[160:163], v[222:225], v[26:29]
	v_mfma_f32_16x16x32_bf16 v[22:25], v[190:193], v[214:217], v[22:25]
	v_mfma_f32_16x16x32_bf16 v[18:21], v[190:193], v[222:225], v[18:21]
	v_mfma_f32_16x16x32_bf16 v[14:17], v[198:201], v[214:217], v[14:17]
	v_mfma_f32_16x16x32_bf16 v[10:13], v[198:201], v[222:225], v[10:13]
	v_mfma_f32_16x16x32_bf16 v[6:9], v[206:209], v[214:217], v[6:9]
	v_mfma_f32_16x16x32_bf16 v[2:5], v[206:209], v[222:225], v[2:5]
	v_mfma_f32_16x16x32_bf16 v[30:33], v[164:167], v[218:221], v[30:33]
	v_mfma_f32_16x16x32_bf16 v[26:29], v[164:167], v[226:229], v[26:29]
	v_mfma_f32_16x16x32_bf16 v[22:25], v[194:197], v[218:221], v[22:25]
	v_mfma_f32_16x16x32_bf16 v[18:21], v[194:197], v[226:229], v[18:21]
	v_mfma_f32_16x16x32_bf16 v[14:17], v[202:205], v[218:221], v[14:17]
	v_mfma_f32_16x16x32_bf16 v[10:13], v[202:205], v[226:229], v[10:13]
	v_mfma_f32_16x16x32_bf16 v[6:9], v[210:213], v[218:221], v[6:9]
	v_mfma_f32_16x16x32_bf16 v[2:5], v[210:213], v[226:229], v[2:5]
	s_add_i32 s6, s6, 2
	s_add_u32 s4, s4, 0x100
	s_addc_u32 s5, s5, 0
	s_cmp_gt_u32 s6, 11
	s_barrier
	s_cbranch_scc0 .LBB0_227
	v_add_u32_e32 v138, 0, v143
	s_add_u32 s0, s0, 0x40780
	v_add_u32_e32 v136, 0x10000, v138
	s_addc_u32 s1, s1, 0
	s_mov_b32 m0, s8
	ds_read_b128 v[132:135], v136
	ds_read_b128 v[144:147], v136 offset:1024
	ds_read_b128 v[148:151], v136 offset:2048
	ds_read_b128 v[152:155], v136 offset:3072
	ds_read_b128 v[156:159], v142
	ds_read_b128 v[160:163], v142 offset:1024
	ds_read_b128 v[164:167], v142 offset:2048
	ds_read_b128 v[190:193], v142 offset:3072
	ds_read_b128 v[194:197], v142 offset:4096
	ds_read_b128 v[198:201], v142 offset:5120
	ds_read_b128 v[202:205], v142 offset:6144
	ds_read_b128 v[206:209], v142 offset:7168
	v_lshl_add_u64 v[136:137], s[0:1], 0, v[0:1]
	global_load_lds_dwordx4 v[136:137], off
	v_lshl_add_u64 v[130:131], s[0:1], 0, v[130:131]
	s_mov_b32 m0, s7
	s_nop 0
	global_load_lds_dwordx4 v[130:131], off
	s_barrier
	s_waitcnt lgkmcnt(0)
	v_mfma_f32_16x16x32_bf16 v[126:129], v[156:159], v[132:135], v[126:129]
	v_mfma_f32_16x16x32_bf16 v[122:125], v[156:159], v[148:151], v[122:125]
	v_mfma_f32_16x16x32_bf16 v[118:121], v[164:167], v[132:135], v[118:121]
	v_mfma_f32_16x16x32_bf16 v[114:117], v[164:167], v[148:151], v[114:117]
	v_mfma_f32_16x16x32_bf16 v[98:101], v[202:205], v[148:151], v[98:101]
	v_mfma_f32_16x16x32_bf16 v[126:129], v[160:163], v[144:147], v[126:129]
	v_mfma_f32_16x16x32_bf16 v[122:125], v[160:163], v[152:155], v[122:125]
	v_mfma_f32_16x16x32_bf16 v[118:121], v[190:193], v[144:147], v[118:121]
	v_mfma_f32_16x16x32_bf16 v[114:117], v[190:193], v[152:155], v[114:117]
	v_mfma_f32_16x16x32_bf16 v[110:113], v[194:197], v[132:135], v[110:113]
	v_mfma_f32_16x16x32_bf16 v[106:109], v[194:197], v[148:151], v[106:109]
	v_mfma_f32_16x16x32_bf16 v[102:105], v[202:205], v[132:135], v[102:105]
	v_mfma_f32_16x16x32_bf16 v[98:101], v[206:209], v[152:155], v[98:101]
	v_mfma_f32_16x16x32_bf16 v[210:213], v[198:201], v[144:147], v[110:113]
	v_mfma_f32_16x16x32_bf16 v[214:217], v[198:201], v[152:155], v[106:109]
	v_mfma_f32_16x16x32_bf16 v[218:221], v[206:209], v[144:147], v[102:105]
	v_add_u32_e32 v0, 0x14000, v138
	s_barrier
	s_nop 0
	ds_read_b128 v[102:105], v0
	ds_read_b128 v[106:109], v0 offset:1024
	ds_read_b128 v[110:113], v0 offset:2048
	ds_read_b128 v[222:225], v0 offset:3072
	s_barrier
	s_waitcnt lgkmcnt(0)
	v_mfma_f32_16x16x32_bf16 v[94:97], v[156:159], v[102:105], v[94:97]
	v_mfma_f32_16x16x32_bf16 v[90:93], v[156:159], v[110:113], v[90:93]
	v_mfma_f32_16x16x32_bf16 v[86:89], v[164:167], v[102:105], v[86:89]
	v_mfma_f32_16x16x32_bf16 v[82:85], v[164:167], v[110:113], v[82:85]
	v_mfma_f32_16x16x32_bf16 v[66:69], v[202:205], v[110:113], v[66:69]
	v_mfma_f32_16x16x32_bf16 v[94:97], v[160:163], v[106:109], v[94:97]
	v_mfma_f32_16x16x32_bf16 v[90:93], v[160:163], v[222:225], v[90:93]
	v_mfma_f32_16x16x32_bf16 v[86:89], v[190:193], v[106:109], v[86:89]
	v_mfma_f32_16x16x32_bf16 v[82:85], v[190:193], v[222:225], v[82:85]
	v_mfma_f32_16x16x32_bf16 v[78:81], v[194:197], v[102:105], v[78:81]
	v_mfma_f32_16x16x32_bf16 v[74:77], v[194:197], v[110:113], v[74:77]
	v_mfma_f32_16x16x32_bf16 v[70:73], v[202:205], v[102:105], v[70:73]
	v_mfma_f32_16x16x32_bf16 v[66:69], v[206:209], v[222:225], v[66:69]
	v_mfma_f32_16x16x32_bf16 v[156:159], v[198:201], v[106:109], v[78:81]
	v_mfma_f32_16x16x32_bf16 v[160:163], v[198:201], v[222:225], v[74:77]
	v_mfma_f32_16x16x32_bf16 v[164:167], v[206:209], v[106:109], v[70:73]
	s_barrier
;     __device__ __forceinline__ unsigned* BAR() const { return (unsigned*)(ws + OFF_BAR); }
; #define LDA(dst, b, h) do { _Pragma("unroll") for (int m = 0; m < 4; ++m) _Pragma("unroll") for (int k = 0; k < 2; ++k) dst[m][k] = *(const LAS bf16x8*)(lds + SA(b, h) + aoff + m * 2048 + k * 1024); } while (0)
; #define LDB(dst, b, h) do { _Pragma("unroll") for (int n = 0; n < 2; ++n) _Pragma("unroll") for (int k = 0; k < 2; ++k) dst[n][k] = *(const LAS bf16x8*)(lds + SB(b, h) + boff + n * 2048 + k * 1024); } while (0)
; #define MMA(ai, bj, At, Bx) do { __builtin_amdgcn_s_setprio(1); _Pragma("unroll") for (int m = 0; m < 4; ++m) _Pragma("unroll") for (int n = 0; n < 2; ++n) _Pragma("unroll") for (int k = 0; k < 2; ++k) \
;       acc[ai][bj][m][n] = __builtin_amdgcn_mfma_f32_16x16x32_bf16(At[m][k], Bx[n][k], acc[ai][bj][m][n], 0, 0, 0); \
;     __builtin_amdgcn_s_setprio(0); } while (0)
; #define WAIT_V(n) asm volatile("s_waitcnt vmcnt(" #n ")" ::: "memory")
; #define WAIT_L(n) asm volatile("s_waitcnt lgkmcnt(" #n ")" ::: "memory")
; #define BAR __builtin_amdgcn_s_barrier()
;     ...
;       LDB(B1, 0, 1); BAR; WAIT_L(0); MMA(0, 1, At, B1); BAR;
;       LDA(At, 0, 1); WAIT_V(4); BAR; WAIT_L(0); MMA(1, 0, At, B0); MMA(1, 1, At, B1); BAR; }
;     { LDB(B0, 1, 0); LDA(At, 1, 0); WAIT_V(2); BAR; WAIT_L(0); MMA(0, 0, At, B0); BAR;
;       LDB(B1, 1, 1); WAIT_V(0); BAR; WAIT_L(0); MMA(0, 1, At, B1); BAR;
	s_nop 1
	ds_read_b128 v[70:73], v142 offset:16384
	ds_read_b128 v[74:77], v142 offset:17408
	ds_read_b128 v[78:81], v142 offset:18432
	ds_read_b128 v[190:193], v142 offset:19456
	ds_read_b128 v[194:197], v142 offset:20480
	ds_read_b128 v[198:201], v142 offset:21504
	ds_read_b128 v[202:205], v142 offset:22528
	ds_read_b128 v[206:209], v142 offset:23552
	s_waitcnt vmcnt(4)
	s_barrier
	s_waitcnt lgkmcnt(0)
	v_mfma_f32_16x16x32_bf16 v[62:65], v[70:73], v[132:135], v[62:65]
	v_mfma_f32_16x16x32_bf16 v[58:61], v[70:73], v[148:151], v[58:61]
	v_mfma_f32_16x16x32_bf16 v[54:57], v[78:81], v[132:135], v[54:57]
	v_mfma_f32_16x16x32_bf16 v[50:53], v[78:81], v[148:151], v[50:53]
	v_mfma_f32_16x16x32_bf16 v[34:37], v[202:205], v[148:151], v[34:37]
	v_mfma_f32_16x16x32_bf16 v[62:65], v[74:77], v[144:147], v[62:65]
	v_mfma_f32_16x16x32_bf16 v[58:61], v[74:77], v[152:155], v[58:61]
	v_mfma_f32_16x16x32_bf16 v[54:57], v[190:193], v[144:147], v[54:57]
	v_mfma_f32_16x16x32_bf16 v[50:53], v[190:193], v[152:155], v[50:53]
	v_mfma_f32_16x16x32_bf16 v[46:49], v[194:197], v[132:135], v[46:49]
	v_mfma_f32_16x16x32_bf16 v[42:45], v[194:197], v[148:151], v[42:45]
	v_mfma_f32_16x16x32_bf16 v[38:41], v[202:205], v[132:135], v[38:41]
	v_mfma_f32_16x16x32_bf16 v[34:37], v[206:209], v[152:155], v[34:37]
	v_mfma_f32_16x16x32_bf16 v[226:229], v[198:201], v[144:147], v[46:49]
	v_mfma_f32_16x16x32_bf16 v[230:233], v[198:201], v[152:155], v[42:45]
	v_mfma_f32_16x16x32_bf16 v[130:133], v[206:209], v[144:147], v[38:41]
	v_mfma_f32_16x16x32_bf16 v[30:33], v[70:73], v[102:105], v[30:33]
	v_mfma_f32_16x16x32_bf16 v[26:29], v[70:73], v[110:113], v[26:29]
	v_mfma_f32_16x16x32_bf16 v[22:25], v[78:81], v[102:105], v[22:25]
	v_mfma_f32_16x16x32_bf16 v[18:21], v[78:81], v[110:113], v[18:21]
	v_mfma_f32_16x16x32_bf16 v[2:5], v[202:205], v[110:113], v[2:5]
	v_mfma_f32_16x16x32_bf16 v[30:33], v[74:77], v[106:109], v[30:33]
	v_mfma_f32_16x16x32_bf16 v[26:29], v[74:77], v[222:225], v[26:29]
	v_mfma_f32_16x16x32_bf16 v[22:25], v[190:193], v[106:109], v[22:25]
	v_mfma_f32_16x16x32_bf16 v[18:21], v[190:193], v[222:225], v[18:21]
	v_mfma_f32_16x16x32_bf16 v[14:17], v[194:197], v[102:105], v[14:17]
	v_mfma_f32_16x16x32_bf16 v[10:13], v[194:197], v[110:113], v[10:13]
	v_mfma_f32_16x16x32_bf16 v[6:9], v[202:205], v[102:105], v[6:9]
	v_mfma_f32_16x16x32_bf16 v[2:5], v[206:209], v[222:225], v[2:5]
	v_mfma_f32_16x16x32_bf16 v[134:137], v[198:201], v[106:109], v[14:17]
	v_mfma_f32_16x16x32_bf16 v[144:147], v[198:201], v[222:225], v[10:13]
	v_mfma_f32_16x16x32_bf16 v[148:151], v[206:209], v[106:109], v[6:9]
	v_add_u32_e32 v0, 0x18000, v138
	s_barrier
	s_nop 0
	ds_read_b128 v[6:9], v0
	ds_read_b128 v[10:13], v0 offset:1024
	ds_read_b128 v[14:17], v0 offset:2048
	ds_read_b128 v[152:155], v0 offset:3072
	ds_read_b128 v[38:41], v142 offset:32768
	ds_read_b128 v[42:45], v142 offset:33792
	ds_read_b128 v[46:49], v142 offset:34816
	ds_read_b128 v[70:73], v142 offset:35840
	ds_read_b128 v[190:193], v142 offset:36864
	ds_read_b128 v[194:197], v142 offset:37888
	ds_read_b128 v[198:201], v142 offset:38912
	ds_read_b128 v[202:205], v142 offset:39936
	s_waitcnt vmcnt(2)
	s_barrier
	s_waitcnt lgkmcnt(0)
	v_mfma_f32_16x16x32_bf16 v[74:77], v[38:41], v[6:9], v[126:129]
	v_mfma_f32_16x16x32_bf16 v[126:129], v[42:45], v[10:13], v[74:77]
	v_mfma_f32_16x16x32_bf16 v[74:77], v[38:41], v[14:17], v[122:125]
	v_mfma_f32_16x16x32_bf16 v[110:113], v[42:45], v[152:155], v[74:77]
	v_mfma_f32_16x16x32_bf16 v[74:77], v[46:49], v[6:9], v[118:121]
	v_mfma_f32_16x16x32_bf16 v[122:125], v[70:73], v[10:13], v[74:77]
	v_mfma_f32_16x16x32_bf16 v[74:77], v[46:49], v[14:17], v[114:117]
	v_mfma_f32_16x16x32_bf16 v[106:109], v[70:73], v[152:155], v[74:77]
	v_mfma_f32_16x16x32_bf16 v[74:77], v[190:193], v[6:9], v[210:213]
	v_mfma_f32_16x16x32_bf16 v[118:121], v[194:197], v[10:13], v[74:77]
	v_mfma_f32_16x16x32_bf16 v[74:77], v[190:193], v[14:17], v[214:217]
	v_mfma_f32_16x16x32_bf16 v[102:105], v[194:197], v[152:155], v[74:77]
	v_mfma_f32_16x16x32_bf16 v[74:77], v[198:201], v[6:9], v[218:221]
	v_mfma_f32_16x16x32_bf16 v[114:117], v[202:205], v[10:13], v[74:77]
	v_mfma_f32_16x16x32_bf16 v[74:77], v[198:201], v[14:17], v[98:101]
	v_mfma_f32_16x16x32_bf16 v[98:101], v[202:205], v[152:155], v[74:77]
	v_add_u32_e32 v0, 0x1c000, v138
	s_barrier
;     __device__ __forceinline__ unsigned* BAR() const { return (unsigned*)(ws + OFF_BAR); }
; #define LDA(dst, b, h) do { _Pragma("unroll") for (int m = 0; m < 4; ++m) _Pragma("unroll") for (int k = 0; k < 2; ++k) dst[m][k] = *(const LAS bf16x8*)(lds + SA(b, h) + aoff + m * 2048 + k * 1024); } while (0)
; #define LDB(dst, b, h) do { _Pragma("unroll") for (int n = 0; n < 2; ++n) _Pragma("unroll") for (int k = 0; k < 2; ++k) dst[n][k] = *(const LAS bf16x8*)(lds + SB(b, h) + boff + n * 2048 + k * 1024); } while (0)
; #define MMA(ai, bj, At, Bx) do { __builtin_amdgcn_s_setprio(1); _Pragma("unroll") for (int m = 0; m < 4; ++m) _Pragma("unroll") for (int n = 0; n < 2; ++n) _Pragma("unroll") for (int k = 0; k < 2; ++k) \
;       acc[ai][bj][m][n] = __builtin_amdgcn_mfma_f32_16x16x32_bf16(At[m][k], Bx[n][k], acc[ai][bj][m][n], 0, 0, 0); \
;     __builtin_amdgcn_s_setprio(0); } while (0)
; #define WAIT_V(n) asm volatile("s_waitcnt vmcnt(" #n ")" ::: "memory")
; #define WAIT_L(n) asm volatile("s_waitcnt lgkmcnt(" #n ")" ::: "memory")
; #define BAR __builtin_amdgcn_s_barrier()
;     ...
;     { LDB(B0, 1, 0); LDA(At, 1, 0); WAIT_V(2); BAR; WAIT_L(0); MMA(0, 0, At, B0); BAR;
;       LDB(B1, 1, 1); WAIT_V(0); BAR; WAIT_L(0); MMA(0, 1, At, B1); BAR;
;       LDA(At, 1, 1); BAR; WAIT_L(0); MMA(1, 0, At, B0); MMA(1, 1, At, B1); BAR; }
;     if (wr == 0) BAR;
	ds_read_b128 v[206:209], v0
	ds_read_b128 v[210:213], v0 offset:1024
	ds_read_b128 v[214:217], v0 offset:2048
	ds_read_b128 v[218:221], v0 offset:3072
	s_waitcnt vmcnt(0)
	s_barrier
	s_waitcnt lgkmcnt(0)
	v_mfma_f32_16x16x32_bf16 v[74:77], v[38:41], v[206:209], v[94:97]
	v_mfma_f32_16x16x32_bf16 v[38:41], v[38:41], v[214:217], v[90:93]
	v_mfma_f32_16x16x32_bf16 v[78:81], v[42:45], v[218:221], v[38:41]
	v_mfma_f32_16x16x32_bf16 v[38:41], v[46:49], v[206:209], v[86:89]
	v_mfma_f32_16x16x32_bf16 v[90:93], v[70:73], v[210:213], v[38:41]
	v_mfma_f32_16x16x32_bf16 v[38:41], v[46:49], v[214:217], v[82:85]
	v_mfma_f32_16x16x32_bf16 v[94:97], v[42:45], v[210:213], v[74:77]
	v_mfma_f32_16x16x32_bf16 v[74:77], v[70:73], v[218:221], v[38:41]
	v_mfma_f32_16x16x32_bf16 v[38:41], v[190:193], v[206:209], v[156:159]
	v_mfma_f32_16x16x32_bf16 v[86:89], v[194:197], v[210:213], v[38:41]
	v_mfma_f32_16x16x32_bf16 v[38:41], v[190:193], v[214:217], v[160:163]
	v_mfma_f32_16x16x32_bf16 v[70:73], v[194:197], v[218:221], v[38:41]
	v_mfma_f32_16x16x32_bf16 v[38:41], v[198:201], v[206:209], v[164:167]
	v_mfma_f32_16x16x32_bf16 v[82:85], v[202:205], v[210:213], v[38:41]
	v_mfma_f32_16x16x32_bf16 v[38:41], v[198:201], v[214:217], v[66:69]
	v_mfma_f32_16x16x32_bf16 v[66:69], v[202:205], v[218:221], v[38:41]
	s_barrier
	ds_read_b128 v[156:159], v142 offset:49152
	ds_read_b128 v[160:163], v142 offset:50176
	ds_read_b128 v[164:167], v142 offset:51200
	ds_read_b128 v[190:193], v142 offset:52224
	ds_read_b128 v[194:197], v142 offset:53248
	ds_read_b128 v[198:201], v142 offset:54272
	ds_read_b128 v[202:205], v142 offset:55296
	ds_read_b128 v[140:143], v142 offset:56320
	s_barrier
	s_waitcnt lgkmcnt(0)
	v_mfma_f32_16x16x32_bf16 v[38:41], v[156:159], v[6:9], v[62:65]
	v_mfma_f32_16x16x32_bf16 v[62:65], v[160:163], v[10:13], v[38:41]
	v_mfma_f32_16x16x32_bf16 v[38:41], v[156:159], v[14:17], v[58:61]
	v_mfma_f32_16x16x32_bf16 v[46:49], v[160:163], v[152:155], v[38:41]
	v_mfma_f32_16x16x32_bf16 v[38:41], v[164:167], v[6:9], v[54:57]
	v_mfma_f32_16x16x32_bf16 v[58:61], v[190:193], v[10:13], v[38:41]
	v_mfma_f32_16x16x32_bf16 v[38:41], v[164:167], v[14:17], v[50:53]
	v_mfma_f32_16x16x32_bf16 v[42:45], v[190:193], v[152:155], v[38:41]
	v_mfma_f32_16x16x32_bf16 v[38:41], v[194:197], v[6:9], v[226:229]
	v_mfma_f32_16x16x32_bf16 v[6:9], v[202:205], v[6:9], v[130:133]
	v_mfma_f32_16x16x32_bf16 v[54:57], v[198:201], v[10:13], v[38:41]
	v_mfma_f32_16x16x32_bf16 v[38:41], v[194:197], v[14:17], v[230:233]
	v_mfma_f32_16x16x32_bf16 v[50:53], v[140:143], v[10:13], v[6:9]
	v_mfma_f32_16x16x32_bf16 v[6:9], v[202:205], v[14:17], v[34:37]
	v_mfma_f32_16x16x32_bf16 v[38:41], v[198:201], v[152:155], v[38:41]
	v_mfma_f32_16x16x32_bf16 v[34:37], v[140:143], v[152:155], v[6:9]
	v_mfma_f32_16x16x32_bf16 v[6:9], v[156:159], v[206:209], v[30:33]
	v_mfma_f32_16x16x32_bf16 v[30:33], v[160:163], v[210:213], v[6:9]
	v_mfma_f32_16x16x32_bf16 v[6:9], v[156:159], v[214:217], v[26:29]
	v_mfma_f32_16x16x32_bf16 v[14:17], v[160:163], v[218:221], v[6:9]
	v_mfma_f32_16x16x32_bf16 v[6:9], v[164:167], v[206:209], v[22:25]
	v_mfma_f32_16x16x32_bf16 v[26:29], v[190:193], v[210:213], v[6:9]
	v_mfma_f32_16x16x32_bf16 v[6:9], v[164:167], v[214:217], v[18:21]
	v_mfma_f32_16x16x32_bf16 v[10:13], v[190:193], v[218:221], v[6:9]
	v_mfma_f32_16x16x32_bf16 v[6:9], v[194:197], v[206:209], v[134:137]
	v_mfma_f32_16x16x32_bf16 v[22:25], v[198:201], v[210:213], v[6:9]
	v_mfma_f32_16x16x32_bf16 v[6:9], v[194:197], v[214:217], v[144:147]
	v_mfma_f32_16x16x32_bf16 v[18:21], v[202:205], v[206:209], v[148:151]
	v_mfma_f32_16x16x32_bf16 v[2:5], v[202:205], v[214:217], v[2:5]
	v_mfma_f32_16x16x32_bf16 v[6:9], v[198:201], v[218:221], v[6:9]
	v_mfma_f32_16x16x32_bf16 v[18:21], v[140:143], v[210:213], v[18:21]
	v_mfma_f32_16x16x32_bf16 v[2:5], v[140:143], v[218:221], v[2:5]
	s_cmpk_lt_u32 s10, 0x100
	s_barrier
	s_cbranch_scc0 .LBB0_230
	s_barrier

;     __device__ __forceinline__ unsigned* BAR() const { return (unsigned*)(ws + OFF_BAR); }
; #define STAGE(bufoff, gbase, voff) do { _Pragma("unroll") for (int _i = 0; _i < 2; ++_i) \
;         __builtin_amdgcn_global_load_lds((const unsigned*)((const char*)(gbase) + voff[_i]), (LAS unsigned*)(lds + (bufoff) + ldsw + _i * 8192), 16, 0, 0); } while (0)
; #define LDA(dst, b, h) do { _Pragma("unroll") for (int m = 0; m < 4; ++m) _Pragma("unroll") for (int k = 0; k < 2; ++k) dst[m][k] = *(const LAS bf16x8*)(lds + SA(b, h) + aoff + m * 2048 + k * 1024); } while (0)
; #define LDB(dst, b, h) do { _Pragma("unroll") for (int n = 0; n < 2; ++n) _Pragma("unroll") for (int k = 0; k < 2; ++k) dst[n][k] = *(const LAS bf16x8*)(lds + SB(b, h) + boff + n * 2048 + k * 1024); } while (0)
; #define MMA(ai, bj, At, Bx) do { __builtin_amdgcn_s_setprio(1); _Pragma("unroll") for (int m = 0; m < 4; ++m) _Pragma("unroll") for (int n = 0; n < 2; ++n) _Pragma("unroll") for (int k = 0; k < 2; ++k) \
;       acc[ai][bj][m][n] = __builtin_amdgcn_mfma_f32_16x16x32_bf16(At[m][k], Bx[n][k], acc[ai][bj][m][n], 0, 0, 0); \
;     __builtin_amdgcn_s_setprio(0); } while (0)
; #define WAIT_L(n) asm volatile("s_waitcnt lgkmcnt(" #n ")" ::: "memory")
; #define BAR __builtin_amdgcn_s_barrier()
; #define SCHED __builtin_amdgcn_sched_barrier(0)
;     ...
;     for (int t = 0; t < nt - 2; t += 2) {
;         if (KSEG && t > 0 && (t % (KSEG ? KSEG : 1)) == 0) hook(t / (KSEG ? KSEG : 1), acc);
;         const char* a1 = pA(t + 1); const char* a2 = pA(t + 2); const char* a3 = pA(t + 3);
;         const char* b2 = pB(t + 2); const char* b3 = pB(t + 3);
;         LDB(B0, 0, 0); SCHED; LDA(At, 0, 0); STAGE(SA(1, 1), a1 + hstepA, voffA);
;         WAIT_L(8); BAR; WAIT_L(0); MMA(0, 0, At, B0); BAR; SCHED;
;         LDB(B1, 0, 1); STAGE(SB(0, 0), b2, voffB);
;         BAR; WAIT_L(0); MMA(0, 1, At, B1); BAR;
;         LDA(At, 0, 1); STAGE(SA(0, 0), a2, voffA);
.LBB0_377:
	s_add_i32 s9, 0, 0x10000
	v_add_u32_e32 v138, s9, v143
	ds_read_b128 v[144:147], v138
	ds_read_b128 v[148:151], v138 offset:1024
	ds_read_b128 v[152:155], v138 offset:2048
	ds_read_b128 v[156:159], v138 offset:3072
	v_lshl_add_u64 v[138:139], s[20:21], 0, v[136:137]
	s_add_i32 s8, s13, 0xc000
	v_lshl_add_u64 v[214:215], v[138:139], 0, s[54:55]
	s_mov_b32 m0, s8
	v_lshl_add_u64 v[230:231], s[20:21], 0, v[140:141]
	s_add_i32 s7, s13, 0xe000
	ds_read_b128 v[160:163], v142
	ds_read_b128 v[164:167], v142 offset:1024
	ds_read_b128 v[190:193], v142 offset:2048
	ds_read_b128 v[194:197], v142 offset:3072
	ds_read_b128 v[198:201], v142 offset:4096
	ds_read_b128 v[202:205], v142 offset:5120
	ds_read_b128 v[206:209], v142 offset:6144
	ds_read_b128 v[210:213], v142 offset:7168
	global_load_lds_dwordx4 v[214:215], off
	v_lshl_add_u64 v[214:215], v[230:231], 0, s[54:55]
	s_mov_b32 m0, s7
	s_nop 0
	global_load_lds_dwordx4 v[214:215], off
	s_waitcnt lgkmcnt(8)
	s_barrier
	s_waitcnt lgkmcnt(0)
	v_mfma_f32_16x16x32_bf16 v[126:129], v[160:163], v[144:147], v[126:129]
	v_mfma_f32_16x16x32_bf16 v[122:125], v[160:163], v[152:155], v[122:125]
	v_mfma_f32_16x16x32_bf16 v[118:121], v[190:193], v[144:147], v[118:121]
	v_mfma_f32_16x16x32_bf16 v[114:117], v[190:193], v[152:155], v[114:117]
	v_mfma_f32_16x16x32_bf16 v[110:113], v[198:201], v[144:147], v[110:113]
	v_mfma_f32_16x16x32_bf16 v[106:109], v[198:201], v[152:155], v[106:109]
	v_mfma_f32_16x16x32_bf16 v[102:105], v[206:209], v[144:147], v[102:105]
	v_mfma_f32_16x16x32_bf16 v[98:101], v[206:209], v[152:155], v[98:101]
	v_mfma_f32_16x16x32_bf16 v[126:129], v[164:167], v[148:151], v[126:129]
	v_mfma_f32_16x16x32_bf16 v[122:125], v[164:167], v[156:159], v[122:125]
	v_mfma_f32_16x16x32_bf16 v[118:121], v[194:197], v[148:151], v[118:121]
	v_mfma_f32_16x16x32_bf16 v[114:117], v[194:197], v[156:159], v[114:117]
	v_mfma_f32_16x16x32_bf16 v[110:113], v[202:205], v[148:151], v[110:113]
	v_mfma_f32_16x16x32_bf16 v[106:109], v[202:205], v[156:159], v[106:109]
	v_mfma_f32_16x16x32_bf16 v[102:105], v[210:213], v[148:151], v[102:105]
	v_mfma_f32_16x16x32_bf16 v[98:101], v[210:213], v[156:159], v[98:101]
	s_barrier
	s_add_i32 s10, 0, 0x14000
	v_lshl_add_u64 v[232:233], s[20:21], 0, v[132:133]
	s_add_i32 s9, s9, s1
	v_add_u32_e32 v226, s10, v143
	v_lshl_add_u64 v[234:235], v[232:233], 0, s[40:41]
	s_mov_b32 m0, s9
	ds_read_b128 v[214:217], v226
	ds_read_b128 v[218:221], v226 offset:1024
	ds_read_b128 v[222:225], v226 offset:2048
	ds_read_b128 v[226:229], v226 offset:3072
	global_load_lds_dwordx4 v[234:235], off
	v_lshl_add_u64 v[234:235], s[20:21], 0, v[134:135]
	v_lshl_add_u64 v[236:237], v[234:235], 0, s[40:41]
	s_add_i32 m0, s9, 0x2000
	s_nop 0
	global_load_lds_dwordx4 v[236:237], off
	s_barrier
	s_waitcnt lgkmcnt(0)
	v_mfma_f32_16x16x32_bf16 v[94:97], v[160:163], v[214:217], v[94:97]
	v_mfma_f32_16x16x32_bf16 v[90:93], v[160:163], v[222:225], v[90:93]
	v_mfma_f32_16x16x32_bf16 v[86:89], v[190:193], v[214:217], v[86:89]
	v_mfma_f32_16x16x32_bf16 v[82:85], v[190:193], v[222:225], v[82:85]
	v_mfma_f32_16x16x32_bf16 v[78:81], v[198:201], v[214:217], v[78:81]
	v_mfma_f32_16x16x32_bf16 v[74:77], v[198:201], v[222:225], v[74:77]
	v_mfma_f32_16x16x32_bf16 v[70:73], v[206:209], v[214:217], v[70:73]
	v_mfma_f32_16x16x32_bf16 v[66:69], v[206:209], v[222:225], v[66:69]
	v_mfma_f32_16x16x32_bf16 v[94:97], v[164:167], v[218:221], v[94:97]
	v_mfma_f32_16x16x32_bf16 v[90:93], v[164:167], v[226:229], v[90:93]
	v_mfma_f32_16x16x32_bf16 v[86:89], v[194:197], v[218:221], v[86:89]
	v_mfma_f32_16x16x32_bf16 v[82:85], v[194:197], v[226:229], v[82:85]
	v_mfma_f32_16x16x32_bf16 v[78:81], v[202:205], v[218:221], v[78:81]
	v_mfma_f32_16x16x32_bf16 v[74:77], v[202:205], v[226:229], v[74:77]
	v_mfma_f32_16x16x32_bf16 v[70:73], v[210:213], v[218:221], v[70:73]
	v_mfma_f32_16x16x32_bf16 v[66:69], v[210:213], v[226:229], v[66:69]
	s_mov_b32 m0, s13
	v_lshl_add_u64 v[236:237], v[138:139], 0, s[38:39]
	s_barrier
	ds_read_b128 v[160:163], v142 offset:16384
	ds_read_b128 v[164:167], v142 offset:17408
	ds_read_b128 v[190:193], v142 offset:18432
	ds_read_b128 v[194:197], v142 offset:19456
	ds_read_b128 v[198:201], v142 offset:20480
	ds_read_b128 v[202:205], v142 offset:21504
	ds_read_b128 v[206:209], v142 offset:22528
	ds_read_b128 v[210:213], v142 offset:23552
	global_load_lds_dwordx4 v[236:237], off
	v_lshl_add_u64 v[236:237], v[230:231], 0, s[38:39]
	s_mov_b32 m0, s14
	s_nop 0
	global_load_lds_dwordx4 v[236:237], off
	s_barrier
	s_waitcnt lgkmcnt(0)
	v_mfma_f32_16x16x32_bf16 v[62:65], v[160:163], v[144:147], v[62:65]
	v_mfma_f32_16x16x32_bf16 v[58:61], v[160:163], v[152:155], v[58:61]
	v_mfma_f32_16x16x32_bf16 v[54:57], v[190:193], v[144:147], v[54:57]
	v_mfma_f32_16x16x32_bf16 v[50:53], v[190:193], v[152:155], v[50:53]
	v_mfma_f32_16x16x32_bf16 v[46:49], v[198:201], v[144:147], v[46:49]
	v_mfma_f32_16x16x32_bf16 v[42:45], v[198:201], v[152:155], v[42:45]
	v_mfma_f32_16x16x32_bf16 v[38:41], v[206:209], v[144:147], v[38:41]
	v_mfma_f32_16x16x32_bf16 v[34:37], v[206:209], v[152:155], v[34:37]
	v_mfma_f32_16x16x32_bf16 v[62:65], v[164:167], v[148:151], v[62:65]
	v_mfma_f32_16x16x32_bf16 v[58:61], v[164:167], v[156:159], v[58:61]
	v_mfma_f32_16x16x32_bf16 v[54:57], v[194:197], v[148:151], v[54:57]
	v_mfma_f32_16x16x32_bf16 v[50:53], v[194:197], v[156:159], v[50:53]
	v_mfma_f32_16x16x32_bf16 v[46:49], v[202:205], v[148:151], v[46:49]
	v_mfma_f32_16x16x32_bf16 v[42:45], v[202:205], v[156:159], v[42:45]
	v_mfma_f32_16x16x32_bf16 v[38:41], v[210:213], v[148:151], v[38:41]
	v_mfma_f32_16x16x32_bf16 v[34:37], v[210:213], v[156:159], v[34:37]
	s_barrier
;     __device__ __forceinline__ unsigned* BAR() const { return (unsigned*)(ws + OFF_BAR); }
; #define STAGE(bufoff, gbase, voff) do { _Pragma("unroll") for (int _i = 0; _i < 2; ++_i) \
;         __builtin_amdgcn_global_load_lds((const unsigned*)((const char*)(gbase) + voff[_i]), (LAS unsigned*)(lds + (bufoff) + ldsw + _i * 8192), 16, 0, 0); } while (0)
; #define LDA(dst, b, h) do { _Pragma("unroll") for (int m = 0; m < 4; ++m) _Pragma("unroll") for (int k = 0; k < 2; ++k) dst[m][k] = *(const LAS bf16x8*)(lds + SA(b, h) + aoff + m * 2048 + k * 1024); } while (0)
; #define LDB(dst, b, h) do { _Pragma("unroll") for (int n = 0; n < 2; ++n) _Pragma("unroll") for (int k = 0; k < 2; ++k) dst[n][k] = *(const LAS bf16x8*)(lds + SB(b, h) + boff + n * 2048 + k * 1024); } while (0)
; #define MMA(ai, bj, At, Bx) do { __builtin_amdgcn_s_setprio(1); _Pragma("unroll") for (int m = 0; m < 4; ++m) _Pragma("unroll") for (int n = 0; n < 2; ++n) _Pragma("unroll") for (int k = 0; k < 2; ++k) \
;       acc[ai][bj][m][n] = __builtin_amdgcn_mfma_f32_16x16x32_bf16(At[m][k], Bx[n][k], acc[ai][bj][m][n], 0, 0, 0); \
;     __builtin_amdgcn_s_setprio(0); } while (0)
; #define WAIT_V(n) asm volatile("s_waitcnt vmcnt(" #n ")" ::: "memory")
; #define WAIT_L(n) asm volatile("s_waitcnt lgkmcnt(" #n ")" ::: "memory")
; #define BAR __builtin_amdgcn_s_barrier()
; #define SCHED __builtin_amdgcn_sched_barrier(0)
;     ...
;         LDA(At, 0, 1); STAGE(SA(0, 0), a2, voffA);
;         BAR; WAIT_L(0); MMA(1, 0, At, B0); BAR; SCHED;
;         STAGE(SB(0, 1), b2 + hstepB, voffB);
;         WAIT_V(6); BAR; MMA(1, 1, At, B1); BAR;
;         LDB(B0, 1, 0); SCHED; LDA(At, 1, 0); STAGE(SA(0, 1), a2 + hstepA, voffA);
;         WAIT_L(8); BAR; WAIT_L(0); MMA(0, 0, At, B0); BAR; SCHED;
;         LDB(B1, 1, 1); STAGE(SB(1, 0), b3, voffB);
;         BAR; WAIT_L(0); MMA(0, 1, At, B1); BAR;
;         LDA(At, 1, 1); STAGE(SA(1, 0), a3, voffA);
	s_add_i32 s9, s10, s1
	v_lshl_add_u64 v[144:145], v[232:233], 0, s[46:47]
	s_mov_b32 m0, s9
	s_nop 0
	global_load_lds_dwordx4 v[144:145], off
	v_lshl_add_u64 v[144:145], v[234:235], 0, s[46:47]
	s_add_i32 m0, s9, 0x2000
	s_nop 0
	global_load_lds_dwordx4 v[144:145], off
	s_waitcnt vmcnt(6)
	s_barrier
	v_mfma_f32_16x16x32_bf16 v[30:33], v[160:163], v[214:217], v[30:33]
	v_mfma_f32_16x16x32_bf16 v[26:29], v[160:163], v[222:225], v[26:29]
	v_mfma_f32_16x16x32_bf16 v[22:25], v[190:193], v[214:217], v[22:25]
	v_mfma_f32_16x16x32_bf16 v[18:21], v[190:193], v[222:225], v[18:21]
	v_mfma_f32_16x16x32_bf16 v[14:17], v[198:201], v[214:217], v[14:17]
	v_mfma_f32_16x16x32_bf16 v[10:13], v[198:201], v[222:225], v[10:13]
	v_mfma_f32_16x16x32_bf16 v[6:9], v[206:209], v[214:217], v[6:9]
	v_mfma_f32_16x16x32_bf16 v[2:5], v[206:209], v[222:225], v[2:5]
	v_mfma_f32_16x16x32_bf16 v[30:33], v[164:167], v[218:221], v[30:33]
	v_mfma_f32_16x16x32_bf16 v[26:29], v[164:167], v[226:229], v[26:29]
	v_mfma_f32_16x16x32_bf16 v[22:25], v[194:197], v[218:221], v[22:25]
	v_mfma_f32_16x16x32_bf16 v[18:21], v[194:197], v[226:229], v[18:21]
	v_mfma_f32_16x16x32_bf16 v[14:17], v[202:205], v[218:221], v[14:17]
	v_mfma_f32_16x16x32_bf16 v[10:13], v[202:205], v[226:229], v[10:13]
	v_mfma_f32_16x16x32_bf16 v[6:9], v[210:213], v[218:221], v[6:9]
	v_mfma_f32_16x16x32_bf16 v[2:5], v[210:213], v[226:229], v[2:5]
	s_add_i32 s9, 0, 0x18000
	v_add_u32_e32 v156, s9, v143
	s_barrier
	ds_read_b128 v[144:147], v156
	ds_read_b128 v[148:151], v156 offset:1024
	ds_read_b128 v[152:155], v156 offset:2048
	ds_read_b128 v[156:159], v156 offset:3072
	s_mov_b32 m0, s15
	v_lshl_add_u64 v[214:215], v[138:139], 0, s[44:45]
	ds_read_b128 v[160:163], v142 offset:32768
	ds_read_b128 v[164:167], v142 offset:33792
	ds_read_b128 v[190:193], v142 offset:34816
	ds_read_b128 v[194:197], v142 offset:35840
	ds_read_b128 v[198:201], v142 offset:36864
	ds_read_b128 v[202:205], v142 offset:37888
	ds_read_b128 v[206:209], v142 offset:38912
	ds_read_b128 v[210:213], v142 offset:39936
	global_load_lds_dwordx4 v[214:215], off
	v_lshl_add_u64 v[214:215], v[230:231], 0, s[44:45]
	s_mov_b32 m0, s30
	s_nop 0
	global_load_lds_dwordx4 v[214:215], off
	s_waitcnt lgkmcnt(8)
	s_barrier
	s_waitcnt lgkmcnt(0)
	v_mfma_f32_16x16x32_bf16 v[126:129], v[160:163], v[144:147], v[126:129]
	v_mfma_f32_16x16x32_bf16 v[122:125], v[160:163], v[152:155], v[122:125]
	v_mfma_f32_16x16x32_bf16 v[118:121], v[190:193], v[144:147], v[118:121]
	v_mfma_f32_16x16x32_bf16 v[114:117], v[190:193], v[152:155], v[114:117]
	v_mfma_f32_16x16x32_bf16 v[110:113], v[198:201], v[144:147], v[110:113]
	v_mfma_f32_16x16x32_bf16 v[106:109], v[198:201], v[152:155], v[106:109]
	v_mfma_f32_16x16x32_bf16 v[102:105], v[206:209], v[144:147], v[102:105]
	v_mfma_f32_16x16x32_bf16 v[98:101], v[206:209], v[152:155], v[98:101]
	v_mfma_f32_16x16x32_bf16 v[126:129], v[164:167], v[148:151], v[126:129]
	v_mfma_f32_16x16x32_bf16 v[122:125], v[164:167], v[156:159], v[122:125]
	v_mfma_f32_16x16x32_bf16 v[118:121], v[194:197], v[148:151], v[118:121]
	v_mfma_f32_16x16x32_bf16 v[114:117], v[194:197], v[156:159], v[114:117]
	v_mfma_f32_16x16x32_bf16 v[110:113], v[202:205], v[148:151], v[110:113]
	v_mfma_f32_16x16x32_bf16 v[106:109], v[202:205], v[156:159], v[106:109]
	v_mfma_f32_16x16x32_bf16 v[102:105], v[210:213], v[148:151], v[102:105]
	v_mfma_f32_16x16x32_bf16 v[98:101], v[210:213], v[156:159], v[98:101]
	s_barrier
	s_add_i32 s10, 0, 0x1c000
	s_add_i32 s9, s9, s1
	v_add_u32_e32 v226, s10, v143
	v_lshl_add_u64 v[236:237], v[232:233], 0, s[64:65]
	s_mov_b32 m0, s9
	ds_read_b128 v[214:217], v226
	ds_read_b128 v[218:221], v226 offset:1024
	ds_read_b128 v[222:225], v226 offset:2048
	ds_read_b128 v[226:229], v226 offset:3072
	global_load_lds_dwordx4 v[236:237], off
	v_lshl_add_u64 v[236:237], v[234:235], 0, s[64:65]
	s_add_i32 m0, s9, 0x2000
	s_nop 0
	global_load_lds_dwordx4 v[236:237], off
	s_barrier
	s_waitcnt lgkmcnt(0)
	v_mfma_f32_16x16x32_bf16 v[94:97], v[160:163], v[214:217], v[94:97]
	v_mfma_f32_16x16x32_bf16 v[90:93], v[160:163], v[222:225], v[90:93]
	v_mfma_f32_16x16x32_bf16 v[86:89], v[190:193], v[214:217], v[86:89]
	v_mfma_f32_16x16x32_bf16 v[82:85], v[190:193], v[222:225], v[82:85]
	v_mfma_f32_16x16x32_bf16 v[78:81], v[198:201], v[214:217], v[78:81]
	v_mfma_f32_16x16x32_bf16 v[74:77], v[198:201], v[222:225], v[74:77]
	v_mfma_f32_16x16x32_bf16 v[70:73], v[206:209], v[214:217], v[70:73]
	v_mfma_f32_16x16x32_bf16 v[66:69], v[206:209], v[222:225], v[66:69]
	v_mfma_f32_16x16x32_bf16 v[94:97], v[164:167], v[218:221], v[94:97]
	v_mfma_f32_16x16x32_bf16 v[90:93], v[164:167], v[226:229], v[90:93]
	v_mfma_f32_16x16x32_bf16 v[86:89], v[194:197], v[218:221], v[86:89]
	v_mfma_f32_16x16x32_bf16 v[82:85], v[194:197], v[226:229], v[82:85]
	v_mfma_f32_16x16x32_bf16 v[78:81], v[202:205], v[218:221], v[78:81]
	v_mfma_f32_16x16x32_bf16 v[74:77], v[202:205], v[226:229], v[74:77]
	v_mfma_f32_16x16x32_bf16 v[70:73], v[210:213], v[218:221], v[70:73]
	v_mfma_f32_16x16x32_bf16 v[66:69], v[210:213], v[226:229], v[66:69]
	s_mov_b32 m0, s31
	v_lshl_add_u64 v[138:139], v[138:139], 0, s[48:49]
	s_barrier
	ds_read_b128 v[160:163], v142 offset:49152
	ds_read_b128 v[164:167], v142 offset:50176
	ds_read_b128 v[190:193], v142 offset:51200
	ds_read_b128 v[194:197], v142 offset:52224
	ds_read_b128 v[198:201], v142 offset:53248
	ds_read_b128 v[202:205], v142 offset:54272
	ds_read_b128 v[206:209], v142 offset:55296
	ds_read_b128 v[210:213], v142 offset:56320
	global_load_lds_dwordx4 v[138:139], off
	v_lshl_add_u64 v[138:139], v[230:231], 0, s[48:49]
	s_mov_b32 m0, s42
	s_nop 0
	global_load_lds_dwordx4 v[138:139], off
	s_barrier
;     __device__ __forceinline__ unsigned* BAR() const { return (unsigned*)(ws + OFF_BAR); }
; #define STAGE(bufoff, gbase, voff) do { _Pragma("unroll") for (int _i = 0; _i < 2; ++_i) \
;         __builtin_amdgcn_global_load_lds((const unsigned*)((const char*)(gbase) + voff[_i]), (LAS unsigned*)(lds + (bufoff) + ldsw + _i * 8192), 16, 0, 0); } while (0)
; #define LDA(dst, b, h) do { _Pragma("unroll") for (int m = 0; m < 4; ++m) _Pragma("unroll") for (int k = 0; k < 2; ++k) dst[m][k] = *(const LAS bf16x8*)(lds + SA(b, h) + aoff + m * 2048 + k * 1024); } while (0)
; #define LDB(dst, b, h) do { _Pragma("unroll") for (int n = 0; n < 2; ++n) _Pragma("unroll") for (int k = 0; k < 2; ++k) dst[n][k] = *(const LAS bf16x8*)(lds + SB(b, h) + boff + n * 2048 + k * 1024); } while (0)
; #define MMA(ai, bj, At, Bx) do { __builtin_amdgcn_s_setprio(1); _Pragma("unroll") for (int m = 0; m < 4; ++m) _Pragma("unroll") for (int n = 0; n < 2; ++n) _Pragma("unroll") for (int k = 0; k < 2; ++k) \
;       acc[ai][bj][m][n] = __builtin_amdgcn_mfma_f32_16x16x32_bf16(At[m][k], Bx[n][k], acc[ai][bj][m][n], 0, 0, 0); \
;     __builtin_amdgcn_s_setprio(0); } while (0)
; #define WAIT_V(n) asm volatile("s_waitcnt vmcnt(" #n ")" ::: "memory")
; #define WAIT_L(n) asm volatile("s_waitcnt lgkmcnt(" #n ")" ::: "memory")
; #define BAR __builtin_amdgcn_s_barrier()
; #define SCHED __builtin_amdgcn_sched_barrier(0)
;     ...
;         LDA(At, 1, 1); STAGE(SA(1, 0), a3, voffA);
;         BAR; WAIT_L(0); MMA(1, 0, At, B0); BAR; SCHED;
;         STAGE(SB(1, 1), b3 + hstepB, voffB);
;         WAIT_V(6); BAR; MMA(1, 1, At, B1); BAR;
;     }
;     { LDB(B0, 0, 0); LDA(At, 0, 0); STAGE(SA(1, 1), pA(nt - 1) + hstepA, voffA);
;       BAR; WAIT_L(0); MMA(0, 0, At, B0); BAR;
;       LDB(B1, 0, 1); BAR; WAIT_L(0); MMA(0, 1, At, B1); BAR;
;       LDA(At, 0, 1); WAIT_V(4); BAR; WAIT_L(0); MMA(1, 0, At, B0); MMA(1, 1, At, B1); BAR; }
	s_waitcnt lgkmcnt(0)
	v_mfma_f32_16x16x32_bf16 v[62:65], v[160:163], v[144:147], v[62:65]
	v_mfma_f32_16x16x32_bf16 v[58:61], v[160:163], v[152:155], v[58:61]
	v_mfma_f32_16x16x32_bf16 v[54:57], v[190:193], v[144:147], v[54:57]
	v_mfma_f32_16x16x32_bf16 v[50:53], v[190:193], v[152:155], v[50:53]
	v_mfma_f32_16x16x32_bf16 v[46:49], v[198:201], v[144:147], v[46:49]
	v_mfma_f32_16x16x32_bf16 v[42:45], v[198:201], v[152:155], v[42:45]
	v_mfma_f32_16x16x32_bf16 v[38:41], v[206:209], v[144:147], v[38:41]
	v_mfma_f32_16x16x32_bf16 v[34:37], v[206:209], v[152:155], v[34:37]
	v_mfma_f32_16x16x32_bf16 v[62:65], v[164:167], v[148:151], v[62:65]
	v_mfma_f32_16x16x32_bf16 v[58:61], v[164:167], v[156:159], v[58:61]
	v_mfma_f32_16x16x32_bf16 v[54:57], v[194:197], v[148:151], v[54:57]
	v_mfma_f32_16x16x32_bf16 v[50:53], v[194:197], v[156:159], v[50:53]
	v_mfma_f32_16x16x32_bf16 v[46:49], v[202:205], v[148:151], v[46:49]
	v_mfma_f32_16x16x32_bf16 v[42:45], v[202:205], v[156:159], v[42:45]
	v_mfma_f32_16x16x32_bf16 v[38:41], v[210:213], v[148:151], v[38:41]
	v_mfma_f32_16x16x32_bf16 v[34:37], v[210:213], v[156:159], v[34:37]
	s_barrier
	s_add_i32 s9, s10, s1
	v_lshl_add_u64 v[138:139], v[232:233], 0, s[56:57]
	s_mov_b32 m0, s9
	s_nop 0
	global_load_lds_dwordx4 v[138:139], off
	v_lshl_add_u64 v[138:139], v[234:235], 0, s[56:57]
	s_add_i32 m0, s9, 0x2000
	s_nop 0
	global_load_lds_dwordx4 v[138:139], off
	s_waitcnt vmcnt(6)
	s_barrier
	v_mfma_f32_16x16x32_bf16 v[30:33], v[160:163], v[214:217], v[30:33]
	v_mfma_f32_16x16x32_bf16 v[26:29], v[160:163], v[222:225], v[26:29]
	v_mfma_f32_16x16x32_bf16 v[22:25], v[190:193], v[214:217], v[22:25]
	v_mfma_f32_16x16x32_bf16 v[18:21], v[190:193], v[222:225], v[18:21]
	v_mfma_f32_16x16x32_bf16 v[14:17], v[198:201], v[214:217], v[14:17]
	v_mfma_f32_16x16x32_bf16 v[10:13], v[198:201], v[222:225], v[10:13]
	v_mfma_f32_16x16x32_bf16 v[6:9], v[206:209], v[214:217], v[6:9]
	v_mfma_f32_16x16x32_bf16 v[2:5], v[206:209], v[222:225], v[2:5]
	v_mfma_f32_16x16x32_bf16 v[30:33], v[164:167], v[218:221], v[30:33]
	v_mfma_f32_16x16x32_bf16 v[26:29], v[164:167], v[226:229], v[26:29]
	v_mfma_f32_16x16x32_bf16 v[22:25], v[194:197], v[218:221], v[22:25]
	v_mfma_f32_16x16x32_bf16 v[18:21], v[194:197], v[226:229], v[18:21]
	v_mfma_f32_16x16x32_bf16 v[14:17], v[202:205], v[218:221], v[14:17]
	v_mfma_f32_16x16x32_bf16 v[10:13], v[202:205], v[226:229], v[10:13]
	v_mfma_f32_16x16x32_bf16 v[6:9], v[210:213], v[218:221], v[6:9]
	v_mfma_f32_16x16x32_bf16 v[2:5], v[210:213], v[226:229], v[2:5]
	s_add_i32 s6, s6, 2
	v_lshl_add_u64 v[132:133], v[132:133], 0, s[40:41]
	v_lshl_add_u64 v[134:135], v[134:135], 0, s[40:41]
	v_lshl_add_u64 v[136:137], v[136:137], 0, s[40:41]
	s_cmp_gt_u32 s6, 11
	v_lshl_add_u64 v[140:141], v[140:141], 0, s[40:41]
	s_barrier
	s_cbranch_scc0 .LBB0_377
	v_add_u32_e32 v138, 0, v143
	s_add_u32 s4, s4, 0x40780
	v_add_u32_e32 v136, 0x10000, v138
	s_addc_u32 s5, s5, 0
	s_mov_b32 m0, s8
	ds_read_b128 v[132:135], v136
	ds_read_b128 v[144:147], v136 offset:1024
	ds_read_b128 v[148:151], v136 offset:2048
	ds_read_b128 v[152:155], v136 offset:3072
	ds_read_b128 v[156:159], v142
	ds_read_b128 v[160:163], v142 offset:1024
	ds_read_b128 v[164:167], v142 offset:2048
	ds_read_b128 v[190:193], v142 offset:3072
	ds_read_b128 v[194:197], v142 offset:4096
	ds_read_b128 v[198:201], v142 offset:5120
	ds_read_b128 v[202:205], v142 offset:6144
	ds_read_b128 v[206:209], v142 offset:7168
	v_lshl_add_u64 v[136:137], s[4:5], 0, v[0:1]
	global_load_lds_dwordx4 v[136:137], off
	v_lshl_add_u64 v[130:131], s[4:5], 0, v[130:131]
	s_mov_b32 m0, s7
	s_nop 0
	global_load_lds_dwordx4 v[130:131], off
	s_barrier
	s_waitcnt lgkmcnt(0)
	v_mfma_f32_16x16x32_bf16 v[126:129], v[156:159], v[132:135], v[126:129]
	v_mfma_f32_16x16x32_bf16 v[122:125], v[156:159], v[148:151], v[122:125]
	v_mfma_f32_16x16x32_bf16 v[118:121], v[164:167], v[132:135], v[118:121]
	v_mfma_f32_16x16x32_bf16 v[110:113], v[194:197], v[132:135], v[110:113]
	v_mfma_f32_16x16x32_bf16 v[106:109], v[194:197], v[148:151], v[106:109]
	v_mfma_f32_16x16x32_bf16 v[102:105], v[202:205], v[132:135], v[102:105]
	v_mfma_f32_16x16x32_bf16 v[98:101], v[202:205], v[148:151], v[98:101]
	v_mfma_f32_16x16x32_bf16 v[126:129], v[160:163], v[144:147], v[126:129]
	v_mfma_f32_16x16x32_bf16 v[122:125], v[160:163], v[152:155], v[122:125]
	v_mfma_f32_16x16x32_bf16 v[118:121], v[190:193], v[144:147], v[118:121]
	v_mfma_f32_16x16x32_bf16 v[114:117], v[164:167], v[148:151], v[114:117]
	v_mfma_f32_16x16x32_bf16 v[110:113], v[198:201], v[144:147], v[110:113]
	v_mfma_f32_16x16x32_bf16 v[106:109], v[198:201], v[152:155], v[106:109]
	v_mfma_f32_16x16x32_bf16 v[102:105], v[206:209], v[144:147], v[102:105]
	v_mfma_f32_16x16x32_bf16 v[98:101], v[206:209], v[152:155], v[98:101]
	v_mfma_f32_16x16x32_bf16 v[210:213], v[190:193], v[152:155], v[114:117]
	v_add_u32_e32 v0, 0x14000, v138
	s_barrier
	ds_read_b128 v[114:117], v0
	ds_read_b128 v[214:217], v0 offset:1024
	ds_read_b128 v[218:221], v0 offset:2048
	ds_read_b128 v[222:225], v0 offset:3072
	s_barrier
	s_waitcnt lgkmcnt(0)
	v_mfma_f32_16x16x32_bf16 v[78:81], v[194:197], v[114:117], v[78:81]
	v_mfma_f32_16x16x32_bf16 v[74:77], v[194:197], v[218:221], v[74:77]
	v_mfma_f32_16x16x32_bf16 v[70:73], v[202:205], v[114:117], v[70:73]
	v_mfma_f32_16x16x32_bf16 v[66:69], v[202:205], v[218:221], v[66:69]
	v_mfma_f32_16x16x32_bf16 v[94:97], v[156:159], v[114:117], v[94:97]
	v_mfma_f32_16x16x32_bf16 v[90:93], v[156:159], v[218:221], v[90:93]
	v_mfma_f32_16x16x32_bf16 v[86:89], v[164:167], v[114:117], v[86:89]
	v_mfma_f32_16x16x32_bf16 v[82:85], v[164:167], v[218:221], v[82:85]
	v_mfma_f32_16x16x32_bf16 v[78:81], v[198:201], v[214:217], v[78:81]
	v_mfma_f32_16x16x32_bf16 v[74:77], v[198:201], v[222:225], v[74:77]
	v_mfma_f32_16x16x32_bf16 v[70:73], v[206:209], v[214:217], v[70:73]
	v_mfma_f32_16x16x32_bf16 v[66:69], v[206:209], v[222:225], v[66:69]
	v_mfma_f32_16x16x32_bf16 v[226:229], v[160:163], v[214:217], v[94:97]
	v_mfma_f32_16x16x32_bf16 v[156:159], v[160:163], v[222:225], v[90:93]
	v_mfma_f32_16x16x32_bf16 v[160:163], v[190:193], v[214:217], v[86:89]
	v_mfma_f32_16x16x32_bf16 v[164:167], v[190:193], v[222:225], v[82:85]
	s_barrier
;     __device__ __forceinline__ unsigned* BAR() const { return (unsigned*)(ws + OFF_BAR); }
; #define LDA(dst, b, h) do { _Pragma("unroll") for (int m = 0; m < 4; ++m) _Pragma("unroll") for (int k = 0; k < 2; ++k) dst[m][k] = *(const LAS bf16x8*)(lds + SA(b, h) + aoff + m * 2048 + k * 1024); } while (0)
; #define LDB(dst, b, h) do { _Pragma("unroll") for (int n = 0; n < 2; ++n) _Pragma("unroll") for (int k = 0; k < 2; ++k) dst[n][k] = *(const LAS bf16x8*)(lds + SB(b, h) + boff + n * 2048 + k * 1024); } while (0)
; #define MMA(ai, bj, At, Bx) do { __builtin_amdgcn_s_setprio(1); _Pragma("unroll") for (int m = 0; m < 4; ++m) _Pragma("unroll") for (int n = 0; n < 2; ++n) _Pragma("unroll") for (int k = 0; k < 2; ++k) \
;       acc[ai][bj][m][n] = __builtin_amdgcn_mfma_f32_16x16x32_bf16(At[m][k], Bx[n][k], acc[ai][bj][m][n], 0, 0, 0); \
;     __builtin_amdgcn_s_setprio(0); } while (0)
; #define WAIT_V(n) asm volatile("s_waitcnt vmcnt(" #n ")" ::: "memory")
; #define WAIT_L(n) asm volatile("s_waitcnt lgkmcnt(" #n ")" ::: "memory")
; #define BAR __builtin_amdgcn_s_barrier()
;     ...
;       LDB(B1, 0, 1); BAR; WAIT_L(0); MMA(0, 1, At, B1); BAR;
;       LDA(At, 0, 1); WAIT_V(4); BAR; WAIT_L(0); MMA(1, 0, At, B0); MMA(1, 1, At, B1); BAR; }
;     { LDB(B0, 1, 0); LDA(At, 1, 0); WAIT_V(2); BAR; WAIT_L(0); MMA(0, 0, At, B0); BAR;
;       LDB(B1, 1, 1); WAIT_V(0); BAR; WAIT_L(0); MMA(0, 1, At, B1); BAR;
	s_nop 0
	ds_read_b128 v[82:85], v142 offset:16384
	ds_read_b128 v[86:89], v142 offset:17408
	ds_read_b128 v[90:93], v142 offset:18432
	ds_read_b128 v[94:97], v142 offset:19456
	ds_read_b128 v[190:193], v142 offset:20480
	ds_read_b128 v[194:197], v142 offset:21504
	ds_read_b128 v[198:201], v142 offset:22528
	ds_read_b128 v[202:205], v142 offset:23552
	s_waitcnt vmcnt(4)
	s_barrier
	s_waitcnt lgkmcnt(0)
	v_mfma_f32_16x16x32_bf16 v[46:49], v[190:193], v[132:135], v[46:49]
	v_mfma_f32_16x16x32_bf16 v[42:45], v[190:193], v[148:151], v[42:45]
	v_mfma_f32_16x16x32_bf16 v[38:41], v[198:201], v[132:135], v[38:41]
	v_mfma_f32_16x16x32_bf16 v[34:37], v[198:201], v[148:151], v[34:37]
	v_mfma_f32_16x16x32_bf16 v[62:65], v[82:85], v[132:135], v[62:65]
	v_mfma_f32_16x16x32_bf16 v[58:61], v[82:85], v[148:151], v[58:61]
	v_mfma_f32_16x16x32_bf16 v[54:57], v[90:93], v[132:135], v[54:57]
	v_mfma_f32_16x16x32_bf16 v[50:53], v[90:93], v[148:151], v[50:53]
	v_mfma_f32_16x16x32_bf16 v[46:49], v[194:197], v[144:147], v[46:49]
	v_mfma_f32_16x16x32_bf16 v[42:45], v[194:197], v[152:155], v[42:45]
	v_mfma_f32_16x16x32_bf16 v[38:41], v[202:205], v[144:147], v[38:41]
	v_mfma_f32_16x16x32_bf16 v[34:37], v[202:205], v[152:155], v[34:37]
	v_mfma_f32_16x16x32_bf16 v[206:209], v[86:89], v[144:147], v[62:65]
	v_mfma_f32_16x16x32_bf16 v[230:233], v[86:89], v[152:155], v[58:61]
	v_mfma_f32_16x16x32_bf16 v[234:237], v[94:97], v[144:147], v[54:57]
	v_mfma_f32_16x16x32_bf16 v[238:241], v[94:97], v[152:155], v[50:53]
	v_mfma_f32_16x16x32_bf16 v[2:5], v[198:201], v[218:221], v[2:5]
	v_mfma_f32_16x16x32_bf16 v[30:33], v[82:85], v[114:117], v[30:33]
	v_mfma_f32_16x16x32_bf16 v[26:29], v[82:85], v[218:221], v[26:29]
	v_mfma_f32_16x16x32_bf16 v[22:25], v[90:93], v[114:117], v[22:25]
	v_mfma_f32_16x16x32_bf16 v[18:21], v[90:93], v[218:221], v[18:21]
	v_mfma_f32_16x16x32_bf16 v[14:17], v[190:193], v[114:117], v[14:17]
	v_mfma_f32_16x16x32_bf16 v[10:13], v[190:193], v[218:221], v[10:13]
	v_mfma_f32_16x16x32_bf16 v[6:9], v[198:201], v[114:117], v[6:9]
	v_mfma_f32_16x16x32_bf16 v[2:5], v[202:205], v[222:225], v[2:5]
	v_mfma_f32_16x16x32_bf16 v[130:133], v[86:89], v[214:217], v[30:33]
	v_mfma_f32_16x16x32_bf16 v[134:137], v[86:89], v[222:225], v[26:29]
	v_mfma_f32_16x16x32_bf16 v[144:147], v[94:97], v[214:217], v[22:25]
	v_mfma_f32_16x16x32_bf16 v[148:151], v[94:97], v[222:225], v[18:21]
	v_mfma_f32_16x16x32_bf16 v[152:155], v[194:197], v[214:217], v[14:17]
	v_mfma_f32_16x16x32_bf16 v[190:193], v[194:197], v[222:225], v[10:13]
	v_mfma_f32_16x16x32_bf16 v[194:197], v[202:205], v[214:217], v[6:9]
	v_add_u32_e32 v0, 0x18000, v138
	s_barrier
	ds_read_b128 v[6:9], v0
	ds_read_b128 v[10:13], v0 offset:1024
	ds_read_b128 v[14:17], v0 offset:2048
	ds_read_b128 v[198:201], v0 offset:3072
	ds_read_b128 v[18:21], v142 offset:32768
	ds_read_b128 v[22:25], v142 offset:33792
	ds_read_b128 v[26:29], v142 offset:34816
	ds_read_b128 v[50:53], v142 offset:35840
	ds_read_b128 v[202:205], v142 offset:36864
	ds_read_b128 v[214:217], v142 offset:37888
	ds_read_b128 v[218:221], v142 offset:38912
	ds_read_b128 v[222:225], v142 offset:39936
	s_waitcnt vmcnt(2)
	s_barrier
	s_waitcnt lgkmcnt(0)
	v_mfma_f32_16x16x32_bf16 v[30:33], v[18:21], v[6:9], v[126:129]
	v_mfma_f32_16x16x32_bf16 v[114:117], v[22:25], v[10:13], v[30:33]
	v_mfma_f32_16x16x32_bf16 v[30:33], v[18:21], v[14:17], v[122:125]
	v_mfma_f32_16x16x32_bf16 v[94:97], v[22:25], v[198:201], v[30:33]
	v_mfma_f32_16x16x32_bf16 v[30:33], v[26:29], v[6:9], v[118:121]
	v_mfma_f32_16x16x32_bf16 v[118:121], v[50:53], v[10:13], v[30:33]
	v_mfma_f32_16x16x32_bf16 v[30:33], v[26:29], v[14:17], v[210:213]
	v_mfma_f32_16x16x32_bf16 v[90:93], v[50:53], v[198:201], v[30:33]
	v_mfma_f32_16x16x32_bf16 v[30:33], v[202:205], v[6:9], v[110:113]
	v_mfma_f32_16x16x32_bf16 v[122:125], v[214:217], v[10:13], v[30:33]
	v_mfma_f32_16x16x32_bf16 v[30:33], v[202:205], v[14:17], v[106:109]
	v_mfma_f32_16x16x32_bf16 v[86:89], v[214:217], v[198:201], v[30:33]
	v_mfma_f32_16x16x32_bf16 v[30:33], v[218:221], v[6:9], v[102:105]
	v_mfma_f32_16x16x32_bf16 v[126:129], v[222:225], v[10:13], v[30:33]
	v_mfma_f32_16x16x32_bf16 v[30:33], v[218:221], v[14:17], v[98:101]
	v_mfma_f32_16x16x32_bf16 v[82:85], v[222:225], v[198:201], v[30:33]
	v_add_u32_e32 v0, 0x1c000, v138
	s_barrier
;     __device__ __forceinline__ unsigned* BAR() const { return (unsigned*)(ws + OFF_BAR); }
; #define LDA(dst, b, h) do { _Pragma("unroll") for (int m = 0; m < 4; ++m) _Pragma("unroll") for (int k = 0; k < 2; ++k) dst[m][k] = *(const LAS bf16x8*)(lds + SA(b, h) + aoff + m * 2048 + k * 1024); } while (0)
; #define LDB(dst, b, h) do { _Pragma("unroll") for (int n = 0; n < 2; ++n) _Pragma("unroll") for (int k = 0; k < 2; ++k) dst[n][k] = *(const LAS bf16x8*)(lds + SB(b, h) + boff + n * 2048 + k * 1024); } while (0)
; #define MMA(ai, bj, At, Bx) do { __builtin_amdgcn_s_setprio(1); _Pragma("unroll") for (int m = 0; m < 4; ++m) _Pragma("unroll") for (int n = 0; n < 2; ++n) _Pragma("unroll") for (int k = 0; k < 2; ++k) \
;       acc[ai][bj][m][n] = __builtin_amdgcn_mfma_f32_16x16x32_bf16(At[m][k], Bx[n][k], acc[ai][bj][m][n], 0, 0, 0); \
;     __builtin_amdgcn_s_setprio(0); } while (0)
; #define WAIT_V(n) asm volatile("s_waitcnt vmcnt(" #n ")" ::: "memory")
; #define WAIT_L(n) asm volatile("s_waitcnt lgkmcnt(" #n ")" ::: "memory")
; #define BAR __builtin_amdgcn_s_barrier()
;     ...
;     { LDB(B0, 1, 0); LDA(At, 1, 0); WAIT_V(2); BAR; WAIT_L(0); MMA(0, 0, At, B0); BAR;
;       LDB(B1, 1, 1); WAIT_V(0); BAR; WAIT_L(0); MMA(0, 1, At, B1); BAR;
;       LDA(At, 1, 1); BAR; WAIT_L(0); MMA(1, 0, At, B0); MMA(1, 1, At, B1); BAR; }
;     if (wr == 0) BAR;
	ds_read_b128 v[210:213], v0
	ds_read_b128 v[242:245], v0 offset:1024
	ds_read_b128 v[246:249], v0 offset:2048
	ds_read_b128 v[138:141], v0 offset:3072
	s_waitcnt vmcnt(0)
	s_barrier
	s_waitcnt lgkmcnt(0)
	v_mfma_f32_16x16x32_bf16 v[30:33], v[18:21], v[210:213], v[226:229]
	v_mfma_f32_16x16x32_bf16 v[18:21], v[18:21], v[246:249], v[156:159]
	v_mfma_f32_16x16x32_bf16 v[62:65], v[22:25], v[242:245], v[30:33]
	v_mfma_f32_16x16x32_bf16 v[30:33], v[22:25], v[138:141], v[18:21]
	v_mfma_f32_16x16x32_bf16 v[18:21], v[26:29], v[210:213], v[160:163]
	v_mfma_f32_16x16x32_bf16 v[58:61], v[50:53], v[242:245], v[18:21]
	v_mfma_f32_16x16x32_bf16 v[18:21], v[26:29], v[246:249], v[164:167]
	v_mfma_f32_16x16x32_bf16 v[26:29], v[50:53], v[138:141], v[18:21]
	v_mfma_f32_16x16x32_bf16 v[18:21], v[202:205], v[210:213], v[78:81]
	v_mfma_f32_16x16x32_bf16 v[54:57], v[214:217], v[242:245], v[18:21]
	v_mfma_f32_16x16x32_bf16 v[18:21], v[202:205], v[246:249], v[74:77]
	v_mfma_f32_16x16x32_bf16 v[22:25], v[214:217], v[138:141], v[18:21]
	v_mfma_f32_16x16x32_bf16 v[18:21], v[218:221], v[210:213], v[70:73]
	v_mfma_f32_16x16x32_bf16 v[50:53], v[222:225], v[242:245], v[18:21]
	v_mfma_f32_16x16x32_bf16 v[18:21], v[218:221], v[246:249], v[66:69]
	v_mfma_f32_16x16x32_bf16 v[18:21], v[222:225], v[138:141], v[18:21]
	s_barrier
	ds_read_b128 v[156:159], v142 offset:49152
	ds_read_b128 v[160:163], v142 offset:50176
	ds_read_b128 v[164:167], v142 offset:51200
	ds_read_b128 v[202:205], v142 offset:52224
	ds_read_b128 v[214:217], v142 offset:53248
	ds_read_b128 v[218:221], v142 offset:54272
	ds_read_b128 v[222:225], v142 offset:55296
	ds_read_b128 v[226:229], v142 offset:56320
	s_barrier
	s_waitcnt lgkmcnt(0)
	v_mfma_f32_16x16x32_bf16 v[66:69], v[156:159], v[6:9], v[206:209]
	v_mfma_f32_16x16x32_bf16 v[110:113], v[160:163], v[10:13], v[66:69]
	v_mfma_f32_16x16x32_bf16 v[66:69], v[156:159], v[14:17], v[230:233]
	v_mfma_f32_16x16x32_bf16 v[78:81], v[160:163], v[198:201], v[66:69]
	v_mfma_f32_16x16x32_bf16 v[66:69], v[164:167], v[6:9], v[234:237]
	v_mfma_f32_16x16x32_bf16 v[46:49], v[214:217], v[6:9], v[46:49]
	v_mfma_f32_16x16x32_bf16 v[6:9], v[222:225], v[6:9], v[38:41]
	v_mfma_f32_16x16x32_bf16 v[106:109], v[202:205], v[10:13], v[66:69]
	v_mfma_f32_16x16x32_bf16 v[66:69], v[164:167], v[14:17], v[238:241]
	v_mfma_f32_16x16x32_bf16 v[42:45], v[214:217], v[14:17], v[42:45]
	v_mfma_f32_16x16x32_bf16 v[98:101], v[226:229], v[10:13], v[6:9]
	v_mfma_f32_16x16x32_bf16 v[6:9], v[222:225], v[14:17], v[34:37]
	v_mfma_f32_16x16x32_bf16 v[74:77], v[202:205], v[198:201], v[66:69]
	v_mfma_f32_16x16x32_bf16 v[102:105], v[218:221], v[10:13], v[46:49]
	v_mfma_f32_16x16x32_bf16 v[70:73], v[218:221], v[198:201], v[42:45]
	v_mfma_f32_16x16x32_bf16 v[66:69], v[226:229], v[198:201], v[6:9]
	v_mfma_f32_16x16x32_bf16 v[6:9], v[156:159], v[210:213], v[130:133]
	v_mfma_f32_16x16x32_bf16 v[46:49], v[160:163], v[242:245], v[6:9]
	v_mfma_f32_16x16x32_bf16 v[6:9], v[156:159], v[246:249], v[134:137]
	v_mfma_f32_16x16x32_bf16 v[14:17], v[160:163], v[138:141], v[6:9]
	v_mfma_f32_16x16x32_bf16 v[6:9], v[164:167], v[210:213], v[144:147]
	v_mfma_f32_16x16x32_bf16 v[42:45], v[202:205], v[242:245], v[6:9]
	v_mfma_f32_16x16x32_bf16 v[6:9], v[164:167], v[246:249], v[148:151]
	v_mfma_f32_16x16x32_bf16 v[10:13], v[202:205], v[138:141], v[6:9]
	v_mfma_f32_16x16x32_bf16 v[6:9], v[214:217], v[210:213], v[152:155]
	v_mfma_f32_16x16x32_bf16 v[38:41], v[218:221], v[242:245], v[6:9]
	v_mfma_f32_16x16x32_bf16 v[6:9], v[214:217], v[246:249], v[190:193]
	v_mfma_f32_16x16x32_bf16 v[34:37], v[222:225], v[210:213], v[194:197]
	v_mfma_f32_16x16x32_bf16 v[2:5], v[222:225], v[246:249], v[2:5]
	v_mfma_f32_16x16x32_bf16 v[6:9], v[218:221], v[138:141], v[6:9]
	v_mfma_f32_16x16x32_bf16 v[34:37], v[226:229], v[242:245], v[34:37]
	v_mfma_f32_16x16x32_bf16 v[2:5], v[226:229], v[138:141], v[2:5]
	s_cmpk_lt_u32 s12, 0x100
	s_barrier
	s_cbranch_scc0 .LBB0_206
	s_barrier
	s_branch .LBB0_206

;     __device__ __forceinline__ unsigned* BAR() const { return (unsigned*)(ws + OFF_BAR); }
; #define STAGE(bufoff, gbase, voff) do { _Pragma("unroll") for (int _i = 0; _i < 2; ++_i) \
;         __builtin_amdgcn_global_load_lds((const unsigned*)((const char*)(gbase) + voff[_i]), (LAS unsigned*)(lds + (bufoff) + ldsw + _i * 8192), 16, 0, 0); } while (0)
; #define LDA(dst, b, h) do { _Pragma("unroll") for (int m = 0; m < 4; ++m) _Pragma("unroll") for (int k = 0; k < 2; ++k) dst[m][k] = *(const LAS bf16x8*)(lds + SA(b, h) + aoff + m * 2048 + k * 1024); } while (0)
; #define LDB(dst, b, h) do { _Pragma("unroll") for (int n = 0; n < 2; ++n) _Pragma("unroll") for (int k = 0; k < 2; ++k) dst[n][k] = *(const LAS bf16x8*)(lds + SB(b, h) + boff + n * 2048 + k * 1024); } while (0)
; #define MMA(ai, bj, At, Bx) do { __builtin_amdgcn_s_setprio(1); _Pragma("unroll") for (int m = 0; m < 4; ++m) _Pragma("unroll") for (int n = 0; n < 2; ++n) _Pragma("unroll") for (int k = 0; k < 2; ++k) \
;       acc[ai][bj][m][n] = __builtin_amdgcn_mfma_f32_16x16x32_bf16(At[m][k], Bx[n][k], acc[ai][bj][m][n], 0, 0, 0); \
;     __builtin_amdgcn_s_setprio(0); } while (0)
; #define WAIT_L(n) asm volatile("s_waitcnt lgkmcnt(" #n ")" ::: "memory")
; #define BAR __builtin_amdgcn_s_barrier()
; #define SCHED __builtin_amdgcn_sched_barrier(0)
;     ...
;     for (int t = 0; t < nt - 2; t += 2) {
;         if (KSEG && t > 0 && (t % (KSEG ? KSEG : 1)) == 0) hook(t / (KSEG ? KSEG : 1), acc);
;         const char* a1 = pA(t + 1); const char* a2 = pA(t + 2); const char* a3 = pA(t + 3);
;         const char* b2 = pB(t + 2); const char* b3 = pB(t + 3);
;         LDB(B0, 0, 0); SCHED; LDA(At, 0, 0); STAGE(SA(1, 1), a1 + hstepA, voffA);
;         WAIT_L(8); BAR; WAIT_L(0); MMA(0, 0, At, B0); BAR; SCHED;
;         LDB(B1, 0, 1); STAGE(SB(0, 0), b2, voffB);
;         BAR; WAIT_L(0); MMA(0, 1, At, B1); BAR;
;         LDA(At, 0, 1); STAGE(SA(0, 0), a2, voffA);
.LBB0_574:
	s_add_i32 s10, s12, 4
	s_lshr_b32 s24, s10, 3
	s_and_b32 s17, s43, 0x300000
	s_and_b32 vcc_lo, s8, 0x300
	s_lshl_b64 s[14:15], s[24:25], 20
	s_add_u32 s10, s8, 0x100
	s_addc_u32 s11, s9, 0
	s_add_i32 s9, s12, 5
	s_lshr_b32 s12, s9, 3
	s_mov_b32 s13, s25
	s_addk_i32 s8, 0x180
	s_and_b32 s94, s10, 0x300
	s_lshl_b64 s[92:93], s[12:13], 20
	s_and_b32 vcc_hi, s8, 0x380
	s_mul_i32 s9, s24, 0x1200000
	s_mul_hi_u32 s8, s24, 0x1200000
	s_add_u32 s9, s6, s9
	s_addc_u32 s8, s7, s8
	s_mul_hi_u32 s13, s12, 0x1200000
	s_mul_i32 s12, s12, 0x1200000
	s_add_u32 s55, s6, s12
	s_addc_u32 s16, s7, s13
	s_add_i32 s45, 0, 0x10000
	v_add_u32_e32 v138, s45, v143
	ds_read_b128 v[130:133], v138
	ds_read_b128 v[134:137], v138 offset:1024
	ds_read_b128 v[144:147], v138 offset:2048
	ds_read_b128 v[148:151], v138 offset:3072
	s_add_u32 s12, s4, s17
	s_addc_u32 s13, s5, 0
	s_add_u32 s17, s4, s14
	s_addc_u32 s23, s5, s15
	s_add_u32 s24, s4, s92
	s_addc_u32 s92, s5, s93
	s_add_u32 s14, s9, s94
	s_addc_u32 s15, s8, 0
	s_add_u32 s12, s12, vcc_lo
	s_addc_u32 s13, s13, 0
	s_add_u32 s8, s24, vcc_hi
	s_addc_u32 s9, s92, 0
	s_add_u32 s12, s12, 0x20080
	s_addc_u32 s13, s13, 0
	s_add_i32 vcc_lo, s75, 0xc000
	v_lshl_add_u64 v[138:139], s[12:13], 0, v[0:1]
	s_mov_b32 m0, vcc_lo
	s_add_i32 s24, s75, 0xe000
	ds_read_b128 v[152:155], v142
	ds_read_b128 v[156:159], v142 offset:1024
	ds_read_b128 v[160:163], v142 offset:2048
	ds_read_b128 v[164:167], v142 offset:3072
	ds_read_b128 v[190:193], v142 offset:4096
	ds_read_b128 v[194:197], v142 offset:5120
	ds_read_b128 v[198:201], v142 offset:6144
	ds_read_b128 v[202:205], v142 offset:7168
	global_load_lds_dwordx4 v[138:139], off
	v_lshl_add_u64 v[138:139], s[12:13], 0, v[140:141]
	s_mov_b32 m0, s24
	s_add_u32 s12, s17, s94
	global_load_lds_dwordx4 v[138:139], off
	s_waitcnt lgkmcnt(8)
	s_barrier
	s_waitcnt lgkmcnt(0)
	s_addc_u32 s13, s23, 0
	s_waitcnt lgkmcnt(0)
	v_mfma_f32_16x16x32_bf16 v[126:129], v[152:155], v[130:133], v[126:129]
	v_mfma_f32_16x16x32_bf16 v[122:125], v[152:155], v[144:147], v[122:125]
	v_mfma_f32_16x16x32_bf16 v[118:121], v[160:163], v[130:133], v[118:121]
	v_mfma_f32_16x16x32_bf16 v[114:117], v[160:163], v[144:147], v[114:117]
	v_mfma_f32_16x16x32_bf16 v[110:113], v[190:193], v[130:133], v[110:113]
	v_mfma_f32_16x16x32_bf16 v[106:109], v[190:193], v[144:147], v[106:109]
	v_mfma_f32_16x16x32_bf16 v[102:105], v[198:201], v[130:133], v[102:105]
	v_mfma_f32_16x16x32_bf16 v[98:101], v[198:201], v[144:147], v[98:101]
	v_mfma_f32_16x16x32_bf16 v[126:129], v[156:159], v[134:137], v[126:129]
	v_mfma_f32_16x16x32_bf16 v[122:125], v[156:159], v[148:151], v[122:125]
	v_mfma_f32_16x16x32_bf16 v[118:121], v[164:167], v[134:137], v[118:121]
	v_mfma_f32_16x16x32_bf16 v[114:117], v[164:167], v[148:151], v[114:117]
	v_mfma_f32_16x16x32_bf16 v[110:113], v[194:197], v[134:137], v[110:113]
	v_mfma_f32_16x16x32_bf16 v[106:109], v[194:197], v[148:151], v[106:109]
	v_mfma_f32_16x16x32_bf16 v[102:105], v[202:205], v[134:137], v[102:105]
	v_mfma_f32_16x16x32_bf16 v[98:101], v[202:205], v[148:151], v[98:101]
	s_barrier
	s_add_i32 s17, 0, 0x14000
	v_add_u32_e32 v138, s17, v143
	s_add_i32 s23, s45, s1
	ds_read_b128 v[206:209], v138
	ds_read_b128 v[210:213], v138 offset:1024
	ds_read_b128 v[214:217], v138 offset:2048
	ds_read_b128 v[218:221], v138 offset:3072
	v_lshl_add_u64 v[138:139], s[14:15], 0, v[0:1]
	s_mov_b32 m0, s23
	s_nop 0
	global_load_lds_dwordx4 v[138:139], off
	v_lshl_add_u64 v[138:139], s[14:15], 0, v[140:141]
	s_add_i32 m0, s23, 0x2000
	s_nop 0
	global_load_lds_dwordx4 v[138:139], off
	s_barrier
	s_waitcnt lgkmcnt(0)
	v_mfma_f32_16x16x32_bf16 v[94:97], v[152:155], v[206:209], v[94:97]
	v_mfma_f32_16x16x32_bf16 v[90:93], v[152:155], v[214:217], v[90:93]
	v_mfma_f32_16x16x32_bf16 v[86:89], v[160:163], v[206:209], v[86:89]
	v_mfma_f32_16x16x32_bf16 v[82:85], v[160:163], v[214:217], v[82:85]
	v_mfma_f32_16x16x32_bf16 v[78:81], v[190:193], v[206:209], v[78:81]
	v_mfma_f32_16x16x32_bf16 v[74:77], v[190:193], v[214:217], v[74:77]
	v_mfma_f32_16x16x32_bf16 v[70:73], v[198:201], v[206:209], v[70:73]
	v_mfma_f32_16x16x32_bf16 v[66:69], v[198:201], v[214:217], v[66:69]
	v_mfma_f32_16x16x32_bf16 v[94:97], v[156:159], v[210:213], v[94:97]
	v_mfma_f32_16x16x32_bf16 v[90:93], v[156:159], v[218:221], v[90:93]
	v_mfma_f32_16x16x32_bf16 v[86:89], v[164:167], v[210:213], v[86:89]
	v_mfma_f32_16x16x32_bf16 v[82:85], v[164:167], v[218:221], v[82:85]
	v_mfma_f32_16x16x32_bf16 v[78:81], v[194:197], v[210:213], v[78:81]
	v_mfma_f32_16x16x32_bf16 v[74:77], v[194:197], v[218:221], v[74:77]
	v_mfma_f32_16x16x32_bf16 v[70:73], v[202:205], v[210:213], v[70:73]
	v_mfma_f32_16x16x32_bf16 v[66:69], v[202:205], v[218:221], v[66:69]
	s_mov_b32 m0, s75
	v_lshl_add_u64 v[138:139], s[12:13], 0, v[0:1]
	s_barrier
	ds_read_b128 v[152:155], v142 offset:16384
	ds_read_b128 v[156:159], v142 offset:17408
	ds_read_b128 v[160:163], v142 offset:18432
	ds_read_b128 v[164:167], v142 offset:19456
	ds_read_b128 v[190:193], v142 offset:20480
	ds_read_b128 v[194:197], v142 offset:21504
	ds_read_b128 v[198:201], v142 offset:22528
	ds_read_b128 v[202:205], v142 offset:23552
	global_load_lds_dwordx4 v[138:139], off
	v_lshl_add_u64 v[138:139], s[12:13], 0, v[140:141]
	s_mov_b32 m0, s76
	s_nop 0
	global_load_lds_dwordx4 v[138:139], off
	s_barrier
;     __device__ __forceinline__ unsigned* BAR() const { return (unsigned*)(ws + OFF_BAR); }
; #define STAGE(bufoff, gbase, voff) do { _Pragma("unroll") for (int _i = 0; _i < 2; ++_i) \
;         __builtin_amdgcn_global_load_lds((const unsigned*)((const char*)(gbase) + voff[_i]), (LAS unsigned*)(lds + (bufoff) + ldsw + _i * 8192), 16, 0, 0); } while (0)
; #define LDA(dst, b, h) do { _Pragma("unroll") for (int m = 0; m < 4; ++m) _Pragma("unroll") for (int k = 0; k < 2; ++k) dst[m][k] = *(const LAS bf16x8*)(lds + SA(b, h) + aoff + m * 2048 + k * 1024); } while (0)
; #define LDB(dst, b, h) do { _Pragma("unroll") for (int n = 0; n < 2; ++n) _Pragma("unroll") for (int k = 0; k < 2; ++k) dst[n][k] = *(const LAS bf16x8*)(lds + SB(b, h) + boff + n * 2048 + k * 1024); } while (0)
; #define MMA(ai, bj, At, Bx) do { __builtin_amdgcn_s_setprio(1); _Pragma("unroll") for (int m = 0; m < 4; ++m) _Pragma("unroll") for (int n = 0; n < 2; ++n) _Pragma("unroll") for (int k = 0; k < 2; ++k) \
;       acc[ai][bj][m][n] = __builtin_amdgcn_mfma_f32_16x16x32_bf16(At[m][k], Bx[n][k], acc[ai][bj][m][n], 0, 0, 0); \
;     __builtin_amdgcn_s_setprio(0); } while (0)
; #define WAIT_V(n) asm volatile("s_waitcnt vmcnt(" #n ")" ::: "memory")
; #define WAIT_L(n) asm volatile("s_waitcnt lgkmcnt(" #n ")" ::: "memory")
; #define BAR __builtin_amdgcn_s_barrier()
; #define SCHED __builtin_amdgcn_sched_barrier(0)
;     ...
;         BAR; WAIT_L(0); MMA(1, 0, At, B0); BAR; SCHED;
;         STAGE(SB(0, 1), b2 + hstepB, voffB);
;         WAIT_V(6); BAR; MMA(1, 1, At, B1); BAR;
;         LDB(B0, 1, 0); SCHED; LDA(At, 1, 0); STAGE(SA(0, 1), a2 + hstepA, voffA);
;         WAIT_L(8); BAR; WAIT_L(0); MMA(0, 0, At, B0); BAR; SCHED;
;         LDB(B1, 1, 1); STAGE(SB(1, 0), b3, voffB);
	s_waitcnt lgkmcnt(0)
	v_mfma_f32_16x16x32_bf16 v[62:65], v[152:155], v[130:133], v[62:65]
	v_mfma_f32_16x16x32_bf16 v[58:61], v[152:155], v[144:147], v[58:61]
	v_mfma_f32_16x16x32_bf16 v[54:57], v[160:163], v[130:133], v[54:57]
	v_mfma_f32_16x16x32_bf16 v[50:53], v[160:163], v[144:147], v[50:53]
	v_mfma_f32_16x16x32_bf16 v[46:49], v[190:193], v[130:133], v[46:49]
	v_mfma_f32_16x16x32_bf16 v[42:45], v[190:193], v[144:147], v[42:45]
	v_mfma_f32_16x16x32_bf16 v[38:41], v[198:201], v[130:133], v[38:41]
	v_mfma_f32_16x16x32_bf16 v[34:37], v[198:201], v[144:147], v[34:37]
	v_mfma_f32_16x16x32_bf16 v[62:65], v[156:159], v[134:137], v[62:65]
	v_mfma_f32_16x16x32_bf16 v[58:61], v[156:159], v[148:151], v[58:61]
	v_mfma_f32_16x16x32_bf16 v[54:57], v[164:167], v[134:137], v[54:57]
	v_mfma_f32_16x16x32_bf16 v[50:53], v[164:167], v[148:151], v[50:53]
	v_mfma_f32_16x16x32_bf16 v[46:49], v[194:197], v[134:137], v[46:49]
	v_mfma_f32_16x16x32_bf16 v[42:45], v[194:197], v[148:151], v[42:45]
	v_mfma_f32_16x16x32_bf16 v[38:41], v[202:205], v[134:137], v[38:41]
	v_mfma_f32_16x16x32_bf16 v[34:37], v[202:205], v[148:151], v[34:37]
	s_barrier
	s_add_u32 s14, s14, 0x20000
	s_addc_u32 s15, s15, 0
	s_add_i32 s17, s17, s1
	v_lshl_add_u64 v[130:131], s[14:15], 0, v[0:1]
	s_mov_b32 m0, s17
	s_nop 0
	global_load_lds_dwordx4 v[130:131], off
	v_lshl_add_u64 v[130:131], s[14:15], 0, v[140:141]
	s_add_i32 m0, s17, 0x2000
	s_nop 0
	global_load_lds_dwordx4 v[130:131], off
	s_waitcnt vmcnt(6)
	s_barrier
	v_mfma_f32_16x16x32_bf16 v[30:33], v[152:155], v[206:209], v[30:33]
	v_mfma_f32_16x16x32_bf16 v[26:29], v[152:155], v[214:217], v[26:29]
	v_mfma_f32_16x16x32_bf16 v[22:25], v[160:163], v[206:209], v[22:25]
	v_mfma_f32_16x16x32_bf16 v[18:21], v[160:163], v[214:217], v[18:21]
	v_mfma_f32_16x16x32_bf16 v[14:17], v[190:193], v[206:209], v[14:17]
	v_mfma_f32_16x16x32_bf16 v[10:13], v[190:193], v[214:217], v[10:13]
	v_mfma_f32_16x16x32_bf16 v[6:9], v[198:201], v[206:209], v[6:9]
	v_mfma_f32_16x16x32_bf16 v[2:5], v[198:201], v[214:217], v[2:5]
	v_mfma_f32_16x16x32_bf16 v[30:33], v[156:159], v[210:213], v[30:33]
	v_mfma_f32_16x16x32_bf16 v[26:29], v[156:159], v[218:221], v[26:29]
	v_mfma_f32_16x16x32_bf16 v[22:25], v[164:167], v[210:213], v[22:25]
	v_mfma_f32_16x16x32_bf16 v[18:21], v[164:167], v[218:221], v[18:21]
	v_mfma_f32_16x16x32_bf16 v[14:17], v[194:197], v[210:213], v[14:17]
	v_mfma_f32_16x16x32_bf16 v[10:13], v[194:197], v[218:221], v[10:13]
	v_mfma_f32_16x16x32_bf16 v[6:9], v[202:205], v[210:213], v[6:9]
	v_mfma_f32_16x16x32_bf16 v[2:5], v[202:205], v[218:221], v[2:5]
	s_add_i32 s14, 0, 0x18000
	v_add_u32_e32 v138, s14, v143
	s_barrier
	ds_read_b128 v[130:133], v138
	ds_read_b128 v[134:137], v138 offset:1024
	ds_read_b128 v[144:147], v138 offset:2048
	ds_read_b128 v[148:151], v138 offset:3072
	s_add_u32 s12, s12, 0x20000
	s_addc_u32 s13, s13, 0
	s_mov_b32 m0, s77
	v_lshl_add_u64 v[138:139], s[12:13], 0, v[0:1]
	ds_read_b128 v[152:155], v142 offset:32768
	ds_read_b128 v[156:159], v142 offset:33792
	ds_read_b128 v[160:163], v142 offset:34816
	ds_read_b128 v[164:167], v142 offset:35840
	ds_read_b128 v[190:193], v142 offset:36864
	ds_read_b128 v[194:197], v142 offset:37888
	ds_read_b128 v[198:201], v142 offset:38912
	ds_read_b128 v[202:205], v142 offset:39936
	global_load_lds_dwordx4 v[138:139], off
	v_lshl_add_u64 v[138:139], s[12:13], 0, v[140:141]
	s_mov_b32 m0, s88
	s_nop 0
	global_load_lds_dwordx4 v[138:139], off
	s_waitcnt lgkmcnt(8)
	s_barrier
	s_waitcnt lgkmcnt(0)
	v_mfma_f32_16x16x32_bf16 v[126:129], v[152:155], v[130:133], v[126:129]
	v_mfma_f32_16x16x32_bf16 v[122:125], v[152:155], v[144:147], v[122:125]
	v_mfma_f32_16x16x32_bf16 v[118:121], v[160:163], v[130:133], v[118:121]
	v_mfma_f32_16x16x32_bf16 v[114:117], v[160:163], v[144:147], v[114:117]
	v_mfma_f32_16x16x32_bf16 v[110:113], v[190:193], v[130:133], v[110:113]
	v_mfma_f32_16x16x32_bf16 v[106:109], v[190:193], v[144:147], v[106:109]
	v_mfma_f32_16x16x32_bf16 v[102:105], v[198:201], v[130:133], v[102:105]
	v_mfma_f32_16x16x32_bf16 v[98:101], v[198:201], v[144:147], v[98:101]
	v_mfma_f32_16x16x32_bf16 v[126:129], v[156:159], v[134:137], v[126:129]
	v_mfma_f32_16x16x32_bf16 v[122:125], v[156:159], v[148:151], v[122:125]
	v_mfma_f32_16x16x32_bf16 v[118:121], v[164:167], v[134:137], v[118:121]
	v_mfma_f32_16x16x32_bf16 v[114:117], v[164:167], v[148:151], v[114:117]
	v_mfma_f32_16x16x32_bf16 v[110:113], v[194:197], v[134:137], v[110:113]
	v_mfma_f32_16x16x32_bf16 v[106:109], v[194:197], v[148:151], v[106:109]
	v_mfma_f32_16x16x32_bf16 v[102:105], v[202:205], v[134:137], v[102:105]
	v_mfma_f32_16x16x32_bf16 v[98:101], v[202:205], v[148:151], v[98:101]
	s_barrier
	s_add_i32 s15, 0, 0x1c000
	s_add_u32 s12, s55, vcc_hi
	v_add_u32_e32 v138, s15, v143
	s_addc_u32 s13, s16, 0
	s_add_i32 s14, s14, s1
	ds_read_b128 v[206:209], v138
	ds_read_b128 v[210:213], v138 offset:1024
	ds_read_b128 v[214:217], v138 offset:2048
	ds_read_b128 v[218:221], v138 offset:3072
	v_lshl_add_u64 v[138:139], s[12:13], 0, v[0:1]
	s_mov_b32 m0, s14
	s_nop 0
	global_load_lds_dwordx4 v[138:139], off
	v_lshl_add_u64 v[138:139], s[12:13], 0, v[140:141]
	s_add_i32 m0, s14, 0x2000
	s_nop 0
	global_load_lds_dwordx4 v[138:139], off
	s_barrier
;     __device__ __forceinline__ unsigned* BAR() const { return (unsigned*)(ws + OFF_BAR); }
; #define STAGE(bufoff, gbase, voff) do { _Pragma("unroll") for (int _i = 0; _i < 2; ++_i) \
;         __builtin_amdgcn_global_load_lds((const unsigned*)((const char*)(gbase) + voff[_i]), (LAS unsigned*)(lds + (bufoff) + ldsw + _i * 8192), 16, 0, 0); } while (0)
; #define LDA(dst, b, h) do { _Pragma("unroll") for (int m = 0; m < 4; ++m) _Pragma("unroll") for (int k = 0; k < 2; ++k) dst[m][k] = *(const LAS bf16x8*)(lds + SA(b, h) + aoff + m * 2048 + k * 1024); } while (0)
; #define LDB(dst, b, h) do { _Pragma("unroll") for (int n = 0; n < 2; ++n) _Pragma("unroll") for (int k = 0; k < 2; ++k) dst[n][k] = *(const LAS bf16x8*)(lds + SB(b, h) + boff + n * 2048 + k * 1024); } while (0)
; #define MMA(ai, bj, At, Bx) do { __builtin_amdgcn_s_setprio(1); _Pragma("unroll") for (int m = 0; m < 4; ++m) _Pragma("unroll") for (int n = 0; n < 2; ++n) _Pragma("unroll") for (int k = 0; k < 2; ++k) \
;       acc[ai][bj][m][n] = __builtin_amdgcn_mfma_f32_16x16x32_bf16(At[m][k], Bx[n][k], acc[ai][bj][m][n], 0, 0, 0); \
;     __builtin_amdgcn_s_setprio(0); } while (0)
; #define WAIT_V(n) asm volatile("s_waitcnt vmcnt(" #n ")" ::: "memory")
; #define WAIT_L(n) asm volatile("s_waitcnt lgkmcnt(" #n ")" ::: "memory")
; #define BAR __builtin_amdgcn_s_barrier()
; #define SCHED __builtin_amdgcn_sched_barrier(0)
;     ...
;         LDB(B1, 1, 1); STAGE(SB(1, 0), b3, voffB);
;         BAR; WAIT_L(0); MMA(0, 1, At, B1); BAR;
;         LDA(At, 1, 1); STAGE(SA(1, 0), a3, voffA);
;         BAR; WAIT_L(0); MMA(1, 0, At, B0); BAR; SCHED;
;         STAGE(SB(1, 1), b3 + hstepB, voffB);
;         WAIT_V(6); BAR; MMA(1, 1, At, B1); BAR;
;     }
	s_waitcnt lgkmcnt(0)
	v_mfma_f32_16x16x32_bf16 v[94:97], v[152:155], v[206:209], v[94:97]
	v_mfma_f32_16x16x32_bf16 v[90:93], v[152:155], v[214:217], v[90:93]
	v_mfma_f32_16x16x32_bf16 v[86:89], v[160:163], v[206:209], v[86:89]
	v_mfma_f32_16x16x32_bf16 v[82:85], v[160:163], v[214:217], v[82:85]
	v_mfma_f32_16x16x32_bf16 v[78:81], v[190:193], v[206:209], v[78:81]
	v_mfma_f32_16x16x32_bf16 v[74:77], v[190:193], v[214:217], v[74:77]
	v_mfma_f32_16x16x32_bf16 v[70:73], v[198:201], v[206:209], v[70:73]
	v_mfma_f32_16x16x32_bf16 v[66:69], v[198:201], v[214:217], v[66:69]
	v_mfma_f32_16x16x32_bf16 v[94:97], v[156:159], v[210:213], v[94:97]
	v_mfma_f32_16x16x32_bf16 v[90:93], v[156:159], v[218:221], v[90:93]
	v_mfma_f32_16x16x32_bf16 v[86:89], v[164:167], v[210:213], v[86:89]
	v_mfma_f32_16x16x32_bf16 v[82:85], v[164:167], v[218:221], v[82:85]
	v_mfma_f32_16x16x32_bf16 v[78:81], v[194:197], v[210:213], v[78:81]
	v_mfma_f32_16x16x32_bf16 v[74:77], v[194:197], v[218:221], v[74:77]
	v_mfma_f32_16x16x32_bf16 v[70:73], v[202:205], v[210:213], v[70:73]
	v_mfma_f32_16x16x32_bf16 v[66:69], v[202:205], v[218:221], v[66:69]
	s_mov_b32 m0, s31
	v_lshl_add_u64 v[138:139], s[8:9], 0, v[0:1]
	s_barrier
	ds_read_b128 v[152:155], v142 offset:49152
	ds_read_b128 v[156:159], v142 offset:50176
	ds_read_b128 v[160:163], v142 offset:51200
	ds_read_b128 v[164:167], v142 offset:52224
	ds_read_b128 v[190:193], v142 offset:53248
	ds_read_b128 v[194:197], v142 offset:54272
	ds_read_b128 v[198:201], v142 offset:55296
	ds_read_b128 v[202:205], v142 offset:56320
	global_load_lds_dwordx4 v[138:139], off
	v_lshl_add_u64 v[138:139], s[8:9], 0, v[140:141]
	s_mov_b32 m0, s27
	s_nop 0
	global_load_lds_dwordx4 v[138:139], off
	s_barrier
	s_waitcnt lgkmcnt(0)
	v_mfma_f32_16x16x32_bf16 v[62:65], v[152:155], v[130:133], v[62:65]
	v_mfma_f32_16x16x32_bf16 v[58:61], v[152:155], v[144:147], v[58:61]
	v_mfma_f32_16x16x32_bf16 v[54:57], v[160:163], v[130:133], v[54:57]
	v_mfma_f32_16x16x32_bf16 v[50:53], v[160:163], v[144:147], v[50:53]
	v_mfma_f32_16x16x32_bf16 v[46:49], v[190:193], v[130:133], v[46:49]
	v_mfma_f32_16x16x32_bf16 v[42:45], v[190:193], v[144:147], v[42:45]
	v_mfma_f32_16x16x32_bf16 v[38:41], v[198:201], v[130:133], v[38:41]
	v_mfma_f32_16x16x32_bf16 v[34:37], v[198:201], v[144:147], v[34:37]
	v_mfma_f32_16x16x32_bf16 v[62:65], v[156:159], v[134:137], v[62:65]
	v_mfma_f32_16x16x32_bf16 v[58:61], v[156:159], v[148:151], v[58:61]
	v_mfma_f32_16x16x32_bf16 v[54:57], v[164:167], v[134:137], v[54:57]
	v_mfma_f32_16x16x32_bf16 v[50:53], v[164:167], v[148:151], v[50:53]
	v_mfma_f32_16x16x32_bf16 v[46:49], v[194:197], v[134:137], v[46:49]
	v_mfma_f32_16x16x32_bf16 v[42:45], v[194:197], v[148:151], v[42:45]
	v_mfma_f32_16x16x32_bf16 v[38:41], v[202:205], v[134:137], v[38:41]
	v_mfma_f32_16x16x32_bf16 v[34:37], v[202:205], v[148:151], v[34:37]
	s_barrier
	s_add_u32 s8, s12, 0x20000
	s_addc_u32 s9, s13, 0
	s_add_i32 s12, s15, s1
	v_lshl_add_u64 v[130:131], s[8:9], 0, v[0:1]
	s_mov_b32 m0, s12
	s_nop 0
	global_load_lds_dwordx4 v[130:131], off
	v_lshl_add_u64 v[130:131], s[8:9], 0, v[140:141]
	s_add_i32 m0, s12, 0x2000
	s_nop 0
	global_load_lds_dwordx4 v[130:131], off
	s_waitcnt vmcnt(6)
	s_barrier
	v_mfma_f32_16x16x32_bf16 v[30:33], v[152:155], v[206:209], v[30:33]
	v_mfma_f32_16x16x32_bf16 v[26:29], v[152:155], v[214:217], v[26:29]
	v_mfma_f32_16x16x32_bf16 v[22:25], v[160:163], v[206:209], v[22:25]
	v_mfma_f32_16x16x32_bf16 v[18:21], v[160:163], v[214:217], v[18:21]
	v_mfma_f32_16x16x32_bf16 v[14:17], v[190:193], v[206:209], v[14:17]
	v_mfma_f32_16x16x32_bf16 v[10:13], v[190:193], v[214:217], v[10:13]
	v_mfma_f32_16x16x32_bf16 v[6:9], v[198:201], v[206:209], v[6:9]
	v_mfma_f32_16x16x32_bf16 v[2:5], v[198:201], v[214:217], v[2:5]
	v_mfma_f32_16x16x32_bf16 v[30:33], v[156:159], v[210:213], v[30:33]
	v_mfma_f32_16x16x32_bf16 v[26:29], v[156:159], v[218:221], v[26:29]
	v_mfma_f32_16x16x32_bf16 v[22:25], v[164:167], v[210:213], v[22:25]
	v_mfma_f32_16x16x32_bf16 v[18:21], v[164:167], v[218:221], v[18:21]
	v_mfma_f32_16x16x32_bf16 v[14:17], v[194:197], v[210:213], v[14:17]
	v_mfma_f32_16x16x32_bf16 v[10:13], v[194:197], v[218:221], v[10:13]
	v_mfma_f32_16x16x32_bf16 v[6:9], v[202:205], v[210:213], v[6:9]
	v_mfma_f32_16x16x32_bf16 v[2:5], v[202:205], v[218:221], v[2:5]
	s_add_i32 s43, s43, 0x40000
	s_cmp_gt_u32 s54, 19
	s_barrier
	s_cbranch_scc1 .LBB0_576
	s_mov_b32 s12, s54
	s_mov_b64 s[8:9], s[10:11]
	s_branch .LBB0_572
;     __device__ __forceinline__ unsigned* BAR() const { return (unsigned*)(ws + OFF_BAR); }
; #define STAGE(bufoff, gbase, voff) do { _Pragma("unroll") for (int _i = 0; _i < 2; ++_i) \
;         __builtin_amdgcn_global_load_lds((const unsigned*)((const char*)(gbase) + voff[_i]), (LAS unsigned*)(lds + (bufoff) + ldsw + _i * 8192), 16, 0, 0); } while (0)
; #define LDA(dst, b, h) do { _Pragma("unroll") for (int m = 0; m < 4; ++m) _Pragma("unroll") for (int k = 0; k < 2; ++k) dst[m][k] = *(const LAS bf16x8*)(lds + SA(b, h) + aoff + m * 2048 + k * 1024); } while (0)
; #define LDB(dst, b, h) do { _Pragma("unroll") for (int n = 0; n < 2; ++n) _Pragma("unroll") for (int k = 0; k < 2; ++k) dst[n][k] = *(const LAS bf16x8*)(lds + SB(b, h) + boff + n * 2048 + k * 1024); } while (0)
; #define MMA(ai, bj, At, Bx) do { __builtin_amdgcn_s_setprio(1); _Pragma("unroll") for (int m = 0; m < 4; ++m) _Pragma("unroll") for (int n = 0; n < 2; ++n) _Pragma("unroll") for (int k = 0; k < 2; ++k) \
;       acc[ai][bj][m][n] = __builtin_amdgcn_mfma_f32_16x16x32_bf16(At[m][k], Bx[n][k], acc[ai][bj][m][n], 0, 0, 0); \
;     __builtin_amdgcn_s_setprio(0); } while (0)
; #define WAIT_V(n) asm volatile("s_waitcnt vmcnt(" #n ")" ::: "memory")
; #define WAIT_L(n) asm volatile("s_waitcnt lgkmcnt(" #n ")" ::: "memory")
; #define BAR __builtin_amdgcn_s_barrier()
;     ...
;     { LDB(B0, 0, 0); LDA(At, 0, 0); STAGE(SA(1, 1), pA(nt - 1) + hstepA, voffA);
;       BAR; WAIT_L(0); MMA(0, 0, At, B0); BAR;
;       LDB(B1, 0, 1); BAR; WAIT_L(0); MMA(0, 1, At, B1); BAR;
;       LDA(At, 0, 1); WAIT_V(4); BAR; WAIT_L(0); MMA(1, 0, At, B0); MMA(1, 1, At, B1); BAR; }
;     { LDB(B0, 1, 0); LDA(At, 1, 0); WAIT_V(2); BAR; WAIT_L(0); MMA(0, 0, At, B0); BAR;
;       LDB(B1, 1, 1); WAIT_V(0); BAR; WAIT_L(0); MMA(0, 1, At, B1); BAR;
.LBB0_576:
	v_add_u32_e32 v143, 0, v143
	s_add_u32 s4, s4, 0x220380
	v_add_u32_e32 v138, 0x10000, v143
	s_addc_u32 s5, s5, 0
	s_mov_b32 m0, vcc_lo
	ds_read_b128 v[130:133], v138
	ds_read_b128 v[134:137], v138 offset:1024
	ds_read_b128 v[144:147], v138 offset:2048
	ds_read_b128 v[148:151], v138 offset:3072
	ds_read_b128 v[152:155], v142
	ds_read_b128 v[156:159], v142 offset:1024
	ds_read_b128 v[160:163], v142 offset:2048
	ds_read_b128 v[164:167], v142 offset:3072
	ds_read_b128 v[190:193], v142 offset:4096
	ds_read_b128 v[194:197], v142 offset:5120
	ds_read_b128 v[198:201], v142 offset:6144
	ds_read_b128 v[202:205], v142 offset:7168
	v_lshl_add_u64 v[138:139], s[4:5], 0, v[0:1]
	global_load_lds_dwordx4 v[138:139], off
	v_lshl_add_u64 v[138:139], s[4:5], 0, v[140:141]
	s_mov_b32 m0, s24
	s_nop 0
	global_load_lds_dwordx4 v[138:139], off
	s_barrier
	s_waitcnt lgkmcnt(0)
	v_mfma_f32_16x16x32_bf16 v[126:129], v[152:155], v[130:133], v[126:129]
	v_mfma_f32_16x16x32_bf16 v[122:125], v[152:155], v[144:147], v[122:125]
	v_mfma_f32_16x16x32_bf16 v[118:121], v[160:163], v[130:133], v[118:121]
	v_mfma_f32_16x16x32_bf16 v[114:117], v[160:163], v[144:147], v[114:117]
	v_mfma_f32_16x16x32_bf16 v[98:101], v[198:201], v[144:147], v[98:101]
	v_mfma_f32_16x16x32_bf16 v[126:129], v[156:159], v[134:137], v[126:129]
	v_mfma_f32_16x16x32_bf16 v[122:125], v[156:159], v[148:151], v[122:125]
	v_mfma_f32_16x16x32_bf16 v[118:121], v[164:167], v[134:137], v[118:121]
	v_mfma_f32_16x16x32_bf16 v[114:117], v[164:167], v[148:151], v[114:117]
	v_mfma_f32_16x16x32_bf16 v[110:113], v[190:193], v[130:133], v[110:113]
	v_mfma_f32_16x16x32_bf16 v[106:109], v[190:193], v[144:147], v[106:109]
	v_mfma_f32_16x16x32_bf16 v[102:105], v[198:201], v[130:133], v[102:105]
	v_mfma_f32_16x16x32_bf16 v[98:101], v[202:205], v[148:151], v[98:101]
	v_mfma_f32_16x16x32_bf16 v[138:141], v[194:197], v[134:137], v[110:113]
	v_mfma_f32_16x16x32_bf16 v[206:209], v[194:197], v[148:151], v[106:109]
	v_mfma_f32_16x16x32_bf16 v[210:213], v[202:205], v[134:137], v[102:105]
	v_add_u32_e32 v0, 0x14000, v143
	s_barrier
	s_nop 0
	ds_read_b128 v[102:105], v0
	ds_read_b128 v[106:109], v0 offset:1024
	ds_read_b128 v[110:113], v0 offset:2048
	ds_read_b128 v[214:217], v0 offset:3072
	s_barrier
	s_waitcnt lgkmcnt(0)
	v_mfma_f32_16x16x32_bf16 v[94:97], v[152:155], v[102:105], v[94:97]
	v_mfma_f32_16x16x32_bf16 v[90:93], v[152:155], v[110:113], v[90:93]
	v_mfma_f32_16x16x32_bf16 v[86:89], v[160:163], v[102:105], v[86:89]
	v_mfma_f32_16x16x32_bf16 v[82:85], v[160:163], v[110:113], v[82:85]
	v_mfma_f32_16x16x32_bf16 v[66:69], v[198:201], v[110:113], v[66:69]
	v_mfma_f32_16x16x32_bf16 v[94:97], v[156:159], v[106:109], v[94:97]
	v_mfma_f32_16x16x32_bf16 v[90:93], v[156:159], v[214:217], v[90:93]
	v_mfma_f32_16x16x32_bf16 v[86:89], v[164:167], v[106:109], v[86:89]
	v_mfma_f32_16x16x32_bf16 v[82:85], v[164:167], v[214:217], v[82:85]
	v_mfma_f32_16x16x32_bf16 v[78:81], v[190:193], v[102:105], v[78:81]
	v_mfma_f32_16x16x32_bf16 v[74:77], v[190:193], v[110:113], v[74:77]
	v_mfma_f32_16x16x32_bf16 v[70:73], v[198:201], v[102:105], v[70:73]
	v_mfma_f32_16x16x32_bf16 v[66:69], v[202:205], v[214:217], v[66:69]
	v_mfma_f32_16x16x32_bf16 v[152:155], v[194:197], v[106:109], v[78:81]
	v_mfma_f32_16x16x32_bf16 v[156:159], v[194:197], v[214:217], v[74:77]
	v_mfma_f32_16x16x32_bf16 v[160:163], v[202:205], v[106:109], v[70:73]
	s_barrier
	s_nop 1
	ds_read_b128 v[70:73], v142 offset:16384
	ds_read_b128 v[74:77], v142 offset:17408
	ds_read_b128 v[78:81], v142 offset:18432
	ds_read_b128 v[164:167], v142 offset:19456
	ds_read_b128 v[190:193], v142 offset:20480
	ds_read_b128 v[194:197], v142 offset:21504
	ds_read_b128 v[198:201], v142 offset:22528
	ds_read_b128 v[202:205], v142 offset:23552
	s_waitcnt vmcnt(4)
	s_barrier
	s_waitcnt lgkmcnt(0)
	v_mfma_f32_16x16x32_bf16 v[62:65], v[70:73], v[130:133], v[62:65]
	v_mfma_f32_16x16x32_bf16 v[58:61], v[70:73], v[144:147], v[58:61]
	v_mfma_f32_16x16x32_bf16 v[54:57], v[78:81], v[130:133], v[54:57]
	v_mfma_f32_16x16x32_bf16 v[50:53], v[78:81], v[144:147], v[50:53]
	v_mfma_f32_16x16x32_bf16 v[34:37], v[198:201], v[144:147], v[34:37]
	v_mfma_f32_16x16x32_bf16 v[62:65], v[74:77], v[134:137], v[62:65]
	v_mfma_f32_16x16x32_bf16 v[58:61], v[74:77], v[148:151], v[58:61]
	v_mfma_f32_16x16x32_bf16 v[54:57], v[164:167], v[134:137], v[54:57]
	v_mfma_f32_16x16x32_bf16 v[50:53], v[164:167], v[148:151], v[50:53]
	v_mfma_f32_16x16x32_bf16 v[46:49], v[190:193], v[130:133], v[46:49]
	v_mfma_f32_16x16x32_bf16 v[42:45], v[190:193], v[144:147], v[42:45]
	v_mfma_f32_16x16x32_bf16 v[38:41], v[198:201], v[130:133], v[38:41]
	v_mfma_f32_16x16x32_bf16 v[34:37], v[202:205], v[148:151], v[34:37]
	v_mfma_f32_16x16x32_bf16 v[218:221], v[194:197], v[134:137], v[46:49]
	v_mfma_f32_16x16x32_bf16 v[222:225], v[194:197], v[148:151], v[42:45]
	v_mfma_f32_16x16x32_bf16 v[130:133], v[202:205], v[134:137], v[38:41]
	v_mfma_f32_16x16x32_bf16 v[30:33], v[70:73], v[102:105], v[30:33]
	v_mfma_f32_16x16x32_bf16 v[26:29], v[70:73], v[110:113], v[26:29]
	v_mfma_f32_16x16x32_bf16 v[22:25], v[78:81], v[102:105], v[22:25]
	v_mfma_f32_16x16x32_bf16 v[18:21], v[78:81], v[110:113], v[18:21]
	v_mfma_f32_16x16x32_bf16 v[2:5], v[198:201], v[110:113], v[2:5]
	v_mfma_f32_16x16x32_bf16 v[30:33], v[74:77], v[106:109], v[30:33]
	v_mfma_f32_16x16x32_bf16 v[26:29], v[74:77], v[214:217], v[26:29]
	v_mfma_f32_16x16x32_bf16 v[22:25], v[164:167], v[106:109], v[22:25]
	v_mfma_f32_16x16x32_bf16 v[18:21], v[164:167], v[214:217], v[18:21]
	v_mfma_f32_16x16x32_bf16 v[14:17], v[190:193], v[102:105], v[14:17]
	v_mfma_f32_16x16x32_bf16 v[10:13], v[190:193], v[110:113], v[10:13]
	v_mfma_f32_16x16x32_bf16 v[6:9], v[198:201], v[102:105], v[6:9]
	v_mfma_f32_16x16x32_bf16 v[2:5], v[202:205], v[214:217], v[2:5]
	v_mfma_f32_16x16x32_bf16 v[134:137], v[194:197], v[106:109], v[14:17]
	v_mfma_f32_16x16x32_bf16 v[144:147], v[194:197], v[214:217], v[10:13]
	v_mfma_f32_16x16x32_bf16 v[148:151], v[202:205], v[106:109], v[6:9]
	v_add_u32_e32 v0, 0x18000, v143
	s_barrier
;     __device__ __forceinline__ unsigned* BAR() const { return (unsigned*)(ws + OFF_BAR); }
; #define LDA(dst, b, h) do { _Pragma("unroll") for (int m = 0; m < 4; ++m) _Pragma("unroll") for (int k = 0; k < 2; ++k) dst[m][k] = *(const LAS bf16x8*)(lds + SA(b, h) + aoff + m * 2048 + k * 1024); } while (0)
; #define LDB(dst, b, h) do { _Pragma("unroll") for (int n = 0; n < 2; ++n) _Pragma("unroll") for (int k = 0; k < 2; ++k) dst[n][k] = *(const LAS bf16x8*)(lds + SB(b, h) + boff + n * 2048 + k * 1024); } while (0)
; #define MMA(ai, bj, At, Bx) do { __builtin_amdgcn_s_setprio(1); _Pragma("unroll") for (int m = 0; m < 4; ++m) _Pragma("unroll") for (int n = 0; n < 2; ++n) _Pragma("unroll") for (int k = 0; k < 2; ++k) \
;       acc[ai][bj][m][n] = __builtin_amdgcn_mfma_f32_16x16x32_bf16(At[m][k], Bx[n][k], acc[ai][bj][m][n], 0, 0, 0); \
;     __builtin_amdgcn_s_setprio(0); } while (0)
; #define WAIT_V(n) asm volatile("s_waitcnt vmcnt(" #n ")" ::: "memory")
; #define WAIT_L(n) asm volatile("s_waitcnt lgkmcnt(" #n ")" ::: "memory")
; #define BAR __builtin_amdgcn_s_barrier()
;     ...
;       LDA(At, 0, 1); WAIT_V(4); BAR; WAIT_L(0); MMA(1, 0, At, B0); MMA(1, 1, At, B1); BAR; }
;     { LDB(B0, 1, 0); LDA(At, 1, 0); WAIT_V(2); BAR; WAIT_L(0); MMA(0, 0, At, B0); BAR;
;       LDB(B1, 1, 1); WAIT_V(0); BAR; WAIT_L(0); MMA(0, 1, At, B1); BAR;
;       LDA(At, 1, 1); BAR; WAIT_L(0); MMA(1, 0, At, B0); MMA(1, 1, At, B1); BAR; }
;     if (wr == 0) BAR;
	s_nop 0
	ds_read_b128 v[6:9], v0
	ds_read_b128 v[10:13], v0 offset:1024
	ds_read_b128 v[14:17], v0 offset:2048
	ds_read_b128 v[164:167], v0 offset:3072
	ds_read_b128 v[38:41], v142 offset:32768
	ds_read_b128 v[42:45], v142 offset:33792
	ds_read_b128 v[46:49], v142 offset:34816
	ds_read_b128 v[70:73], v142 offset:35840
	ds_read_b128 v[190:193], v142 offset:36864
	ds_read_b128 v[194:197], v142 offset:37888
	ds_read_b128 v[198:201], v142 offset:38912
	ds_read_b128 v[202:205], v142 offset:39936
	s_waitcnt vmcnt(2)
	s_barrier
	s_waitcnt lgkmcnt(0)
	v_mfma_f32_16x16x32_bf16 v[74:77], v[38:41], v[6:9], v[126:129]
	v_mfma_f32_16x16x32_bf16 v[126:129], v[42:45], v[10:13], v[74:77]
	v_mfma_f32_16x16x32_bf16 v[74:77], v[38:41], v[14:17], v[122:125]
	v_mfma_f32_16x16x32_bf16 v[110:113], v[42:45], v[164:167], v[74:77]
	v_mfma_f32_16x16x32_bf16 v[74:77], v[46:49], v[6:9], v[118:121]
	v_mfma_f32_16x16x32_bf16 v[122:125], v[70:73], v[10:13], v[74:77]
	v_mfma_f32_16x16x32_bf16 v[74:77], v[46:49], v[14:17], v[114:117]
	v_mfma_f32_16x16x32_bf16 v[106:109], v[70:73], v[164:167], v[74:77]
	v_mfma_f32_16x16x32_bf16 v[74:77], v[190:193], v[6:9], v[138:141]
	v_mfma_f32_16x16x32_bf16 v[118:121], v[194:197], v[10:13], v[74:77]
	v_mfma_f32_16x16x32_bf16 v[74:77], v[190:193], v[14:17], v[206:209]
	v_mfma_f32_16x16x32_bf16 v[102:105], v[194:197], v[164:167], v[74:77]
	v_mfma_f32_16x16x32_bf16 v[74:77], v[198:201], v[6:9], v[210:213]
	v_mfma_f32_16x16x32_bf16 v[114:117], v[202:205], v[10:13], v[74:77]
	v_mfma_f32_16x16x32_bf16 v[74:77], v[198:201], v[14:17], v[98:101]
	v_mfma_f32_16x16x32_bf16 v[98:101], v[202:205], v[164:167], v[74:77]
	v_add_u32_e32 v0, 0x1c000, v143
	s_barrier
	ds_read_b128 v[138:141], v0
	ds_read_b128 v[206:209], v0 offset:1024
	ds_read_b128 v[210:213], v0 offset:2048
	ds_read_b128 v[214:217], v0 offset:3072
	s_waitcnt vmcnt(0)
	s_barrier
	s_waitcnt lgkmcnt(0)
	v_mfma_f32_16x16x32_bf16 v[74:77], v[38:41], v[138:141], v[94:97]
	v_mfma_f32_16x16x32_bf16 v[38:41], v[38:41], v[210:213], v[90:93]
	v_mfma_f32_16x16x32_bf16 v[78:81], v[42:45], v[214:217], v[38:41]
	v_mfma_f32_16x16x32_bf16 v[38:41], v[46:49], v[138:141], v[86:89]
	v_mfma_f32_16x16x32_bf16 v[90:93], v[70:73], v[206:209], v[38:41]
	v_mfma_f32_16x16x32_bf16 v[38:41], v[46:49], v[210:213], v[82:85]
	v_mfma_f32_16x16x32_bf16 v[94:97], v[42:45], v[206:209], v[74:77]
	v_mfma_f32_16x16x32_bf16 v[74:77], v[70:73], v[214:217], v[38:41]
	v_mfma_f32_16x16x32_bf16 v[38:41], v[190:193], v[138:141], v[152:155]
	v_mfma_f32_16x16x32_bf16 v[86:89], v[194:197], v[206:209], v[38:41]
	v_mfma_f32_16x16x32_bf16 v[38:41], v[190:193], v[210:213], v[156:159]
	v_mfma_f32_16x16x32_bf16 v[70:73], v[194:197], v[214:217], v[38:41]
	v_mfma_f32_16x16x32_bf16 v[38:41], v[198:201], v[138:141], v[160:163]
	v_mfma_f32_16x16x32_bf16 v[82:85], v[202:205], v[206:209], v[38:41]
	v_mfma_f32_16x16x32_bf16 v[38:41], v[198:201], v[210:213], v[66:69]
	v_mfma_f32_16x16x32_bf16 v[66:69], v[202:205], v[214:217], v[38:41]
	s_barrier
	ds_read_b128 v[152:155], v142 offset:49152
	ds_read_b128 v[156:159], v142 offset:50176
	ds_read_b128 v[160:163], v142 offset:51200
	ds_read_b128 v[190:193], v142 offset:52224
	ds_read_b128 v[194:197], v142 offset:53248
	ds_read_b128 v[198:201], v142 offset:54272
	ds_read_b128 v[202:205], v142 offset:55296
	ds_read_b128 v[226:229], v142 offset:56320
	s_barrier
	s_waitcnt lgkmcnt(0)
	v_mfma_f32_16x16x32_bf16 v[38:41], v[152:155], v[6:9], v[62:65]
	v_mfma_f32_16x16x32_bf16 v[62:65], v[156:159], v[10:13], v[38:41]
	v_mfma_f32_16x16x32_bf16 v[38:41], v[152:155], v[14:17], v[58:61]
	v_mfma_f32_16x16x32_bf16 v[46:49], v[156:159], v[164:167], v[38:41]
	v_mfma_f32_16x16x32_bf16 v[38:41], v[160:163], v[6:9], v[54:57]
	v_mfma_f32_16x16x32_bf16 v[58:61], v[190:193], v[10:13], v[38:41]
	v_mfma_f32_16x16x32_bf16 v[38:41], v[160:163], v[14:17], v[50:53]
	v_mfma_f32_16x16x32_bf16 v[42:45], v[190:193], v[164:167], v[38:41]
	v_mfma_f32_16x16x32_bf16 v[38:41], v[194:197], v[6:9], v[218:221]
	v_mfma_f32_16x16x32_bf16 v[6:9], v[202:205], v[6:9], v[130:133]
	v_mfma_f32_16x16x32_bf16 v[54:57], v[198:201], v[10:13], v[38:41]
	v_mfma_f32_16x16x32_bf16 v[38:41], v[194:197], v[14:17], v[222:225]
	v_mfma_f32_16x16x32_bf16 v[50:53], v[226:229], v[10:13], v[6:9]
	v_mfma_f32_16x16x32_bf16 v[6:9], v[202:205], v[14:17], v[34:37]
	v_mfma_f32_16x16x32_bf16 v[38:41], v[198:201], v[164:167], v[38:41]
	v_mfma_f32_16x16x32_bf16 v[34:37], v[226:229], v[164:167], v[6:9]
	v_mfma_f32_16x16x32_bf16 v[6:9], v[152:155], v[138:141], v[30:33]
	v_mfma_f32_16x16x32_bf16 v[30:33], v[156:159], v[206:209], v[6:9]
	v_mfma_f32_16x16x32_bf16 v[6:9], v[152:155], v[210:213], v[26:29]
	v_mfma_f32_16x16x32_bf16 v[14:17], v[156:159], v[214:217], v[6:9]
	v_mfma_f32_16x16x32_bf16 v[6:9], v[160:163], v[138:141], v[22:25]
	v_mfma_f32_16x16x32_bf16 v[26:29], v[190:193], v[206:209], v[6:9]
	v_mfma_f32_16x16x32_bf16 v[6:9], v[160:163], v[210:213], v[18:21]
	v_mfma_f32_16x16x32_bf16 v[10:13], v[190:193], v[214:217], v[6:9]
	v_mfma_f32_16x16x32_bf16 v[6:9], v[194:197], v[138:141], v[134:137]
	v_mfma_f32_16x16x32_bf16 v[22:25], v[198:201], v[206:209], v[6:9]
	v_mfma_f32_16x16x32_bf16 v[6:9], v[194:197], v[210:213], v[144:147]
	v_mfma_f32_16x16x32_bf16 v[18:21], v[202:205], v[138:141], v[148:151]
	v_mfma_f32_16x16x32_bf16 v[2:5], v[202:205], v[210:213], v[2:5]
	v_mfma_f32_16x16x32_bf16 v[6:9], v[198:201], v[214:217], v[6:9]
	v_mfma_f32_16x16x32_bf16 v[18:21], v[226:229], v[206:209], v[18:21]
	v_mfma_f32_16x16x32_bf16 v[2:5], v[226:229], v[214:217], v[2:5]
	s_cmpk_lt_u32 s74, 0x100
	s_barrier
	s_cbranch_scc0 .LBB0_578
	s_barrier

;     __device__ __forceinline__ unsigned* BAR() const { return (unsigned*)(ws + OFF_BAR); }
; #define STAGE(bufoff, gbase, voff) do { _Pragma("unroll") for (int _i = 0; _i < 2; ++_i) \
;         __builtin_amdgcn_global_load_lds((const unsigned*)((const char*)(gbase) + voff[_i]), (LAS unsigned*)(lds + (bufoff) + ldsw + _i * 8192), 16, 0, 0); } while (0)
; #define LDA(dst, b, h) do { _Pragma("unroll") for (int m = 0; m < 4; ++m) _Pragma("unroll") for (int k = 0; k < 2; ++k) dst[m][k] = *(const LAS bf16x8*)(lds + SA(b, h) + aoff + m * 2048 + k * 1024); } while (0)
; #define LDB(dst, b, h) do { _Pragma("unroll") for (int n = 0; n < 2; ++n) _Pragma("unroll") for (int k = 0; k < 2; ++k) dst[n][k] = *(const LAS bf16x8*)(lds + SB(b, h) + boff + n * 2048 + k * 1024); } while (0)
; #define MMA(ai, bj, At, Bx) do { __builtin_amdgcn_s_setprio(1); _Pragma("unroll") for (int m = 0; m < 4; ++m) _Pragma("unroll") for (int n = 0; n < 2; ++n) _Pragma("unroll") for (int k = 0; k < 2; ++k) \
;       acc[ai][bj][m][n] = __builtin_amdgcn_mfma_f32_16x16x32_bf16(At[m][k], Bx[n][k], acc[ai][bj][m][n], 0, 0, 0); \
;     __builtin_amdgcn_s_setprio(0); } while (0)
; #define WAIT_L(n) asm volatile("s_waitcnt lgkmcnt(" #n ")" ::: "memory")
; #define BAR __builtin_amdgcn_s_barrier()
; #define SCHED __builtin_amdgcn_sched_barrier(0)
;     ...
;     for (int t = 0; t < nt - 2; t += 2) {
;         if (KSEG && t > 0 && (t % (KSEG ? KSEG : 1)) == 0) hook(t / (KSEG ? KSEG : 1), acc);
;         const char* a1 = pA(t + 1); const char* a2 = pA(t + 2); const char* a3 = pA(t + 3);
;         const char* b2 = pB(t + 2); const char* b3 = pB(t + 3);
;         LDB(B0, 0, 0); SCHED; LDA(At, 0, 0); STAGE(SA(1, 1), a1 + hstepA, voffA);
;         WAIT_L(8); BAR; WAIT_L(0); MMA(0, 0, At, B0); BAR; SCHED;
;         LDB(B1, 0, 1); STAGE(SB(0, 0), b2, voffB);
;         BAR; WAIT_L(0); MMA(0, 1, At, B1); BAR;
;         LDA(At, 0, 1); STAGE(SA(0, 0), a2, voffA);
.LBB0_617:
	s_add_i32 s16, 0, 0x10000
	v_add_u32_e32 v138, s16, v143
	ds_read_b128 v[144:147], v138
	ds_read_b128 v[148:151], v138 offset:1024
	ds_read_b128 v[152:155], v138 offset:2048
	ds_read_b128 v[156:159], v138 offset:3072
	v_lshl_add_u64 v[138:139], s[8:9], 0, v[136:137]
	s_add_i32 s88, s42, 0xc000
	v_lshl_add_u64 v[214:215], v[138:139], 0, s[84:85]
	s_mov_b32 m0, s88
	v_lshl_add_u64 v[230:231], s[8:9], 0, v[140:141]
	s_add_i32 s11, s42, 0xe000
	ds_read_b128 v[160:163], v142
	ds_read_b128 v[164:167], v142 offset:1024
	ds_read_b128 v[190:193], v142 offset:2048
	ds_read_b128 v[194:197], v142 offset:3072
	ds_read_b128 v[198:201], v142 offset:4096
	ds_read_b128 v[202:205], v142 offset:5120
	ds_read_b128 v[206:209], v142 offset:6144
	ds_read_b128 v[210:213], v142 offset:7168
	global_load_lds_dwordx4 v[214:215], off
	v_lshl_add_u64 v[214:215], v[230:231], 0, s[84:85]
	s_mov_b32 m0, s11
	s_nop 0
	global_load_lds_dwordx4 v[214:215], off
	s_waitcnt lgkmcnt(8)
	s_barrier
	s_waitcnt lgkmcnt(0)
	v_mfma_f32_16x16x32_bf16 v[126:129], v[160:163], v[144:147], v[126:129]
	v_mfma_f32_16x16x32_bf16 v[122:125], v[160:163], v[152:155], v[122:125]
	v_mfma_f32_16x16x32_bf16 v[118:121], v[190:193], v[144:147], v[118:121]
	v_mfma_f32_16x16x32_bf16 v[114:117], v[190:193], v[152:155], v[114:117]
	v_mfma_f32_16x16x32_bf16 v[110:113], v[198:201], v[144:147], v[110:113]
	v_mfma_f32_16x16x32_bf16 v[106:109], v[198:201], v[152:155], v[106:109]
	v_mfma_f32_16x16x32_bf16 v[102:105], v[206:209], v[144:147], v[102:105]
	v_mfma_f32_16x16x32_bf16 v[98:101], v[206:209], v[152:155], v[98:101]
	v_mfma_f32_16x16x32_bf16 v[126:129], v[164:167], v[148:151], v[126:129]
	v_mfma_f32_16x16x32_bf16 v[122:125], v[164:167], v[156:159], v[122:125]
	v_mfma_f32_16x16x32_bf16 v[118:121], v[194:197], v[148:151], v[118:121]
	v_mfma_f32_16x16x32_bf16 v[114:117], v[194:197], v[156:159], v[114:117]
	v_mfma_f32_16x16x32_bf16 v[110:113], v[202:205], v[148:151], v[110:113]
	v_mfma_f32_16x16x32_bf16 v[106:109], v[202:205], v[156:159], v[106:109]
	v_mfma_f32_16x16x32_bf16 v[102:105], v[210:213], v[148:151], v[102:105]
	v_mfma_f32_16x16x32_bf16 v[98:101], v[210:213], v[156:159], v[98:101]
	s_barrier
	s_add_i32 s17, 0, 0x14000
	v_lshl_add_u64 v[232:233], s[8:9], 0, v[132:133]
	s_add_i32 s16, s16, s15
	v_add_u32_e32 v226, s17, v143
	v_lshl_add_u64 v[234:235], v[232:233], 0, s[52:53]
	s_mov_b32 m0, s16
	ds_read_b128 v[214:217], v226
	ds_read_b128 v[218:221], v226 offset:1024
	ds_read_b128 v[222:225], v226 offset:2048
	ds_read_b128 v[226:229], v226 offset:3072
	global_load_lds_dwordx4 v[234:235], off
	v_lshl_add_u64 v[234:235], s[8:9], 0, v[134:135]
	v_lshl_add_u64 v[236:237], v[234:235], 0, s[52:53]
	s_add_i32 m0, s16, 0x2000
	s_nop 0
	global_load_lds_dwordx4 v[236:237], off
	s_barrier
	s_waitcnt lgkmcnt(0)
	v_mfma_f32_16x16x32_bf16 v[94:97], v[160:163], v[214:217], v[94:97]
	v_mfma_f32_16x16x32_bf16 v[90:93], v[160:163], v[222:225], v[90:93]
	v_mfma_f32_16x16x32_bf16 v[86:89], v[190:193], v[214:217], v[86:89]
	v_mfma_f32_16x16x32_bf16 v[82:85], v[190:193], v[222:225], v[82:85]
	v_mfma_f32_16x16x32_bf16 v[78:81], v[198:201], v[214:217], v[78:81]
	v_mfma_f32_16x16x32_bf16 v[74:77], v[198:201], v[222:225], v[74:77]
	v_mfma_f32_16x16x32_bf16 v[70:73], v[206:209], v[214:217], v[70:73]
	v_mfma_f32_16x16x32_bf16 v[66:69], v[206:209], v[222:225], v[66:69]
	v_mfma_f32_16x16x32_bf16 v[94:97], v[164:167], v[218:221], v[94:97]
	v_mfma_f32_16x16x32_bf16 v[90:93], v[164:167], v[226:229], v[90:93]
	v_mfma_f32_16x16x32_bf16 v[86:89], v[194:197], v[218:221], v[86:89]
	v_mfma_f32_16x16x32_bf16 v[82:85], v[194:197], v[226:229], v[82:85]
	v_mfma_f32_16x16x32_bf16 v[78:81], v[202:205], v[218:221], v[78:81]
	v_mfma_f32_16x16x32_bf16 v[74:77], v[202:205], v[226:229], v[74:77]
	v_mfma_f32_16x16x32_bf16 v[70:73], v[210:213], v[218:221], v[70:73]
	v_mfma_f32_16x16x32_bf16 v[66:69], v[210:213], v[226:229], v[66:69]
	s_mov_b32 m0, s42
	v_lshl_add_u64 v[236:237], v[138:139], 0, s[58:59]
	s_barrier
	ds_read_b128 v[160:163], v142 offset:16384
	ds_read_b128 v[164:167], v142 offset:17408
	ds_read_b128 v[190:193], v142 offset:18432
	ds_read_b128 v[194:197], v142 offset:19456
	ds_read_b128 v[198:201], v142 offset:20480
	ds_read_b128 v[202:205], v142 offset:21504
	ds_read_b128 v[206:209], v142 offset:22528
	ds_read_b128 v[210:213], v142 offset:23552
	global_load_lds_dwordx4 v[236:237], off
	v_lshl_add_u64 v[236:237], v[230:231], 0, s[58:59]
	s_mov_b32 m0, s43
	s_nop 0
	global_load_lds_dwordx4 v[236:237], off
	s_barrier
	s_waitcnt lgkmcnt(0)
	v_mfma_f32_16x16x32_bf16 v[62:65], v[160:163], v[144:147], v[62:65]
	v_mfma_f32_16x16x32_bf16 v[58:61], v[160:163], v[152:155], v[58:61]
	v_mfma_f32_16x16x32_bf16 v[54:57], v[190:193], v[144:147], v[54:57]
	v_mfma_f32_16x16x32_bf16 v[50:53], v[190:193], v[152:155], v[50:53]
	v_mfma_f32_16x16x32_bf16 v[46:49], v[198:201], v[144:147], v[46:49]
	v_mfma_f32_16x16x32_bf16 v[42:45], v[198:201], v[152:155], v[42:45]
	v_mfma_f32_16x16x32_bf16 v[38:41], v[206:209], v[144:147], v[38:41]
	v_mfma_f32_16x16x32_bf16 v[34:37], v[206:209], v[152:155], v[34:37]
	v_mfma_f32_16x16x32_bf16 v[62:65], v[164:167], v[148:151], v[62:65]
	v_mfma_f32_16x16x32_bf16 v[58:61], v[164:167], v[156:159], v[58:61]
	v_mfma_f32_16x16x32_bf16 v[54:57], v[194:197], v[148:151], v[54:57]
	v_mfma_f32_16x16x32_bf16 v[50:53], v[194:197], v[156:159], v[50:53]
	v_mfma_f32_16x16x32_bf16 v[46:49], v[202:205], v[148:151], v[46:49]
	v_mfma_f32_16x16x32_bf16 v[42:45], v[202:205], v[156:159], v[42:45]
	v_mfma_f32_16x16x32_bf16 v[38:41], v[210:213], v[148:151], v[38:41]
	v_mfma_f32_16x16x32_bf16 v[34:37], v[210:213], v[156:159], v[34:37]
	s_barrier
;     __device__ __forceinline__ unsigned* BAR() const { return (unsigned*)(ws + OFF_BAR); }
; #define STAGE(bufoff, gbase, voff) do { _Pragma("unroll") for (int _i = 0; _i < 2; ++_i) \
;         __builtin_amdgcn_global_load_lds((const unsigned*)((const char*)(gbase) + voff[_i]), (LAS unsigned*)(lds + (bufoff) + ldsw + _i * 8192), 16, 0, 0); } while (0)
; #define LDA(dst, b, h) do { _Pragma("unroll") for (int m = 0; m < 4; ++m) _Pragma("unroll") for (int k = 0; k < 2; ++k) dst[m][k] = *(const LAS bf16x8*)(lds + SA(b, h) + aoff + m * 2048 + k * 1024); } while (0)
; #define LDB(dst, b, h) do { _Pragma("unroll") for (int n = 0; n < 2; ++n) _Pragma("unroll") for (int k = 0; k < 2; ++k) dst[n][k] = *(const LAS bf16x8*)(lds + SB(b, h) + boff + n * 2048 + k * 1024); } while (0)
; #define MMA(ai, bj, At, Bx) do { __builtin_amdgcn_s_setprio(1); _Pragma("unroll") for (int m = 0; m < 4; ++m) _Pragma("unroll") for (int n = 0; n < 2; ++n) _Pragma("unroll") for (int k = 0; k < 2; ++k) \
;       acc[ai][bj][m][n] = __builtin_amdgcn_mfma_f32_16x16x32_bf16(At[m][k], Bx[n][k], acc[ai][bj][m][n], 0, 0, 0); \
;     __builtin_amdgcn_s_setprio(0); } while (0)
; #define WAIT_V(n) asm volatile("s_waitcnt vmcnt(" #n ")" ::: "memory")
; #define WAIT_L(n) asm volatile("s_waitcnt lgkmcnt(" #n ")" ::: "memory")
; #define BAR __builtin_amdgcn_s_barrier()
; #define SCHED __builtin_amdgcn_sched_barrier(0)
;     ...
;         BAR; WAIT_L(0); MMA(1, 0, At, B0); BAR; SCHED;
;         STAGE(SB(0, 1), b2 + hstepB, voffB);
;         WAIT_V(6); BAR; MMA(1, 1, At, B1); BAR;
;         LDB(B0, 1, 0); SCHED; LDA(At, 1, 0); STAGE(SA(0, 1), a2 + hstepA, voffA);
;         WAIT_L(8); BAR; WAIT_L(0); MMA(0, 0, At, B0); BAR; SCHED;
;         LDB(B1, 1, 1); STAGE(SB(1, 0), b3, voffB);
	s_add_i32 s16, s17, s15
	v_lshl_add_u64 v[144:145], v[232:233], 0, s[82:83]
	s_mov_b32 m0, s16
	s_nop 0
	global_load_lds_dwordx4 v[144:145], off
	v_lshl_add_u64 v[144:145], v[234:235], 0, s[82:83]
	s_add_i32 m0, s16, 0x2000
	s_nop 0
	global_load_lds_dwordx4 v[144:145], off
	s_waitcnt vmcnt(6)
	s_barrier
	v_mfma_f32_16x16x32_bf16 v[30:33], v[160:163], v[214:217], v[30:33]
	v_mfma_f32_16x16x32_bf16 v[26:29], v[160:163], v[222:225], v[26:29]
	v_mfma_f32_16x16x32_bf16 v[22:25], v[190:193], v[214:217], v[22:25]
	v_mfma_f32_16x16x32_bf16 v[18:21], v[190:193], v[222:225], v[18:21]
	v_mfma_f32_16x16x32_bf16 v[14:17], v[198:201], v[214:217], v[14:17]
	v_mfma_f32_16x16x32_bf16 v[10:13], v[198:201], v[222:225], v[10:13]
	v_mfma_f32_16x16x32_bf16 v[6:9], v[206:209], v[214:217], v[6:9]
	v_mfma_f32_16x16x32_bf16 v[2:5], v[206:209], v[222:225], v[2:5]
	v_mfma_f32_16x16x32_bf16 v[30:33], v[164:167], v[218:221], v[30:33]
	v_mfma_f32_16x16x32_bf16 v[26:29], v[164:167], v[226:229], v[26:29]
	v_mfma_f32_16x16x32_bf16 v[22:25], v[194:197], v[218:221], v[22:25]
	v_mfma_f32_16x16x32_bf16 v[18:21], v[194:197], v[226:229], v[18:21]
	v_mfma_f32_16x16x32_bf16 v[14:17], v[202:205], v[218:221], v[14:17]
	v_mfma_f32_16x16x32_bf16 v[10:13], v[202:205], v[226:229], v[10:13]
	v_mfma_f32_16x16x32_bf16 v[6:9], v[210:213], v[218:221], v[6:9]
	v_mfma_f32_16x16x32_bf16 v[2:5], v[210:213], v[226:229], v[2:5]
	s_add_i32 s16, 0, 0x18000
	v_add_u32_e32 v156, s16, v143
	s_barrier
	ds_read_b128 v[144:147], v156
	ds_read_b128 v[148:151], v156 offset:1024
	ds_read_b128 v[152:155], v156 offset:2048
	ds_read_b128 v[156:159], v156 offset:3072
	s_mov_b32 m0, s54
	v_lshl_add_u64 v[214:215], v[138:139], 0, s[96:97]
	ds_read_b128 v[160:163], v142 offset:32768
	ds_read_b128 v[164:167], v142 offset:33792
	ds_read_b128 v[190:193], v142 offset:34816
	ds_read_b128 v[194:197], v142 offset:35840
	ds_read_b128 v[198:201], v142 offset:36864
	ds_read_b128 v[202:205], v142 offset:37888
	ds_read_b128 v[206:209], v142 offset:38912
	ds_read_b128 v[210:213], v142 offset:39936
	global_load_lds_dwordx4 v[214:215], off
	v_lshl_add_u64 v[214:215], v[230:231], 0, s[96:97]
	s_mov_b32 m0, s55
	s_nop 0
	global_load_lds_dwordx4 v[214:215], off
	s_waitcnt lgkmcnt(8)
	s_barrier
	s_waitcnt lgkmcnt(0)
	v_mfma_f32_16x16x32_bf16 v[126:129], v[160:163], v[144:147], v[126:129]
	v_mfma_f32_16x16x32_bf16 v[122:125], v[160:163], v[152:155], v[122:125]
	v_mfma_f32_16x16x32_bf16 v[118:121], v[190:193], v[144:147], v[118:121]
	v_mfma_f32_16x16x32_bf16 v[114:117], v[190:193], v[152:155], v[114:117]
	v_mfma_f32_16x16x32_bf16 v[110:113], v[198:201], v[144:147], v[110:113]
	v_mfma_f32_16x16x32_bf16 v[106:109], v[198:201], v[152:155], v[106:109]
	v_mfma_f32_16x16x32_bf16 v[102:105], v[206:209], v[144:147], v[102:105]
	v_mfma_f32_16x16x32_bf16 v[98:101], v[206:209], v[152:155], v[98:101]
	v_mfma_f32_16x16x32_bf16 v[126:129], v[164:167], v[148:151], v[126:129]
	v_mfma_f32_16x16x32_bf16 v[122:125], v[164:167], v[156:159], v[122:125]
	v_mfma_f32_16x16x32_bf16 v[118:121], v[194:197], v[148:151], v[118:121]
	v_mfma_f32_16x16x32_bf16 v[114:117], v[194:197], v[156:159], v[114:117]
	v_mfma_f32_16x16x32_bf16 v[110:113], v[202:205], v[148:151], v[110:113]
	v_mfma_f32_16x16x32_bf16 v[106:109], v[202:205], v[156:159], v[106:109]
	v_mfma_f32_16x16x32_bf16 v[102:105], v[210:213], v[148:151], v[102:105]
	v_mfma_f32_16x16x32_bf16 v[98:101], v[210:213], v[156:159], v[98:101]
	s_barrier
	s_add_i32 s17, 0, 0x1c000
	s_add_i32 s16, s16, s15
	v_add_u32_e32 v226, s17, v143
	v_lshl_add_u64 v[236:237], v[232:233], 0, s[18:19]
	s_mov_b32 m0, s16
	ds_read_b128 v[214:217], v226
	ds_read_b128 v[218:221], v226 offset:1024
	ds_read_b128 v[222:225], v226 offset:2048
	ds_read_b128 v[226:229], v226 offset:3072
	global_load_lds_dwordx4 v[236:237], off
	v_lshl_add_u64 v[236:237], v[234:235], 0, s[18:19]
	s_add_i32 m0, s16, 0x2000
	s_nop 0
	global_load_lds_dwordx4 v[236:237], off
	s_barrier
	s_waitcnt lgkmcnt(0)
	v_mfma_f32_16x16x32_bf16 v[94:97], v[160:163], v[214:217], v[94:97]
	v_mfma_f32_16x16x32_bf16 v[90:93], v[160:163], v[222:225], v[90:93]
	v_mfma_f32_16x16x32_bf16 v[86:89], v[190:193], v[214:217], v[86:89]
	v_mfma_f32_16x16x32_bf16 v[82:85], v[190:193], v[222:225], v[82:85]
	v_mfma_f32_16x16x32_bf16 v[78:81], v[198:201], v[214:217], v[78:81]
	v_mfma_f32_16x16x32_bf16 v[74:77], v[198:201], v[222:225], v[74:77]
	v_mfma_f32_16x16x32_bf16 v[70:73], v[206:209], v[214:217], v[70:73]
	v_mfma_f32_16x16x32_bf16 v[66:69], v[206:209], v[222:225], v[66:69]
	v_mfma_f32_16x16x32_bf16 v[94:97], v[164:167], v[218:221], v[94:97]
	v_mfma_f32_16x16x32_bf16 v[90:93], v[164:167], v[226:229], v[90:93]
	v_mfma_f32_16x16x32_bf16 v[86:89], v[194:197], v[218:221], v[86:89]
	v_mfma_f32_16x16x32_bf16 v[82:85], v[194:197], v[226:229], v[82:85]
	v_mfma_f32_16x16x32_bf16 v[78:81], v[202:205], v[218:221], v[78:81]
	v_mfma_f32_16x16x32_bf16 v[74:77], v[202:205], v[226:229], v[74:77]
	v_mfma_f32_16x16x32_bf16 v[70:73], v[210:213], v[218:221], v[70:73]
	v_mfma_f32_16x16x32_bf16 v[66:69], v[210:213], v[226:229], v[66:69]
	s_mov_b32 m0, s56
	v_lshl_add_u64 v[138:139], v[138:139], 0, s[34:35]
	s_barrier
	ds_read_b128 v[160:163], v142 offset:49152
	ds_read_b128 v[164:167], v142 offset:50176
	ds_read_b128 v[190:193], v142 offset:51200
	ds_read_b128 v[194:197], v142 offset:52224
	ds_read_b128 v[198:201], v142 offset:53248
	ds_read_b128 v[202:205], v142 offset:54272
	ds_read_b128 v[206:209], v142 offset:55296
	ds_read_b128 v[210:213], v142 offset:56320
	global_load_lds_dwordx4 v[138:139], off
	v_lshl_add_u64 v[138:139], v[230:231], 0, s[34:35]
	s_mov_b32 m0, s57
	s_nop 0
	global_load_lds_dwordx4 v[138:139], off
	s_barrier
;     __device__ __forceinline__ unsigned* BAR() const { return (unsigned*)(ws + OFF_BAR); }
; #define STAGE(bufoff, gbase, voff) do { _Pragma("unroll") for (int _i = 0; _i < 2; ++_i) \
;         __builtin_amdgcn_global_load_lds((const unsigned*)((const char*)(gbase) + voff[_i]), (LAS unsigned*)(lds + (bufoff) + ldsw + _i * 8192), 16, 0, 0); } while (0)
; #define LDA(dst, b, h) do { _Pragma("unroll") for (int m = 0; m < 4; ++m) _Pragma("unroll") for (int k = 0; k < 2; ++k) dst[m][k] = *(const LAS bf16x8*)(lds + SA(b, h) + aoff + m * 2048 + k * 1024); } while (0)
; #define LDB(dst, b, h) do { _Pragma("unroll") for (int n = 0; n < 2; ++n) _Pragma("unroll") for (int k = 0; k < 2; ++k) dst[n][k] = *(const LAS bf16x8*)(lds + SB(b, h) + boff + n * 2048 + k * 1024); } while (0)
; #define MMA(ai, bj, At, Bx) do { __builtin_amdgcn_s_setprio(1); _Pragma("unroll") for (int m = 0; m < 4; ++m) _Pragma("unroll") for (int n = 0; n < 2; ++n) _Pragma("unroll") for (int k = 0; k < 2; ++k) \
;       acc[ai][bj][m][n] = __builtin_amdgcn_mfma_f32_16x16x32_bf16(At[m][k], Bx[n][k], acc[ai][bj][m][n], 0, 0, 0); \
;     __builtin_amdgcn_s_setprio(0); } while (0)
; #define WAIT_V(n) asm volatile("s_waitcnt vmcnt(" #n ")" ::: "memory")
; #define WAIT_L(n) asm volatile("s_waitcnt lgkmcnt(" #n ")" ::: "memory")
; #define BAR __builtin_amdgcn_s_barrier()
; #define SCHED __builtin_amdgcn_sched_barrier(0)
;     ...
;         LDB(B1, 1, 1); STAGE(SB(1, 0), b3, voffB);
;         BAR; WAIT_L(0); MMA(0, 1, At, B1); BAR;
;         LDA(At, 1, 1); STAGE(SA(1, 0), a3, voffA);
;         BAR; WAIT_L(0); MMA(1, 0, At, B0); BAR; SCHED;
;         STAGE(SB(1, 1), b3 + hstepB, voffB);
;         WAIT_V(6); BAR; MMA(1, 1, At, B1); BAR;
;     }
;     { LDB(B0, 0, 0); LDA(At, 0, 0); STAGE(SA(1, 1), pA(nt - 1) + hstepA, voffA);
;       BAR; WAIT_L(0); MMA(0, 0, At, B0); BAR;
;       LDB(B1, 0, 1); BAR; WAIT_L(0); MMA(0, 1, At, B1); BAR;
;       LDA(At, 0, 1); WAIT_V(4); BAR; WAIT_L(0); MMA(1, 0, At, B0); MMA(1, 1, At, B1); BAR; }
	s_waitcnt lgkmcnt(0)
	v_mfma_f32_16x16x32_bf16 v[62:65], v[160:163], v[144:147], v[62:65]
	v_mfma_f32_16x16x32_bf16 v[58:61], v[160:163], v[152:155], v[58:61]
	v_mfma_f32_16x16x32_bf16 v[54:57], v[190:193], v[144:147], v[54:57]
	v_mfma_f32_16x16x32_bf16 v[50:53], v[190:193], v[152:155], v[50:53]
	v_mfma_f32_16x16x32_bf16 v[46:49], v[198:201], v[144:147], v[46:49]
	v_mfma_f32_16x16x32_bf16 v[42:45], v[198:201], v[152:155], v[42:45]
	v_mfma_f32_16x16x32_bf16 v[38:41], v[206:209], v[144:147], v[38:41]
	v_mfma_f32_16x16x32_bf16 v[34:37], v[206:209], v[152:155], v[34:37]
	v_mfma_f32_16x16x32_bf16 v[62:65], v[164:167], v[148:151], v[62:65]
	v_mfma_f32_16x16x32_bf16 v[58:61], v[164:167], v[156:159], v[58:61]
	v_mfma_f32_16x16x32_bf16 v[54:57], v[194:197], v[148:151], v[54:57]
	v_mfma_f32_16x16x32_bf16 v[50:53], v[194:197], v[156:159], v[50:53]
	v_mfma_f32_16x16x32_bf16 v[46:49], v[202:205], v[148:151], v[46:49]
	v_mfma_f32_16x16x32_bf16 v[42:45], v[202:205], v[156:159], v[42:45]
	v_mfma_f32_16x16x32_bf16 v[38:41], v[210:213], v[148:151], v[38:41]
	v_mfma_f32_16x16x32_bf16 v[34:37], v[210:213], v[156:159], v[34:37]
	s_barrier
	s_add_i32 s16, s17, s15
	v_lshl_add_u64 v[138:139], v[232:233], 0, s[86:87]
	s_mov_b32 m0, s16
	s_nop 0
	global_load_lds_dwordx4 v[138:139], off
	v_lshl_add_u64 v[138:139], v[234:235], 0, s[86:87]
	s_add_i32 m0, s16, 0x2000
	s_nop 0
	global_load_lds_dwordx4 v[138:139], off
	s_waitcnt vmcnt(6)
	s_barrier
	v_mfma_f32_16x16x32_bf16 v[30:33], v[160:163], v[214:217], v[30:33]
	v_mfma_f32_16x16x32_bf16 v[26:29], v[160:163], v[222:225], v[26:29]
	v_mfma_f32_16x16x32_bf16 v[22:25], v[190:193], v[214:217], v[22:25]
	v_mfma_f32_16x16x32_bf16 v[18:21], v[190:193], v[222:225], v[18:21]
	v_mfma_f32_16x16x32_bf16 v[14:17], v[198:201], v[214:217], v[14:17]
	v_mfma_f32_16x16x32_bf16 v[10:13], v[198:201], v[222:225], v[10:13]
	v_mfma_f32_16x16x32_bf16 v[6:9], v[206:209], v[214:217], v[6:9]
	v_mfma_f32_16x16x32_bf16 v[2:5], v[206:209], v[222:225], v[2:5]
	v_mfma_f32_16x16x32_bf16 v[30:33], v[164:167], v[218:221], v[30:33]
	v_mfma_f32_16x16x32_bf16 v[26:29], v[164:167], v[226:229], v[26:29]
	v_mfma_f32_16x16x32_bf16 v[22:25], v[194:197], v[218:221], v[22:25]
	v_mfma_f32_16x16x32_bf16 v[18:21], v[194:197], v[226:229], v[18:21]
	v_mfma_f32_16x16x32_bf16 v[14:17], v[202:205], v[218:221], v[14:17]
	v_mfma_f32_16x16x32_bf16 v[10:13], v[202:205], v[226:229], v[10:13]
	v_mfma_f32_16x16x32_bf16 v[6:9], v[210:213], v[218:221], v[6:9]
	v_mfma_f32_16x16x32_bf16 v[2:5], v[210:213], v[226:229], v[2:5]
	s_add_i32 s10, s10, 2
	s_add_u32 s8, s8, 0x100
	s_addc_u32 s9, s9, 0
	s_cmp_gt_u32 s10, 11
	s_barrier
	s_cbranch_scc0 .LBB0_617
	v_add_u32_e32 v143, 0, v143
	s_add_u32 s6, s6, 0x40780
	v_add_u32_e32 v140, 0x10000, v143
	s_addc_u32 s7, s7, 0
	s_mov_b32 m0, s88
	ds_read_b128 v[132:135], v140
	ds_read_b128 v[136:139], v140 offset:1024
	ds_read_b128 v[144:147], v140 offset:2048
	ds_read_b128 v[148:151], v140 offset:3072
	ds_read_b128 v[152:155], v142
	ds_read_b128 v[156:159], v142 offset:1024
	ds_read_b128 v[160:163], v142 offset:2048
	ds_read_b128 v[164:167], v142 offset:3072
	ds_read_b128 v[190:193], v142 offset:4096
	ds_read_b128 v[194:197], v142 offset:5120
	ds_read_b128 v[198:201], v142 offset:6144
	ds_read_b128 v[202:205], v142 offset:7168
	v_lshl_add_u64 v[140:141], s[6:7], 0, v[0:1]
	global_load_lds_dwordx4 v[140:141], off
	v_lshl_add_u64 v[130:131], s[6:7], 0, v[130:131]
	s_mov_b32 m0, s11
	s_nop 0
	global_load_lds_dwordx4 v[130:131], off
	s_barrier
	s_waitcnt lgkmcnt(0)
	v_mfma_f32_16x16x32_bf16 v[126:129], v[152:155], v[132:135], v[126:129]
	v_mfma_f32_16x16x32_bf16 v[122:125], v[152:155], v[144:147], v[122:125]
	v_mfma_f32_16x16x32_bf16 v[118:121], v[160:163], v[132:135], v[118:121]
	v_mfma_f32_16x16x32_bf16 v[114:117], v[160:163], v[144:147], v[114:117]
	v_mfma_f32_16x16x32_bf16 v[110:113], v[190:193], v[132:135], v[110:113]
	v_mfma_f32_16x16x32_bf16 v[106:109], v[190:193], v[144:147], v[106:109]
	v_mfma_f32_16x16x32_bf16 v[102:105], v[198:201], v[132:135], v[102:105]
	v_mfma_f32_16x16x32_bf16 v[98:101], v[198:201], v[144:147], v[98:101]
	v_mfma_f32_16x16x32_bf16 v[126:129], v[156:159], v[136:139], v[126:129]
	v_mfma_f32_16x16x32_bf16 v[122:125], v[156:159], v[148:151], v[122:125]
	v_mfma_f32_16x16x32_bf16 v[118:121], v[164:167], v[136:139], v[118:121]
	v_mfma_f32_16x16x32_bf16 v[114:117], v[164:167], v[148:151], v[114:117]
	v_mfma_f32_16x16x32_bf16 v[110:113], v[194:197], v[136:139], v[110:113]
	v_mfma_f32_16x16x32_bf16 v[106:109], v[194:197], v[148:151], v[106:109]
	v_mfma_f32_16x16x32_bf16 v[102:105], v[202:205], v[136:139], v[102:105]
	v_mfma_f32_16x16x32_bf16 v[98:101], v[202:205], v[148:151], v[98:101]
	v_add_u32_e32 v0, 0x14000, v143
	s_barrier
	ds_read_b128 v[206:209], v0
	ds_read_b128 v[210:213], v0 offset:1024
	ds_read_b128 v[214:217], v0 offset:2048
	ds_read_b128 v[218:221], v0 offset:3072
	s_barrier
	s_waitcnt lgkmcnt(0)
	v_mfma_f32_16x16x32_bf16 v[66:69], v[198:201], v[214:217], v[66:69]
	v_mfma_f32_16x16x32_bf16 v[94:97], v[152:155], v[206:209], v[94:97]
	v_mfma_f32_16x16x32_bf16 v[90:93], v[152:155], v[214:217], v[90:93]
	v_mfma_f32_16x16x32_bf16 v[86:89], v[160:163], v[206:209], v[86:89]
	v_mfma_f32_16x16x32_bf16 v[82:85], v[160:163], v[214:217], v[82:85]
	v_mfma_f32_16x16x32_bf16 v[78:81], v[190:193], v[206:209], v[78:81]
	v_mfma_f32_16x16x32_bf16 v[74:77], v[190:193], v[214:217], v[74:77]
	v_mfma_f32_16x16x32_bf16 v[70:73], v[198:201], v[206:209], v[70:73]
	v_mfma_f32_16x16x32_bf16 v[66:69], v[202:205], v[218:221], v[66:69]
	v_mfma_f32_16x16x32_bf16 v[222:225], v[156:159], v[210:213], v[94:97]
	v_mfma_f32_16x16x32_bf16 v[152:155], v[156:159], v[218:221], v[90:93]
	v_mfma_f32_16x16x32_bf16 v[156:159], v[164:167], v[210:213], v[86:89]
	v_mfma_f32_16x16x32_bf16 v[160:163], v[164:167], v[218:221], v[82:85]
	v_mfma_f32_16x16x32_bf16 v[164:167], v[194:197], v[210:213], v[78:81]
	v_mfma_f32_16x16x32_bf16 v[190:193], v[194:197], v[218:221], v[74:77]
	v_mfma_f32_16x16x32_bf16 v[194:197], v[202:205], v[210:213], v[70:73]
	s_barrier
;     __device__ __forceinline__ unsigned* BAR() const { return (unsigned*)(ws + OFF_BAR); }
; #define LDA(dst, b, h) do { _Pragma("unroll") for (int m = 0; m < 4; ++m) _Pragma("unroll") for (int k = 0; k < 2; ++k) dst[m][k] = *(const LAS bf16x8*)(lds + SA(b, h) + aoff + m * 2048 + k * 1024); } while (0)
; #define LDB(dst, b, h) do { _Pragma("unroll") for (int n = 0; n < 2; ++n) _Pragma("unroll") for (int k = 0; k < 2; ++k) dst[n][k] = *(const LAS bf16x8*)(lds + SB(b, h) + boff + n * 2048 + k * 1024); } while (0)
; #define MMA(ai, bj, At, Bx) do { __builtin_amdgcn_s_setprio(1); _Pragma("unroll") for (int m = 0; m < 4; ++m) _Pragma("unroll") for (int n = 0; n < 2; ++n) _Pragma("unroll") for (int k = 0; k < 2; ++k) \
;       acc[ai][bj][m][n] = __builtin_amdgcn_mfma_f32_16x16x32_bf16(At[m][k], Bx[n][k], acc[ai][bj][m][n], 0, 0, 0); \
;     __builtin_amdgcn_s_setprio(0); } while (0)
; #define WAIT_V(n) asm volatile("s_waitcnt vmcnt(" #n ")" ::: "memory")
; #define WAIT_L(n) asm volatile("s_waitcnt lgkmcnt(" #n ")" ::: "memory")
; #define BAR __builtin_amdgcn_s_barrier()
;     ...
;       LDA(At, 0, 1); WAIT_V(4); BAR; WAIT_L(0); MMA(1, 0, At, B0); MMA(1, 1, At, B1); BAR; }
;     { LDB(B0, 1, 0); LDA(At, 1, 0); WAIT_V(2); BAR; WAIT_L(0); MMA(0, 0, At, B0); BAR;
;       LDB(B1, 1, 1); WAIT_V(0); BAR; WAIT_L(0); MMA(0, 1, At, B1); BAR;
;       LDA(At, 1, 1); BAR; WAIT_L(0); MMA(1, 0, At, B0); MMA(1, 1, At, B1); BAR; }
	s_nop 0
	ds_read_b128 v[70:73], v142 offset:16384
	ds_read_b128 v[74:77], v142 offset:17408
	ds_read_b128 v[78:81], v142 offset:18432
	ds_read_b128 v[82:85], v142 offset:19456
	ds_read_b128 v[86:89], v142 offset:20480
	ds_read_b128 v[90:93], v142 offset:21504
	ds_read_b128 v[94:97], v142 offset:22528
	ds_read_b128 v[198:201], v142 offset:23552
	s_waitcnt vmcnt(4)
	s_barrier
	s_waitcnt lgkmcnt(0)
	v_mfma_f32_16x16x32_bf16 v[62:65], v[70:73], v[132:135], v[62:65]
	v_mfma_f32_16x16x32_bf16 v[58:61], v[70:73], v[144:147], v[58:61]
	v_mfma_f32_16x16x32_bf16 v[54:57], v[78:81], v[132:135], v[54:57]
	v_mfma_f32_16x16x32_bf16 v[50:53], v[78:81], v[144:147], v[50:53]
	v_mfma_f32_16x16x32_bf16 v[34:37], v[94:97], v[144:147], v[34:37]
	v_mfma_f32_16x16x32_bf16 v[62:65], v[74:77], v[136:139], v[62:65]
	v_mfma_f32_16x16x32_bf16 v[58:61], v[74:77], v[148:151], v[58:61]
	v_mfma_f32_16x16x32_bf16 v[54:57], v[82:85], v[136:139], v[54:57]
	v_mfma_f32_16x16x32_bf16 v[50:53], v[82:85], v[148:151], v[50:53]
	v_mfma_f32_16x16x32_bf16 v[46:49], v[86:89], v[132:135], v[46:49]
	v_mfma_f32_16x16x32_bf16 v[42:45], v[86:89], v[144:147], v[42:45]
	v_mfma_f32_16x16x32_bf16 v[38:41], v[94:97], v[132:135], v[38:41]
	v_mfma_f32_16x16x32_bf16 v[34:37], v[198:201], v[148:151], v[34:37]
	v_mfma_f32_16x16x32_bf16 v[202:205], v[90:93], v[136:139], v[46:49]
	v_mfma_f32_16x16x32_bf16 v[226:229], v[90:93], v[148:151], v[42:45]
	v_mfma_f32_16x16x32_bf16 v[130:133], v[198:201], v[136:139], v[38:41]
	v_mfma_f32_16x16x32_bf16 v[30:33], v[70:73], v[206:209], v[30:33]
	v_mfma_f32_16x16x32_bf16 v[26:29], v[70:73], v[214:217], v[26:29]
	v_mfma_f32_16x16x32_bf16 v[22:25], v[78:81], v[206:209], v[22:25]
	v_mfma_f32_16x16x32_bf16 v[18:21], v[78:81], v[214:217], v[18:21]
	v_mfma_f32_16x16x32_bf16 v[2:5], v[94:97], v[214:217], v[2:5]
	v_mfma_f32_16x16x32_bf16 v[30:33], v[74:77], v[210:213], v[30:33]
	v_mfma_f32_16x16x32_bf16 v[26:29], v[74:77], v[218:221], v[26:29]
	v_mfma_f32_16x16x32_bf16 v[22:25], v[82:85], v[210:213], v[22:25]
	v_mfma_f32_16x16x32_bf16 v[18:21], v[82:85], v[218:221], v[18:21]
	v_mfma_f32_16x16x32_bf16 v[14:17], v[86:89], v[206:209], v[14:17]
	v_mfma_f32_16x16x32_bf16 v[10:13], v[86:89], v[214:217], v[10:13]
	v_mfma_f32_16x16x32_bf16 v[6:9], v[94:97], v[206:209], v[6:9]
	v_mfma_f32_16x16x32_bf16 v[2:5], v[198:201], v[218:221], v[2:5]
	v_mfma_f32_16x16x32_bf16 v[134:137], v[90:93], v[210:213], v[14:17]
	v_mfma_f32_16x16x32_bf16 v[138:141], v[90:93], v[218:221], v[10:13]
	v_mfma_f32_16x16x32_bf16 v[144:147], v[198:201], v[210:213], v[6:9]
	v_add_u32_e32 v0, 0x18000, v143
	s_barrier
	s_nop 0
	ds_read_b128 v[6:9], v0
	ds_read_b128 v[10:13], v0 offset:1024
	ds_read_b128 v[14:17], v0 offset:2048
	ds_read_b128 v[148:151], v0 offset:3072
	ds_read_b128 v[38:41], v142 offset:32768
	ds_read_b128 v[42:45], v142 offset:33792
	ds_read_b128 v[46:49], v142 offset:34816
	ds_read_b128 v[70:73], v142 offset:35840
	ds_read_b128 v[198:201], v142 offset:36864
	ds_read_b128 v[206:209], v142 offset:37888
	ds_read_b128 v[210:213], v142 offset:38912
	ds_read_b128 v[214:217], v142 offset:39936
	s_waitcnt vmcnt(2)
	s_barrier
	s_waitcnt lgkmcnt(0)
	v_mfma_f32_16x16x32_bf16 v[74:77], v[38:41], v[6:9], v[126:129]
	v_mfma_f32_16x16x32_bf16 v[126:129], v[42:45], v[10:13], v[74:77]
	v_mfma_f32_16x16x32_bf16 v[74:77], v[38:41], v[14:17], v[122:125]
	v_mfma_f32_16x16x32_bf16 v[94:97], v[42:45], v[148:151], v[74:77]
	v_mfma_f32_16x16x32_bf16 v[74:77], v[46:49], v[6:9], v[118:121]
	v_mfma_f32_16x16x32_bf16 v[122:125], v[70:73], v[10:13], v[74:77]
	v_mfma_f32_16x16x32_bf16 v[74:77], v[46:49], v[14:17], v[114:117]
	v_mfma_f32_16x16x32_bf16 v[90:93], v[70:73], v[148:151], v[74:77]
	v_mfma_f32_16x16x32_bf16 v[74:77], v[198:201], v[6:9], v[110:113]
	v_mfma_f32_16x16x32_bf16 v[118:121], v[206:209], v[10:13], v[74:77]
	v_mfma_f32_16x16x32_bf16 v[74:77], v[198:201], v[14:17], v[106:109]
	v_mfma_f32_16x16x32_bf16 v[86:89], v[206:209], v[148:151], v[74:77]
	v_mfma_f32_16x16x32_bf16 v[74:77], v[210:213], v[6:9], v[102:105]
	v_mfma_f32_16x16x32_bf16 v[114:117], v[214:217], v[10:13], v[74:77]
	v_mfma_f32_16x16x32_bf16 v[74:77], v[210:213], v[14:17], v[98:101]
	v_mfma_f32_16x16x32_bf16 v[82:85], v[214:217], v[148:151], v[74:77]
	v_add_u32_e32 v0, 0x1c000, v143
	s_barrier
;     __device__ __forceinline__ unsigned* BAR() const { return (unsigned*)(ws + OFF_BAR); }
; #define LDA(dst, b, h) do { _Pragma("unroll") for (int m = 0; m < 4; ++m) _Pragma("unroll") for (int k = 0; k < 2; ++k) dst[m][k] = *(const LAS bf16x8*)(lds + SA(b, h) + aoff + m * 2048 + k * 1024); } while (0)
; #define LDB(dst, b, h) do { _Pragma("unroll") for (int n = 0; n < 2; ++n) _Pragma("unroll") for (int k = 0; k < 2; ++k) dst[n][k] = *(const LAS bf16x8*)(lds + SB(b, h) + boff + n * 2048 + k * 1024); } while (0)
; #define MMA(ai, bj, At, Bx) do { __builtin_amdgcn_s_setprio(1); _Pragma("unroll") for (int m = 0; m < 4; ++m) _Pragma("unroll") for (int n = 0; n < 2; ++n) _Pragma("unroll") for (int k = 0; k < 2; ++k) \
;       acc[ai][bj][m][n] = __builtin_amdgcn_mfma_f32_16x16x32_bf16(At[m][k], Bx[n][k], acc[ai][bj][m][n], 0, 0, 0); \
;     __builtin_amdgcn_s_setprio(0); } while (0)
; #define WAIT_V(n) asm volatile("s_waitcnt vmcnt(" #n ")" ::: "memory")
; #define WAIT_L(n) asm volatile("s_waitcnt lgkmcnt(" #n ")" ::: "memory")
; #define BAR __builtin_amdgcn_s_barrier()
;     ...
;     { LDB(B0, 1, 0); LDA(At, 1, 0); WAIT_V(2); BAR; WAIT_L(0); MMA(0, 0, At, B0); BAR;
;       LDB(B1, 1, 1); WAIT_V(0); BAR; WAIT_L(0); MMA(0, 1, At, B1); BAR;
;       LDA(At, 1, 1); BAR; WAIT_L(0); MMA(1, 0, At, B0); MMA(1, 1, At, B1); BAR; }
;     if (wr == 0) BAR;
	ds_read_b128 v[218:221], v0
	ds_read_b128 v[230:233], v0 offset:1024
	ds_read_b128 v[234:237], v0 offset:2048
	ds_read_b128 v[238:241], v0 offset:3072
	s_waitcnt vmcnt(0)
	s_barrier
	s_waitcnt lgkmcnt(0)
	v_mfma_f32_16x16x32_bf16 v[74:77], v[38:41], v[218:221], v[222:225]
	v_mfma_f32_16x16x32_bf16 v[38:41], v[38:41], v[234:237], v[152:155]
	v_mfma_f32_16x16x32_bf16 v[78:81], v[42:45], v[238:241], v[38:41]
	v_mfma_f32_16x16x32_bf16 v[38:41], v[46:49], v[218:221], v[156:159]
	v_mfma_f32_16x16x32_bf16 v[106:109], v[70:73], v[230:233], v[38:41]
	v_mfma_f32_16x16x32_bf16 v[38:41], v[46:49], v[234:237], v[160:163]
	v_mfma_f32_16x16x32_bf16 v[110:113], v[42:45], v[230:233], v[74:77]
	v_mfma_f32_16x16x32_bf16 v[74:77], v[70:73], v[238:241], v[38:41]
	v_mfma_f32_16x16x32_bf16 v[38:41], v[198:201], v[218:221], v[164:167]
	v_mfma_f32_16x16x32_bf16 v[102:105], v[206:209], v[230:233], v[38:41]
	v_mfma_f32_16x16x32_bf16 v[38:41], v[198:201], v[234:237], v[190:193]
	v_mfma_f32_16x16x32_bf16 v[70:73], v[206:209], v[238:241], v[38:41]
	v_mfma_f32_16x16x32_bf16 v[38:41], v[210:213], v[218:221], v[194:197]
	v_mfma_f32_16x16x32_bf16 v[98:101], v[214:217], v[230:233], v[38:41]
	v_mfma_f32_16x16x32_bf16 v[38:41], v[210:213], v[234:237], v[66:69]
	v_mfma_f32_16x16x32_bf16 v[66:69], v[214:217], v[238:241], v[38:41]
	s_barrier
	ds_read_b128 v[152:155], v142 offset:49152
	ds_read_b128 v[156:159], v142 offset:50176
	ds_read_b128 v[160:163], v142 offset:51200
	ds_read_b128 v[164:167], v142 offset:52224
	ds_read_b128 v[190:193], v142 offset:53248
	ds_read_b128 v[194:197], v142 offset:54272
	ds_read_b128 v[198:201], v142 offset:55296
	ds_read_b128 v[206:209], v142 offset:56320
	s_barrier
	s_waitcnt lgkmcnt(0)
	v_mfma_f32_16x16x32_bf16 v[38:41], v[152:155], v[6:9], v[62:65]
	v_mfma_f32_16x16x32_bf16 v[62:65], v[156:159], v[10:13], v[38:41]
	v_mfma_f32_16x16x32_bf16 v[38:41], v[152:155], v[14:17], v[58:61]
	v_mfma_f32_16x16x32_bf16 v[46:49], v[156:159], v[148:151], v[38:41]
	v_mfma_f32_16x16x32_bf16 v[38:41], v[160:163], v[6:9], v[54:57]
	v_mfma_f32_16x16x32_bf16 v[58:61], v[164:167], v[10:13], v[38:41]
	v_mfma_f32_16x16x32_bf16 v[38:41], v[160:163], v[14:17], v[50:53]
	v_mfma_f32_16x16x32_bf16 v[42:45], v[164:167], v[148:151], v[38:41]
	v_mfma_f32_16x16x32_bf16 v[38:41], v[190:193], v[6:9], v[202:205]
	v_mfma_f32_16x16x32_bf16 v[6:9], v[198:201], v[6:9], v[130:133]
	v_mfma_f32_16x16x32_bf16 v[54:57], v[194:197], v[10:13], v[38:41]
	v_mfma_f32_16x16x32_bf16 v[38:41], v[190:193], v[14:17], v[226:229]
	v_mfma_f32_16x16x32_bf16 v[50:53], v[206:209], v[10:13], v[6:9]
	v_mfma_f32_16x16x32_bf16 v[6:9], v[198:201], v[14:17], v[34:37]
	v_mfma_f32_16x16x32_bf16 v[38:41], v[194:197], v[148:151], v[38:41]
	v_mfma_f32_16x16x32_bf16 v[34:37], v[206:209], v[148:151], v[6:9]
	v_mfma_f32_16x16x32_bf16 v[6:9], v[152:155], v[218:221], v[30:33]
	v_mfma_f32_16x16x32_bf16 v[30:33], v[156:159], v[230:233], v[6:9]
	v_mfma_f32_16x16x32_bf16 v[6:9], v[152:155], v[234:237], v[26:29]
	v_mfma_f32_16x16x32_bf16 v[14:17], v[156:159], v[238:241], v[6:9]
	v_mfma_f32_16x16x32_bf16 v[6:9], v[160:163], v[218:221], v[22:25]
	v_mfma_f32_16x16x32_bf16 v[26:29], v[164:167], v[230:233], v[6:9]
	v_mfma_f32_16x16x32_bf16 v[6:9], v[160:163], v[234:237], v[18:21]
	v_mfma_f32_16x16x32_bf16 v[10:13], v[164:167], v[238:241], v[6:9]
	v_mfma_f32_16x16x32_bf16 v[6:9], v[190:193], v[218:221], v[134:137]
	v_mfma_f32_16x16x32_bf16 v[22:25], v[194:197], v[230:233], v[6:9]
	v_mfma_f32_16x16x32_bf16 v[6:9], v[190:193], v[234:237], v[138:141]
	v_mfma_f32_16x16x32_bf16 v[18:21], v[198:201], v[218:221], v[144:147]
	v_mfma_f32_16x16x32_bf16 v[2:5], v[198:201], v[234:237], v[2:5]
	v_mfma_f32_16x16x32_bf16 v[6:9], v[194:197], v[238:241], v[6:9]
	v_mfma_f32_16x16x32_bf16 v[18:21], v[206:209], v[230:233], v[18:21]
	v_mfma_f32_16x16x32_bf16 v[2:5], v[206:209], v[238:241], v[2:5]
	s_cmpk_lt_u32 s14, 0x100
	s_barrier
	s_cbranch_scc0 .LBB0_620
	s_barrier
